# static priority raise: per-segment setprio flips removed from the seven GEMM K-loops, waves 4-7 run the K-loop at user priority 1
# speedup vs baseline: 1.0101x; 1.0101x over previous
; #define PG8_STAGE(bufoff, gbase, voff) do { _Pragma("unroll") for (int _i = 0; _i < 2; ++_i) \
;         __builtin_amdgcn_global_load_lds((const unsigned*)((const char*)(gbase) + (voff)[_i]), (LAS unsigned*)(lds + (bufoff) + ldsw + _i * 8192), 16, 0, 0); } while (0)
; #define PG8_LDA(dst, b, h) do { _Pragma("unroll") for (int m = 0; m < 4; ++m) _Pragma("unroll") for (int k = 0; k < 2; ++k) dst[m][k] = *(const LAS bf16x8*)(lds + PG8_SA(b, h) + aoff + m * 2048 + k * 1024); } while (0)
; #define PG8_LDB(dst, b, h) do { _Pragma("unroll") for (int n = 0; n < 2; ++n) _Pragma("unroll") for (int k = 0; k < 2; ++k) dst[n][k] = *(const LAS bf16x8*)(lds + PG8_SB(b, h) + boff + n * 2048 + k * 1024); } while (0)
; #define PG8_WAIT_V(n) asm volatile("s_waitcnt vmcnt(" #n ")" ::: "memory")
; #define PG8_WAIT_L(n) asm volatile("s_waitcnt lgkmcnt(" #n ")" ::: "memory")
; #define PG8_BAR __builtin_amdgcn_s_barrier()
; #define PG8_SCHED __builtin_amdgcn_sched_barrier(0)
; template <class Sched, class Epi, bool ALIGN_EPI, bool SP2>
; __device__ __forceinline__ void gemm_phase(LAS unsigned char* lds, const int K, const int lda, const int ldb, const Sched& S, const Epi& E) {
;     ...
;         const bool has_next = S.next(ui + 1, nxt);
;         const char* nA = has_next ? nxt.A : cA; const char* nB = has_next ? nxt.B : cB;
;         for (int t = 0; t < nt; t += 2) {
;             const bool last = (t == nt - 2);
;             const char* a1 = cA + (size_t)(t + 1) * kstep;
;             const char* a2 = last ? nA : cA + (size_t)(t + 2) * kstep; const char* b2 = last ? nB : cB + (size_t)(t + 2) * kstep;
;             const char* a3 = a2 + kstep; const char* b3 = b2 + kstep;
;             if constexpr (SP2) {
;             PG8_LDB(B0, 0, 0); PG8_LDB(B1, 0, 1); PG8_SCHED; PG8_LDA(At, 0, 0); PG8_STAGE(PG8_SA(1, 1), a1 + hstepA, voffA);
;             PG8_WAIT_V(8); PG8_WAIT_L(0); PG8_BAR; PG8_MMA(0, 0, At, B0); PG8_MMA(0, 1, At, B1); PG8_BAR; PG8_SCHED;
;     ...
; #pragma unroll
;         for (int a = 0; a < 2; ++a)
; #pragma unroll
;             for (int b = 0; b < 2; ++b)
; #pragma unroll
;                 for (int m = 0; m < 4; ++m)
; #pragma unroll
;                     for (int n = 0; n < 2; ++n) acc[a][b][m][n] = (f32x4){0.f, 0.f, 0.f, 0.f};
;         }
;         cur = nxt; cA = nA; cB = nB; ++ui;
.LBB0_154:
	s_add_u32 s20, s20, 0x80080
	s_addc_u32 s21, s21, 0
	s_add_u32 s13, s22, 0x100
	v_mov_b32_e32 v0, 0
	s_addc_u32 s74, s23, 0
	s_mov_b32 s75, -2
	v_mov_b32_e32 v1, v0
	v_mov_b32_e32 v2, v0
	v_mov_b32_e32 v3, v0
	v_mov_b32_e32 v4, v0
	v_mov_b32_e32 v5, v0
	v_mov_b32_e32 v6, v0
	v_mov_b32_e32 v7, v0
	v_mov_b32_e32 v16, v0
	v_mov_b32_e32 v17, v0
	v_mov_b32_e32 v18, v0
	v_mov_b32_e32 v19, v0
	v_mov_b32_e32 v20, v0
	v_mov_b32_e32 v21, v0
	v_mov_b32_e32 v22, v0
	v_mov_b32_e32 v23, v0
	v_mov_b32_e32 v32, v0
	v_mov_b32_e32 v33, v0
	v_mov_b32_e32 v34, v0
	v_mov_b32_e32 v35, v0
	v_mov_b32_e32 v36, v0
	v_mov_b32_e32 v37, v0
	v_mov_b32_e32 v38, v0
	v_mov_b32_e32 v39, v0
	v_mov_b32_e32 v48, v0
	v_mov_b32_e32 v49, v0
	v_mov_b32_e32 v50, v0
	v_mov_b32_e32 v51, v0
	v_mov_b32_e32 v52, v0
	v_mov_b32_e32 v53, v0
	v_mov_b32_e32 v54, v0
	v_mov_b32_e32 v55, v0
	v_mov_b32_e32 v8, v0
	v_mov_b32_e32 v9, v0
	v_mov_b32_e32 v10, v0
	v_mov_b32_e32 v11, v0
	v_mov_b32_e32 v12, v0
	v_mov_b32_e32 v13, v0
	v_mov_b32_e32 v14, v0
	v_mov_b32_e32 v15, v0
	v_mov_b32_e32 v24, v0
	v_mov_b32_e32 v25, v0
	v_mov_b32_e32 v26, v0
	v_mov_b32_e32 v27, v0
	v_mov_b32_e32 v28, v0
	v_mov_b32_e32 v29, v0
	v_mov_b32_e32 v30, v0
	v_mov_b32_e32 v31, v0
	v_mov_b32_e32 v40, v0
	v_mov_b32_e32 v41, v0
	v_mov_b32_e32 v42, v0
	v_mov_b32_e32 v43, v0
	v_mov_b32_e32 v44, v0
	v_mov_b32_e32 v45, v0
	v_mov_b32_e32 v46, v0
	v_mov_b32_e32 v47, v0
	v_mov_b32_e32 v56, v0
	v_mov_b32_e32 v57, v0
	v_mov_b32_e32 v58, v0
	v_mov_b32_e32 v59, v0
	v_mov_b32_e32 v60, v0
	v_mov_b32_e32 v61, v0
	v_mov_b32_e32 v62, v0
	v_mov_b32_e32 v63, v0
	v_mov_b32_e32 v64, v0
	v_mov_b32_e32 v65, v0
	v_mov_b32_e32 v66, v0
	v_mov_b32_e32 v67, v0
	v_mov_b32_e32 v68, v0
	v_mov_b32_e32 v69, v0
	v_mov_b32_e32 v70, v0
	v_mov_b32_e32 v71, v0
	v_mov_b32_e32 v80, v0
	v_mov_b32_e32 v81, v0
	v_mov_b32_e32 v82, v0
	v_mov_b32_e32 v83, v0
	v_mov_b32_e32 v84, v0
	v_mov_b32_e32 v85, v0
	v_mov_b32_e32 v86, v0
	v_mov_b32_e32 v87, v0
	v_mov_b32_e32 v96, v0
	v_mov_b32_e32 v97, v0
	v_mov_b32_e32 v98, v0
	v_mov_b32_e32 v99, v0
	v_mov_b32_e32 v100, v0
	v_mov_b32_e32 v101, v0
	v_mov_b32_e32 v102, v0
	v_mov_b32_e32 v103, v0
	v_mov_b32_e32 v112, v0
	v_mov_b32_e32 v113, v0
	v_mov_b32_e32 v114, v0
	v_mov_b32_e32 v115, v0
	v_mov_b32_e32 v116, v0
	v_mov_b32_e32 v117, v0
	v_mov_b32_e32 v118, v0
	v_mov_b32_e32 v119, v0
	v_mov_b32_e32 v72, v0
	v_mov_b32_e32 v73, v0
	v_mov_b32_e32 v74, v0
	v_mov_b32_e32 v75, v0
	v_mov_b32_e32 v76, v0
	v_mov_b32_e32 v77, v0
	v_mov_b32_e32 v78, v0
	v_mov_b32_e32 v79, v0
	v_mov_b32_e32 v88, v0
	v_mov_b32_e32 v89, v0
	v_mov_b32_e32 v90, v0
	v_mov_b32_e32 v91, v0
	v_mov_b32_e32 v92, v0
	v_mov_b32_e32 v93, v0
	v_mov_b32_e32 v94, v0
	v_mov_b32_e32 v95, v0
	v_mov_b32_e32 v104, v0
	v_mov_b32_e32 v105, v0
	v_mov_b32_e32 v106, v0
	v_mov_b32_e32 v107, v0
	v_mov_b32_e32 v108, v0
	v_mov_b32_e32 v109, v0
	v_mov_b32_e32 v110, v0
	v_mov_b32_e32 v111, v0
	v_mov_b32_e32 v120, v0
	v_mov_b32_e32 v121, v0
	v_mov_b32_e32 v122, v0
	v_mov_b32_e32 v123, v0
	v_mov_b32_e32 v124, v0
	v_mov_b32_e32 v125, v0
	v_mov_b32_e32 v126, v0
	v_mov_b32_e32 v127, v0
	v_readlane_b32 s98, v255, 13
	s_nop 4
	s_cmp_lt_u32 s98, 4
	s_cbranch_scc1 .Lprio_skip_155
	s_setprio 1
.Lprio_skip_155:
.LBB0_155:
	ds_read_b128 v[140:143], v147
	ds_read_b128 v[150:153], v147 offset:1024
	ds_read_b128 v[154:157], v147 offset:2048
	ds_read_b128 v[158:161], v147 offset:3072
	ds_read_b128 v[162:165], v148
	ds_read_b128 v[166:169], v148 offset:1024
	ds_read_b128 v[170:173], v148 offset:2048
	ds_read_b128 v[180:183], v148 offset:3072
	s_add_u32 s22, s20, 0xfff80080
	s_addc_u32 s23, s21, -1
	s_cmp_eq_u32 s75, 28
	s_cselect_b32 s25, s15, s23
	s_cselect_b32 s24, s14, s22
	s_cselect_b32 s23, s17, s74
	s_cselect_b32 s22, s16, s13
	v_lshl_add_u64 v[174:175], s[20:21], 0, v[136:137]
	s_add_i32 m0, s3, 0xc000
	ds_read_b128 v[184:187], v149
	ds_read_b128 v[188:191], v149 offset:1024
	ds_read_b128 v[192:195], v149 offset:2048
	ds_read_b128 v[196:199], v149 offset:3072
	ds_read_b128 v[200:203], v149 offset:4096
	ds_read_b128 v[204:207], v149 offset:5120
	ds_read_b128 v[208:211], v149 offset:6144
	ds_read_b128 v[212:215], v149 offset:7168
	global_load_lds_dwordx4 v[174:175], off
	v_lshl_add_u64 v[174:175], s[20:21], 0, v[138:139]
	s_add_i32 m0, s3, 0xe000
	s_nop 0
	global_load_lds_dwordx4 v[174:175], off
	s_waitcnt vmcnt(8)
	s_waitcnt lgkmcnt(0)
	s_barrier
	s_waitcnt lgkmcnt(0)
	v_mfma_f32_16x16x32_bf16 v[124:127], v[140:143], v[184:187], v[124:127]
	v_mfma_f32_16x16x32_bf16 v[120:123], v[154:157], v[184:187], v[120:123]
	v_mfma_f32_16x16x32_bf16 v[108:111], v[140:143], v[192:195], v[108:111]
	v_mfma_f32_16x16x32_bf16 v[104:107], v[154:157], v[192:195], v[104:107]
	v_mfma_f32_16x16x32_bf16 v[92:95], v[140:143], v[200:203], v[92:95]
	v_mfma_f32_16x16x32_bf16 v[88:91], v[154:157], v[200:203], v[88:91]
	v_mfma_f32_16x16x32_bf16 v[76:79], v[140:143], v[208:211], v[76:79]
	v_mfma_f32_16x16x32_bf16 v[72:75], v[154:157], v[208:211], v[72:75]
	v_mfma_f32_16x16x32_bf16 v[124:127], v[150:153], v[188:191], v[124:127]
	v_mfma_f32_16x16x32_bf16 v[120:123], v[158:161], v[188:191], v[120:123]
	v_mfma_f32_16x16x32_bf16 v[108:111], v[150:153], v[196:199], v[108:111]
	v_mfma_f32_16x16x32_bf16 v[104:107], v[158:161], v[196:199], v[104:107]
	v_mfma_f32_16x16x32_bf16 v[92:95], v[150:153], v[204:207], v[92:95]
	v_mfma_f32_16x16x32_bf16 v[88:91], v[158:161], v[204:207], v[88:91]
	v_mfma_f32_16x16x32_bf16 v[76:79], v[150:153], v[212:215], v[76:79]
	v_mfma_f32_16x16x32_bf16 v[72:75], v[158:161], v[212:215], v[72:75]
	v_mfma_f32_16x16x32_bf16 v[116:119], v[162:165], v[184:187], v[116:119]
	v_mfma_f32_16x16x32_bf16 v[112:115], v[170:173], v[184:187], v[112:115]
	v_mfma_f32_16x16x32_bf16 v[100:103], v[162:165], v[192:195], v[100:103]
	v_mfma_f32_16x16x32_bf16 v[96:99], v[170:173], v[192:195], v[96:99]
	v_mfma_f32_16x16x32_bf16 v[84:87], v[162:165], v[200:203], v[84:87]
	v_mfma_f32_16x16x32_bf16 v[80:83], v[170:173], v[200:203], v[80:83]
	v_mfma_f32_16x16x32_bf16 v[68:71], v[162:165], v[208:211], v[68:71]
	v_mfma_f32_16x16x32_bf16 v[64:67], v[170:173], v[208:211], v[64:67]
	v_mfma_f32_16x16x32_bf16 v[116:119], v[166:169], v[188:191], v[116:119]
	v_mfma_f32_16x16x32_bf16 v[112:115], v[180:183], v[188:191], v[112:115]
	v_mfma_f32_16x16x32_bf16 v[100:103], v[166:169], v[196:199], v[100:103]
	v_mfma_f32_16x16x32_bf16 v[96:99], v[180:183], v[196:199], v[96:99]
	v_mfma_f32_16x16x32_bf16 v[84:87], v[166:169], v[204:207], v[84:87]
	v_mfma_f32_16x16x32_bf16 v[80:83], v[180:183], v[204:207], v[80:83]
	v_mfma_f32_16x16x32_bf16 v[68:71], v[166:169], v[212:215], v[68:71]
	v_mfma_f32_16x16x32_bf16 v[64:67], v[180:183], v[212:215], v[64:67]
	s_barrier
; #define PG8_STAGE(bufoff, gbase, voff) do { _Pragma("unroll") for (int _i = 0; _i < 2; ++_i) \
;         __builtin_amdgcn_global_load_lds((const unsigned*)((const char*)(gbase) + (voff)[_i]), (LAS unsigned*)(lds + (bufoff) + ldsw + _i * 8192), 16, 0, 0); } while (0)
; #define PG8_LDA(dst, b, h) do { _Pragma("unroll") for (int m = 0; m < 4; ++m) _Pragma("unroll") for (int k = 0; k < 2; ++k) dst[m][k] = *(const LAS bf16x8*)(lds + PG8_SA(b, h) + aoff + m * 2048 + k * 1024); } while (0)
; #define PG8_LDB(dst, b, h) do { _Pragma("unroll") for (int n = 0; n < 2; ++n) _Pragma("unroll") for (int k = 0; k < 2; ++k) dst[n][k] = *(const LAS bf16x8*)(lds + PG8_SB(b, h) + boff + n * 2048 + k * 1024); } while (0)
; #define PG8_MMA(ai, bj, At, Bt) do { __builtin_amdgcn_s_setprio(1); _Pragma("unroll") for (int m = 0; m < 4; ++m) _Pragma("unroll") for (int n = 0; n < 2; ++n) _Pragma("unroll") for (int k = 0; k < 2; ++k) \
;         acc[ai][bj][m][n] = __builtin_amdgcn_mfma_f32_16x16x32_bf16(Bt[n][k], At[m][k], acc[ai][bj][m][n], 0, 0, 0); __builtin_amdgcn_s_setprio(0); } while (0)
; #define PG8_WAIT_V(n) asm volatile("s_waitcnt vmcnt(" #n ")" ::: "memory")
; #define PG8_WAIT_L(n) asm volatile("s_waitcnt lgkmcnt(" #n ")" ::: "memory")
; #define PG8_BAR __builtin_amdgcn_s_barrier()
; #define PG8_SCHED __builtin_amdgcn_sched_barrier(0)
; template <class Sched, class Epi, bool ALIGN_EPI, bool SP2>
; __device__ __forceinline__ void gemm_phase(LAS unsigned char* lds, const int K, const int lda, const int ldb, const Sched& S, const Epi& E) {
;     ...
;             PG8_LDA(At, 0, 1); PG8_STAGE(PG8_SB(0, 0), b2, voffB); PG8_STAGE(PG8_SB(0, 1), b2 + hstepB, voffB); PG8_STAGE(PG8_SA(0, 0), a2, voffA);
;             PG8_WAIT_V(8); PG8_WAIT_L(0); PG8_BAR; PG8_MMA(1, 0, At, B0); PG8_MMA(1, 1, At, B1); PG8_BAR; PG8_SCHED;
;             PG8_LDB(B0, 1, 0); PG8_LDB(B1, 1, 1); PG8_SCHED; PG8_LDA(At, 1, 0); PG8_STAGE(PG8_SA(0, 1), a2 + hstepA, voffA);
	s_add_i32 s78, s35, s2
	v_lshl_add_u64 v[174:175], s[22:23], 0, v[130:131]
	s_mov_b32 m0, s78
	ds_read_b128 v[184:187], v149 offset:16384
	ds_read_b128 v[188:191], v149 offset:17408
	ds_read_b128 v[192:195], v149 offset:18432
	ds_read_b128 v[196:199], v149 offset:19456
	ds_read_b128 v[200:203], v149 offset:20480
	ds_read_b128 v[204:207], v149 offset:21504
	ds_read_b128 v[208:211], v149 offset:22528
	ds_read_b128 v[212:215], v149 offset:23552
	global_load_lds_dwordx4 v[174:175], off
	s_add_i32 m0, s78, 0x2000
	s_add_u32 s78, s22, 0x80000
	v_lshl_add_u64 v[216:217], s[22:23], 0, v[134:135]
	s_addc_u32 s79, s23, 0
	s_add_i32 s84, s50, s2
	global_load_lds_dwordx4 v[216:217], off
	v_lshl_add_u64 v[218:219], s[78:79], 0, v[130:131]
	s_mov_b32 m0, s84
	v_lshl_add_u64 v[220:221], s[24:25], 0, v[132:133]
	global_load_lds_dwordx4 v[218:219], off
	v_lshl_add_u64 v[218:219], s[78:79], 0, v[134:135]
	s_add_i32 m0, s84, 0x2000
	s_nop 0
	global_load_lds_dwordx4 v[218:219], off
	v_lshl_add_u64 v[218:219], s[24:25], 0, v[128:129]
	s_mov_b32 m0, s3
	s_nop 0
	global_load_lds_dwordx4 v[218:219], off
	s_mov_b32 m0, s19
	s_nop 0
	global_load_lds_dwordx4 v[220:221], off
	s_waitcnt vmcnt(8)
	s_waitcnt lgkmcnt(0)
	s_barrier
	s_waitcnt lgkmcnt(0)
	v_mfma_f32_16x16x32_bf16 v[60:63], v[140:143], v[184:187], v[60:63]
	v_mfma_f32_16x16x32_bf16 v[56:59], v[154:157], v[184:187], v[56:59]
	v_mfma_f32_16x16x32_bf16 v[44:47], v[140:143], v[192:195], v[44:47]
	v_mfma_f32_16x16x32_bf16 v[40:43], v[154:157], v[192:195], v[40:43]
	v_mfma_f32_16x16x32_bf16 v[28:31], v[140:143], v[200:203], v[28:31]
	v_mfma_f32_16x16x32_bf16 v[24:27], v[154:157], v[200:203], v[24:27]
	v_mfma_f32_16x16x32_bf16 v[12:15], v[140:143], v[208:211], v[12:15]
	v_mfma_f32_16x16x32_bf16 v[8:11], v[154:157], v[208:211], v[8:11]
	v_mfma_f32_16x16x32_bf16 v[60:63], v[150:153], v[188:191], v[60:63]
	v_mfma_f32_16x16x32_bf16 v[56:59], v[158:161], v[188:191], v[56:59]
	v_mfma_f32_16x16x32_bf16 v[44:47], v[150:153], v[196:199], v[44:47]
	v_mfma_f32_16x16x32_bf16 v[40:43], v[158:161], v[196:199], v[40:43]
	v_mfma_f32_16x16x32_bf16 v[28:31], v[150:153], v[204:207], v[28:31]
	v_mfma_f32_16x16x32_bf16 v[24:27], v[158:161], v[204:207], v[24:27]
	v_mfma_f32_16x16x32_bf16 v[12:15], v[150:153], v[212:215], v[12:15]
	v_mfma_f32_16x16x32_bf16 v[8:11], v[158:161], v[212:215], v[8:11]
	v_mfma_f32_16x16x32_bf16 v[52:55], v[162:165], v[184:187], v[52:55]
	v_mfma_f32_16x16x32_bf16 v[48:51], v[170:173], v[184:187], v[48:51]
	v_mfma_f32_16x16x32_bf16 v[36:39], v[162:165], v[192:195], v[36:39]
	v_mfma_f32_16x16x32_bf16 v[32:35], v[170:173], v[192:195], v[32:35]
	v_mfma_f32_16x16x32_bf16 v[20:23], v[162:165], v[200:203], v[20:23]
	v_mfma_f32_16x16x32_bf16 v[16:19], v[170:173], v[200:203], v[16:19]
	v_mfma_f32_16x16x32_bf16 v[4:7], v[162:165], v[208:211], v[4:7]
	v_mfma_f32_16x16x32_bf16 v[0:3], v[170:173], v[208:211], v[0:3]
	v_mfma_f32_16x16x32_bf16 v[52:55], v[166:169], v[188:191], v[52:55]
	v_mfma_f32_16x16x32_bf16 v[48:51], v[180:183], v[188:191], v[48:51]
	v_mfma_f32_16x16x32_bf16 v[36:39], v[166:169], v[196:199], v[36:39]
	v_mfma_f32_16x16x32_bf16 v[32:35], v[180:183], v[196:199], v[32:35]
	v_mfma_f32_16x16x32_bf16 v[20:23], v[166:169], v[204:207], v[20:23]
	v_mfma_f32_16x16x32_bf16 v[16:19], v[180:183], v[204:207], v[16:19]
	v_mfma_f32_16x16x32_bf16 v[4:7], v[166:169], v[212:215], v[4:7]
	v_mfma_f32_16x16x32_bf16 v[0:3], v[180:183], v[212:215], v[0:3]
	s_barrier
	s_add_i32 s78, 0, 0x18000
	s_add_i32 s79, 0, 0x1c000
	v_add_u32_e32 v158, s78, v145
	v_add_u32_e32 v177, s79, v145
	ds_read_b128 v[140:143], v158
	ds_read_b128 v[150:153], v158 offset:1024
	ds_read_b128 v[154:157], v158 offset:2048
	ds_read_b128 v[158:161], v158 offset:3072
	ds_read_b128 v[162:165], v177
	ds_read_b128 v[166:169], v177 offset:1024
	ds_read_b128 v[170:173], v177 offset:2048
	ds_read_b128 v[180:183], v177 offset:3072
	s_add_u32 s24, s24, 0x80000
	s_addc_u32 s25, s25, 0
	s_mov_b32 m0, s26
	v_lshl_add_u64 v[222:223], s[24:25], 0, v[128:129]
	ds_read_b128 v[184:187], v149 offset:32768
	ds_read_b128 v[188:191], v149 offset:33792
	ds_read_b128 v[192:195], v149 offset:34816
	ds_read_b128 v[196:199], v149 offset:35840
	ds_read_b128 v[200:203], v149 offset:36864
	ds_read_b128 v[204:207], v149 offset:37888
	ds_read_b128 v[208:211], v149 offset:38912
	ds_read_b128 v[212:215], v149 offset:39936
	global_load_lds_dwordx4 v[222:223], off
	v_lshl_add_u64 v[222:223], s[24:25], 0, v[132:133]
	s_mov_b32 m0, s27
	s_nop 0
	global_load_lds_dwordx4 v[222:223], off
	s_waitcnt vmcnt(8)
	s_waitcnt lgkmcnt(0)
	s_barrier
; #define PG8_STAGE(bufoff, gbase, voff) do { _Pragma("unroll") for (int _i = 0; _i < 2; ++_i) \
;         __builtin_amdgcn_global_load_lds((const unsigned*)((const char*)(gbase) + (voff)[_i]), (LAS unsigned*)(lds + (bufoff) + ldsw + _i * 8192), 16, 0, 0); } while (0)
; #define PG8_LDA(dst, b, h) do { _Pragma("unroll") for (int m = 0; m < 4; ++m) _Pragma("unroll") for (int k = 0; k < 2; ++k) dst[m][k] = *(const LAS bf16x8*)(lds + PG8_SA(b, h) + aoff + m * 2048 + k * 1024); } while (0)
; #define PG8_MMA(ai, bj, At, Bt) do { __builtin_amdgcn_s_setprio(1); _Pragma("unroll") for (int m = 0; m < 4; ++m) _Pragma("unroll") for (int n = 0; n < 2; ++n) _Pragma("unroll") for (int k = 0; k < 2; ++k) \
;         acc[ai][bj][m][n] = __builtin_amdgcn_mfma_f32_16x16x32_bf16(Bt[n][k], At[m][k], acc[ai][bj][m][n], 0, 0, 0); __builtin_amdgcn_s_setprio(0); } while (0)
; #define PG8_WAIT_V(n) asm volatile("s_waitcnt vmcnt(" #n ")" ::: "memory")
; #define PG8_WAIT_L(n) asm volatile("s_waitcnt lgkmcnt(" #n ")" ::: "memory")
; #define PG8_BAR __builtin_amdgcn_s_barrier()
; #define PG8_SCHED __builtin_amdgcn_sched_barrier(0)
; template <class Sched, class Epi, bool ALIGN_EPI, bool SP2>
; __device__ __forceinline__ void gemm_phase(LAS unsigned char* lds, const int K, const int lda, const int ldb, const Sched& S, const Epi& E) {
;     ...
;         for (int t = 0; t < nt; t += 2) {
;             const bool last = (t == nt - 2);
;             const char* a1 = cA + (size_t)(t + 1) * kstep;
;             const char* a2 = last ? nA : cA + (size_t)(t + 2) * kstep; const char* b2 = last ? nB : cB + (size_t)(t + 2) * kstep;
;     ...
;             PG8_WAIT_V(8); PG8_WAIT_L(0); PG8_BAR; PG8_MMA(0, 0, At, B0); PG8_MMA(0, 1, At, B1); PG8_BAR; PG8_SCHED;
;             PG8_LDA(At, 1, 1); PG8_STAGE(PG8_SB(1, 0), b3, voffB); PG8_STAGE(PG8_SB(1, 1), b3 + hstepB, voffB); PG8_STAGE(PG8_SA(1, 0), a3, voffA);
;             PG8_WAIT_V(8); PG8_WAIT_L(0); PG8_BAR; PG8_MMA(1, 0, At, B0); PG8_MMA(1, 1, At, B1); PG8_BAR; PG8_SCHED;
	s_waitcnt lgkmcnt(0)
	v_mfma_f32_16x16x32_bf16 v[124:127], v[140:143], v[184:187], v[124:127]
	v_mfma_f32_16x16x32_bf16 v[120:123], v[154:157], v[184:187], v[120:123]
	v_mfma_f32_16x16x32_bf16 v[108:111], v[140:143], v[192:195], v[108:111]
	v_mfma_f32_16x16x32_bf16 v[104:107], v[154:157], v[192:195], v[104:107]
	v_mfma_f32_16x16x32_bf16 v[92:95], v[140:143], v[200:203], v[92:95]
	v_mfma_f32_16x16x32_bf16 v[88:91], v[154:157], v[200:203], v[88:91]
	v_mfma_f32_16x16x32_bf16 v[76:79], v[140:143], v[208:211], v[76:79]
	v_mfma_f32_16x16x32_bf16 v[72:75], v[154:157], v[208:211], v[72:75]
	v_mfma_f32_16x16x32_bf16 v[124:127], v[150:153], v[188:191], v[124:127]
	v_mfma_f32_16x16x32_bf16 v[120:123], v[158:161], v[188:191], v[120:123]
	v_mfma_f32_16x16x32_bf16 v[108:111], v[150:153], v[196:199], v[108:111]
	v_mfma_f32_16x16x32_bf16 v[104:107], v[158:161], v[196:199], v[104:107]
	v_mfma_f32_16x16x32_bf16 v[92:95], v[150:153], v[204:207], v[92:95]
	v_mfma_f32_16x16x32_bf16 v[88:91], v[158:161], v[204:207], v[88:91]
	v_mfma_f32_16x16x32_bf16 v[76:79], v[150:153], v[212:215], v[76:79]
	v_mfma_f32_16x16x32_bf16 v[72:75], v[158:161], v[212:215], v[72:75]
	v_mfma_f32_16x16x32_bf16 v[116:119], v[162:165], v[184:187], v[116:119]
	v_mfma_f32_16x16x32_bf16 v[112:115], v[170:173], v[184:187], v[112:115]
	v_mfma_f32_16x16x32_bf16 v[100:103], v[162:165], v[192:195], v[100:103]
	v_mfma_f32_16x16x32_bf16 v[96:99], v[170:173], v[192:195], v[96:99]
	v_mfma_f32_16x16x32_bf16 v[84:87], v[162:165], v[200:203], v[84:87]
	v_mfma_f32_16x16x32_bf16 v[80:83], v[170:173], v[200:203], v[80:83]
	v_mfma_f32_16x16x32_bf16 v[68:71], v[162:165], v[208:211], v[68:71]
	v_mfma_f32_16x16x32_bf16 v[64:67], v[170:173], v[208:211], v[64:67]
	v_mfma_f32_16x16x32_bf16 v[116:119], v[166:169], v[188:191], v[116:119]
	v_mfma_f32_16x16x32_bf16 v[112:115], v[180:183], v[188:191], v[112:115]
	v_mfma_f32_16x16x32_bf16 v[100:103], v[166:169], v[196:199], v[100:103]
	v_mfma_f32_16x16x32_bf16 v[96:99], v[180:183], v[196:199], v[96:99]
	v_mfma_f32_16x16x32_bf16 v[84:87], v[166:169], v[204:207], v[84:87]
	v_mfma_f32_16x16x32_bf16 v[80:83], v[180:183], v[204:207], v[80:83]
	v_mfma_f32_16x16x32_bf16 v[68:71], v[166:169], v[212:215], v[68:71]
	v_mfma_f32_16x16x32_bf16 v[64:67], v[180:183], v[212:215], v[64:67]
	s_barrier
	s_add_i32 s24, s78, s2
	v_lshl_add_u64 v[174:175], v[174:175], 0, s[4:5]
	s_mov_b32 m0, s24
	ds_read_b128 v[184:187], v149 offset:49152
	ds_read_b128 v[188:191], v149 offset:50176
	ds_read_b128 v[192:195], v149 offset:51200
	ds_read_b128 v[196:199], v149 offset:52224
	ds_read_b128 v[200:203], v149 offset:53248
	ds_read_b128 v[204:207], v149 offset:54272
	ds_read_b128 v[208:211], v149 offset:55296
	ds_read_b128 v[212:215], v149 offset:56320
	global_load_lds_dwordx4 v[174:175], off
	s_add_i32 m0, s24, 0x2000
	s_add_u32 s22, s22, 0x80080
	v_lshl_add_u64 v[174:175], v[216:217], 0, s[4:5]
	s_addc_u32 s23, s23, 0
	s_add_i32 s24, s79, s2
	global_load_lds_dwordx4 v[174:175], off
	v_lshl_add_u64 v[174:175], s[22:23], 0, v[130:131]
	s_mov_b32 m0, s24
	s_nop 0
	global_load_lds_dwordx4 v[174:175], off
	v_lshl_add_u64 v[174:175], s[22:23], 0, v[134:135]
	s_add_i32 m0, s24, 0x2000
	s_nop 0
	global_load_lds_dwordx4 v[174:175], off
	v_lshl_add_u64 v[174:175], v[218:219], 0, s[4:5]
	s_mov_b32 m0, s29
	s_nop 0
	global_load_lds_dwordx4 v[174:175], off
	v_lshl_add_u64 v[174:175], v[220:221], 0, s[4:5]
	s_mov_b32 m0, s33
	s_nop 0
	global_load_lds_dwordx4 v[174:175], off
	s_waitcnt vmcnt(8)
	s_waitcnt lgkmcnt(0)
	s_barrier
	s_waitcnt lgkmcnt(0)
	v_mfma_f32_16x16x32_bf16 v[60:63], v[140:143], v[184:187], v[60:63]
	v_mfma_f32_16x16x32_bf16 v[56:59], v[154:157], v[184:187], v[56:59]
	v_mfma_f32_16x16x32_bf16 v[44:47], v[140:143], v[192:195], v[44:47]
	v_mfma_f32_16x16x32_bf16 v[40:43], v[154:157], v[192:195], v[40:43]
	v_mfma_f32_16x16x32_bf16 v[28:31], v[140:143], v[200:203], v[28:31]
	v_mfma_f32_16x16x32_bf16 v[24:27], v[154:157], v[200:203], v[24:27]
	v_mfma_f32_16x16x32_bf16 v[12:15], v[140:143], v[208:211], v[12:15]
	v_mfma_f32_16x16x32_bf16 v[8:11], v[154:157], v[208:211], v[8:11]
	v_mfma_f32_16x16x32_bf16 v[60:63], v[150:153], v[188:191], v[60:63]
	v_mfma_f32_16x16x32_bf16 v[56:59], v[158:161], v[188:191], v[56:59]
	v_mfma_f32_16x16x32_bf16 v[44:47], v[150:153], v[196:199], v[44:47]
	v_mfma_f32_16x16x32_bf16 v[40:43], v[158:161], v[196:199], v[40:43]
	v_mfma_f32_16x16x32_bf16 v[28:31], v[150:153], v[204:207], v[28:31]
	v_mfma_f32_16x16x32_bf16 v[24:27], v[158:161], v[204:207], v[24:27]
	v_mfma_f32_16x16x32_bf16 v[12:15], v[150:153], v[212:215], v[12:15]
	v_mfma_f32_16x16x32_bf16 v[8:11], v[158:161], v[212:215], v[8:11]
	v_mfma_f32_16x16x32_bf16 v[52:55], v[162:165], v[184:187], v[52:55]
	v_mfma_f32_16x16x32_bf16 v[48:51], v[170:173], v[184:187], v[48:51]
	v_mfma_f32_16x16x32_bf16 v[36:39], v[162:165], v[192:195], v[36:39]
	v_mfma_f32_16x16x32_bf16 v[32:35], v[170:173], v[192:195], v[32:35]
	v_mfma_f32_16x16x32_bf16 v[20:23], v[162:165], v[200:203], v[20:23]
	v_mfma_f32_16x16x32_bf16 v[16:19], v[170:173], v[200:203], v[16:19]
	v_mfma_f32_16x16x32_bf16 v[4:7], v[162:165], v[208:211], v[4:7]
	v_mfma_f32_16x16x32_bf16 v[0:3], v[170:173], v[208:211], v[0:3]
	v_mfma_f32_16x16x32_bf16 v[52:55], v[166:169], v[188:191], v[52:55]
	v_mfma_f32_16x16x32_bf16 v[48:51], v[180:183], v[188:191], v[48:51]
	v_mfma_f32_16x16x32_bf16 v[36:39], v[166:169], v[196:199], v[36:39]
	v_mfma_f32_16x16x32_bf16 v[32:35], v[180:183], v[196:199], v[32:35]
	v_mfma_f32_16x16x32_bf16 v[20:23], v[166:169], v[204:207], v[20:23]
	v_mfma_f32_16x16x32_bf16 v[16:19], v[180:183], v[204:207], v[16:19]
	v_mfma_f32_16x16x32_bf16 v[4:7], v[166:169], v[212:215], v[4:7]
	v_mfma_f32_16x16x32_bf16 v[0:3], v[180:183], v[212:215], v[0:3]
	s_barrier
	s_add_i32 s75, s75, 2
	s_add_u32 s20, s20, 0x100
	s_addc_u32 s21, s21, 0
	s_add_u32 s13, s13, 0x100
	s_addc_u32 s74, s74, 0
	s_cmp_gt_u32 s75, 29
	s_cbranch_scc0 .LBB0_155
	s_setprio 0
	s_and_b64 vcc, exec, s[6:7]
	s_cbranch_vccz .LBB0_158
	s_barrier

; #define PG8_STAGE(bufoff, gbase, voff) do { _Pragma("unroll") for (int _i = 0; _i < 2; ++_i) \
;         __builtin_amdgcn_global_load_lds((const unsigned*)((const char*)(gbase) + (voff)[_i]), (LAS unsigned*)(lds + (bufoff) + ldsw + _i * 8192), 16, 0, 0); } while (0)
; #define PG8_LDA(dst, b, h) do { _Pragma("unroll") for (int m = 0; m < 4; ++m) _Pragma("unroll") for (int k = 0; k < 2; ++k) dst[m][k] = *(const LAS bf16x8*)(lds + PG8_SA(b, h) + aoff + m * 2048 + k * 1024); } while (0)
; #define PG8_LDB(dst, b, h) do { _Pragma("unroll") for (int n = 0; n < 2; ++n) _Pragma("unroll") for (int k = 0; k < 2; ++k) dst[n][k] = *(const LAS bf16x8*)(lds + PG8_SB(b, h) + boff + n * 2048 + k * 1024); } while (0)
; #define PG8_WAIT_V(n) asm volatile("s_waitcnt vmcnt(" #n ")" ::: "memory")
; #define PG8_WAIT_L(n) asm volatile("s_waitcnt lgkmcnt(" #n ")" ::: "memory")
; #define PG8_BAR __builtin_amdgcn_s_barrier()
; #define PG8_SCHED __builtin_amdgcn_sched_barrier(0)
; template <class Sched, class Epi, bool ALIGN_EPI, bool SP2>
; __device__ __forceinline__ void gemm_phase(LAS unsigned char* lds, const int K, const int lda, const int ldb, const Sched& S, const Epi& E) {
;     ...
;         const bool has_next = S.next(ui + 1, nxt);
;         const char* nA = has_next ? nxt.A : cA; const char* nB = has_next ? nxt.B : cB;
;         for (int t = 0; t < nt; t += 2) {
;             const bool last = (t == nt - 2);
;             const char* a1 = cA + (size_t)(t + 1) * kstep;
;             const char* a2 = last ? nA : cA + (size_t)(t + 2) * kstep; const char* b2 = last ? nB : cB + (size_t)(t + 2) * kstep;
;             const char* a3 = a2 + kstep; const char* b3 = b2 + kstep;
;             if constexpr (SP2) {
;             PG8_LDB(B0, 0, 0); PG8_LDB(B1, 0, 1); PG8_SCHED; PG8_LDA(At, 0, 0); PG8_STAGE(PG8_SA(1, 1), a1 + hstepA, voffA);
;             PG8_WAIT_V(8); PG8_WAIT_L(0); PG8_BAR; PG8_MMA(0, 0, At, B0); PG8_MMA(0, 1, At, B1); PG8_BAR; PG8_SCHED;
;     ...
; #pragma unroll
;         for (int a = 0; a < 2; ++a)
; #pragma unroll
;             for (int b = 0; b < 2; ++b)
; #pragma unroll
;                 for (int m = 0; m < 4; ++m)
; #pragma unroll
;                     for (int n = 0; n < 2; ++n) acc[a][b][m][n] = (f32x4){0.f, 0.f, 0.f, 0.f};
;         }
;         cur = nxt; cA = nA; cB = nB; ++ui;
.LBB0_242:
	s_add_u32 s89, s22, 0x100
	v_mov_b32_e32 v0, 0
	s_addc_u32 s90, s23, 0
	s_mov_b32 s91, -2
	v_mov_b32_e32 v1, v0
	s_waitcnt lgkmcnt(0)
	v_mov_b32_e32 v2, v0
	v_mov_b32_e32 v3, v0
	v_mov_b32_e32 v4, v0
	v_mov_b32_e32 v5, v0
	v_mov_b32_e32 v6, v0
	v_mov_b32_e32 v7, v0
	v_mov_b32_e32 v16, v0
	v_mov_b32_e32 v17, v0
	v_mov_b32_e32 v18, v0
	v_mov_b32_e32 v19, v0
	v_mov_b32_e32 v20, v0
	v_mov_b32_e32 v21, v0
	v_mov_b32_e32 v22, v0
	v_mov_b32_e32 v23, v0
	v_mov_b32_e32 v32, v0
	v_mov_b32_e32 v33, v0
	v_mov_b32_e32 v34, v0
	v_mov_b32_e32 v35, v0
	v_mov_b32_e32 v36, v0
	v_mov_b32_e32 v37, v0
	v_mov_b32_e32 v38, v0
	v_mov_b32_e32 v39, v0
	v_mov_b32_e32 v48, v0
	v_mov_b32_e32 v49, v0
	v_mov_b32_e32 v50, v0
	v_mov_b32_e32 v51, v0
	v_mov_b32_e32 v52, v0
	v_mov_b32_e32 v53, v0
	v_mov_b32_e32 v54, v0
	v_mov_b32_e32 v55, v0
	v_mov_b32_e32 v8, v0
	v_mov_b32_e32 v9, v0
	v_mov_b32_e32 v10, v0
	v_mov_b32_e32 v11, v0
	v_mov_b32_e32 v12, v0
	v_mov_b32_e32 v13, v0
	v_mov_b32_e32 v14, v0
	v_mov_b32_e32 v15, v0
	v_mov_b32_e32 v24, v0
	v_mov_b32_e32 v25, v0
	v_mov_b32_e32 v26, v0
	v_mov_b32_e32 v27, v0
	v_mov_b32_e32 v28, v0
	v_mov_b32_e32 v29, v0
	v_mov_b32_e32 v30, v0
	v_mov_b32_e32 v31, v0
	v_mov_b32_e32 v40, v0
	v_mov_b32_e32 v41, v0
	v_mov_b32_e32 v42, v0
	v_mov_b32_e32 v43, v0
	v_mov_b32_e32 v44, v0
	v_mov_b32_e32 v45, v0
	v_mov_b32_e32 v46, v0
	v_mov_b32_e32 v47, v0
	v_mov_b32_e32 v56, v0
	v_mov_b32_e32 v57, v0
	v_mov_b32_e32 v58, v0
	v_mov_b32_e32 v59, v0
	v_mov_b32_e32 v60, v0
	v_mov_b32_e32 v61, v0
	v_mov_b32_e32 v62, v0
	v_mov_b32_e32 v63, v0
	v_mov_b32_e32 v64, v0
	v_mov_b32_e32 v65, v0
	v_mov_b32_e32 v66, v0
	v_mov_b32_e32 v67, v0
	v_mov_b32_e32 v68, v0
	v_mov_b32_e32 v69, v0
	v_mov_b32_e32 v70, v0
	v_mov_b32_e32 v71, v0
	v_mov_b32_e32 v80, v0
	v_mov_b32_e32 v81, v0
	v_mov_b32_e32 v82, v0
	v_mov_b32_e32 v83, v0
	v_mov_b32_e32 v84, v0
	v_mov_b32_e32 v85, v0
	v_mov_b32_e32 v86, v0
	v_mov_b32_e32 v87, v0
	v_mov_b32_e32 v96, v0
	v_mov_b32_e32 v97, v0
	v_mov_b32_e32 v98, v0
	v_mov_b32_e32 v99, v0
	v_mov_b32_e32 v100, v0
	v_mov_b32_e32 v101, v0
	v_mov_b32_e32 v102, v0
	v_mov_b32_e32 v103, v0
	v_mov_b32_e32 v112, v0
	v_mov_b32_e32 v113, v0
	v_mov_b32_e32 v114, v0
	v_mov_b32_e32 v115, v0
	v_mov_b32_e32 v116, v0
	v_mov_b32_e32 v117, v0
	v_mov_b32_e32 v118, v0
	v_mov_b32_e32 v119, v0
	v_mov_b32_e32 v72, v0
	v_mov_b32_e32 v73, v0
	v_mov_b32_e32 v74, v0
	v_mov_b32_e32 v75, v0
	v_mov_b32_e32 v76, v0
	v_mov_b32_e32 v77, v0
	v_mov_b32_e32 v78, v0
	v_mov_b32_e32 v79, v0
	v_mov_b32_e32 v88, v0
	v_mov_b32_e32 v89, v0
	v_mov_b32_e32 v90, v0
	v_mov_b32_e32 v91, v0
	v_mov_b32_e32 v92, v0
	v_mov_b32_e32 v93, v0
	v_mov_b32_e32 v94, v0
	v_mov_b32_e32 v95, v0
	v_mov_b32_e32 v104, v0
	v_mov_b32_e32 v105, v0
	v_mov_b32_e32 v106, v0
	v_mov_b32_e32 v107, v0
	v_mov_b32_e32 v108, v0
	v_mov_b32_e32 v109, v0
	v_mov_b32_e32 v110, v0
	v_mov_b32_e32 v111, v0
	v_mov_b32_e32 v120, v0
	v_mov_b32_e32 v121, v0
	v_mov_b32_e32 v122, v0
	v_mov_b32_e32 v123, v0
	v_mov_b32_e32 v128, v0
	v_mov_b32_e32 v129, v0
	v_mov_b32_e32 v130, v0
	v_mov_b32_e32 v131, v0
	v_readlane_b32 s98, v255, 13
	s_nop 4
	s_cmp_lt_u32 s98, 4
	s_cbranch_scc1 .Lprio_skip_243
	s_setprio 1
.Lprio_skip_243:
.LBB0_243:
	ds_read_b128 v[124:127], v169
	ds_read_b128 v[132:135], v169 offset:1024
	ds_read_b128 v[136:139], v169 offset:2048
	ds_read_b128 v[140:143], v169 offset:3072
	ds_read_b128 v[144:147], v170
	ds_read_b128 v[156:159], v170 offset:1024
	ds_read_b128 v[160:163], v170 offset:2048
	ds_read_b128 v[182:185], v170 offset:3072
	s_add_u32 s22, s20, 0x100
	s_addc_u32 s23, s21, 0
	s_cmpk_eq_i32 s91, 0x54
	s_cselect_b32 s27, s17, s23
	s_cselect_b32 s26, s16, s22
	s_cselect_b32 s25, s19, s90
	s_cselect_b32 s24, s18, s89
	s_mov_b32 m0, s78
	v_lshl_add_u64 v[164:165], s[20:21], 0, v[152:153]
	ds_read_b128 v[186:189], v171
	ds_read_b128 v[190:193], v171 offset:1024
	ds_read_b128 v[194:197], v171 offset:2048
	ds_read_b128 v[198:201], v171 offset:3072
	ds_read_b128 v[202:205], v171 offset:4096
	ds_read_b128 v[206:209], v171 offset:5120
	ds_read_b128 v[210:213], v171 offset:6144
	ds_read_b128 v[214:217], v171 offset:7168
	global_load_lds_dwordx4 v[164:165], off
	v_lshl_add_u64 v[164:165], s[20:21], 0, v[154:155]
	s_mov_b32 m0, s79
	s_nop 0
	global_load_lds_dwordx4 v[164:165], off
	s_waitcnt vmcnt(8)
	s_waitcnt lgkmcnt(0)
	s_barrier
	s_waitcnt lgkmcnt(0)
	v_mfma_f32_16x16x32_bf16 v[128:131], v[124:127], v[186:189], v[128:131]
	v_mfma_f32_16x16x32_bf16 v[120:123], v[136:139], v[186:189], v[120:123]
	v_mfma_f32_16x16x32_bf16 v[108:111], v[124:127], v[194:197], v[108:111]
	v_mfma_f32_16x16x32_bf16 v[104:107], v[136:139], v[194:197], v[104:107]
	v_mfma_f32_16x16x32_bf16 v[92:95], v[124:127], v[202:205], v[92:95]
	v_mfma_f32_16x16x32_bf16 v[88:91], v[136:139], v[202:205], v[88:91]
	v_mfma_f32_16x16x32_bf16 v[76:79], v[124:127], v[210:213], v[76:79]
	v_mfma_f32_16x16x32_bf16 v[72:75], v[136:139], v[210:213], v[72:75]
	v_mfma_f32_16x16x32_bf16 v[128:131], v[132:135], v[190:193], v[128:131]
	v_mfma_f32_16x16x32_bf16 v[120:123], v[140:143], v[190:193], v[120:123]
	v_mfma_f32_16x16x32_bf16 v[108:111], v[132:135], v[198:201], v[108:111]
	v_mfma_f32_16x16x32_bf16 v[104:107], v[140:143], v[198:201], v[104:107]
	v_mfma_f32_16x16x32_bf16 v[92:95], v[132:135], v[206:209], v[92:95]
	v_mfma_f32_16x16x32_bf16 v[88:91], v[140:143], v[206:209], v[88:91]
	v_mfma_f32_16x16x32_bf16 v[76:79], v[132:135], v[214:217], v[76:79]
	v_mfma_f32_16x16x32_bf16 v[72:75], v[140:143], v[214:217], v[72:75]
	v_mfma_f32_16x16x32_bf16 v[116:119], v[144:147], v[186:189], v[116:119]
	v_mfma_f32_16x16x32_bf16 v[112:115], v[160:163], v[186:189], v[112:115]
	v_mfma_f32_16x16x32_bf16 v[100:103], v[144:147], v[194:197], v[100:103]
	v_mfma_f32_16x16x32_bf16 v[96:99], v[160:163], v[194:197], v[96:99]
	v_mfma_f32_16x16x32_bf16 v[84:87], v[144:147], v[202:205], v[84:87]
	v_mfma_f32_16x16x32_bf16 v[80:83], v[160:163], v[202:205], v[80:83]
	v_mfma_f32_16x16x32_bf16 v[68:71], v[144:147], v[210:213], v[68:71]
	v_mfma_f32_16x16x32_bf16 v[64:67], v[160:163], v[210:213], v[64:67]
	v_mfma_f32_16x16x32_bf16 v[116:119], v[156:159], v[190:193], v[116:119]
	v_mfma_f32_16x16x32_bf16 v[112:115], v[182:185], v[190:193], v[112:115]
	v_mfma_f32_16x16x32_bf16 v[100:103], v[156:159], v[198:201], v[100:103]
	v_mfma_f32_16x16x32_bf16 v[96:99], v[182:185], v[198:201], v[96:99]
	v_mfma_f32_16x16x32_bf16 v[84:87], v[156:159], v[206:209], v[84:87]
	v_mfma_f32_16x16x32_bf16 v[80:83], v[182:185], v[206:209], v[80:83]
	v_mfma_f32_16x16x32_bf16 v[68:71], v[156:159], v[214:217], v[68:71]
	v_mfma_f32_16x16x32_bf16 v[64:67], v[182:185], v[214:217], v[64:67]
	s_barrier
; #define PG8_STAGE(bufoff, gbase, voff) do { _Pragma("unroll") for (int _i = 0; _i < 2; ++_i) \
;         __builtin_amdgcn_global_load_lds((const unsigned*)((const char*)(gbase) + (voff)[_i]), (LAS unsigned*)(lds + (bufoff) + ldsw + _i * 8192), 16, 0, 0); } while (0)
; #define PG8_LDA(dst, b, h) do { _Pragma("unroll") for (int m = 0; m < 4; ++m) _Pragma("unroll") for (int k = 0; k < 2; ++k) dst[m][k] = *(const LAS bf16x8*)(lds + PG8_SA(b, h) + aoff + m * 2048 + k * 1024); } while (0)
; #define PG8_LDB(dst, b, h) do { _Pragma("unroll") for (int n = 0; n < 2; ++n) _Pragma("unroll") for (int k = 0; k < 2; ++k) dst[n][k] = *(const LAS bf16x8*)(lds + PG8_SB(b, h) + boff + n * 2048 + k * 1024); } while (0)
; #define PG8_MMA(ai, bj, At, Bt) do { __builtin_amdgcn_s_setprio(1); _Pragma("unroll") for (int m = 0; m < 4; ++m) _Pragma("unroll") for (int n = 0; n < 2; ++n) _Pragma("unroll") for (int k = 0; k < 2; ++k) \
;         acc[ai][bj][m][n] = __builtin_amdgcn_mfma_f32_16x16x32_bf16(Bt[n][k], At[m][k], acc[ai][bj][m][n], 0, 0, 0); __builtin_amdgcn_s_setprio(0); } while (0)
; #define PG8_WAIT_V(n) asm volatile("s_waitcnt vmcnt(" #n ")" ::: "memory")
; #define PG8_WAIT_L(n) asm volatile("s_waitcnt lgkmcnt(" #n ")" ::: "memory")
; #define PG8_BAR __builtin_amdgcn_s_barrier()
; #define PG8_SCHED __builtin_amdgcn_sched_barrier(0)
; template <class Sched, class Epi, bool ALIGN_EPI, bool SP2>
; __device__ __forceinline__ void gemm_phase(LAS unsigned char* lds, const int K, const int lda, const int ldb, const Sched& S, const Epi& E) {
;     ...
;             PG8_LDA(At, 0, 1); PG8_STAGE(PG8_SB(0, 0), b2, voffB); PG8_STAGE(PG8_SB(0, 1), b2 + hstepB, voffB); PG8_STAGE(PG8_SA(0, 0), a2, voffA);
;             PG8_WAIT_V(8); PG8_WAIT_L(0); PG8_BAR; PG8_MMA(1, 0, At, B0); PG8_MMA(1, 1, At, B1); PG8_BAR; PG8_SCHED;
;             PG8_LDB(B0, 1, 0); PG8_LDB(B1, 1, 1); PG8_SCHED; PG8_LDA(At, 1, 0); PG8_STAGE(PG8_SA(0, 1), a2 + hstepA, voffA);
	s_mov_b32 m0, s84
	v_lshl_add_u64 v[164:165], s[24:25], 0, v[148:149]
	ds_read_b128 v[186:189], v171 offset:16384
	ds_read_b128 v[190:193], v171 offset:17408
	ds_read_b128 v[194:197], v171 offset:18432
	ds_read_b128 v[198:201], v171 offset:19456
	ds_read_b128 v[202:205], v171 offset:20480
	ds_read_b128 v[206:209], v171 offset:21504
	ds_read_b128 v[210:213], v171 offset:22528
	ds_read_b128 v[214:217], v171 offset:23552
	global_load_lds_dwordx4 v[164:165], off
	s_add_i32 m0, s84, 0x2000
	s_add_u32 s20, s24, 0x160000
	v_lshl_add_u64 v[174:175], s[24:25], 0, v[150:151]
	s_addc_u32 s21, s25, 0
	s_add_i32 s96, s53, s13
	global_load_lds_dwordx4 v[174:175], off
	v_lshl_add_u64 v[218:219], s[20:21], 0, v[148:149]
	s_mov_b32 m0, s96
	v_lshl_add_u64 v[220:221], s[26:27], 0, v[150:151]
	global_load_lds_dwordx4 v[218:219], off
	v_lshl_add_u64 v[218:219], s[20:21], 0, v[150:151]
	s_add_i32 m0, s96, 0x2000
	s_nop 0
	global_load_lds_dwordx4 v[218:219], off
	v_lshl_add_u64 v[218:219], s[26:27], 0, v[148:149]
	s_mov_b32 m0, s28
	s_nop 0
	global_load_lds_dwordx4 v[218:219], off
	s_mov_b32 m0, s29
	s_nop 0
	global_load_lds_dwordx4 v[220:221], off
	s_waitcnt vmcnt(8)
	s_waitcnt lgkmcnt(0)
	s_barrier
	s_waitcnt lgkmcnt(0)
	v_mfma_f32_16x16x32_bf16 v[60:63], v[124:127], v[186:189], v[60:63]
	v_mfma_f32_16x16x32_bf16 v[56:59], v[136:139], v[186:189], v[56:59]
	v_mfma_f32_16x16x32_bf16 v[44:47], v[124:127], v[194:197], v[44:47]
	v_mfma_f32_16x16x32_bf16 v[40:43], v[136:139], v[194:197], v[40:43]
	v_mfma_f32_16x16x32_bf16 v[28:31], v[124:127], v[202:205], v[28:31]
	v_mfma_f32_16x16x32_bf16 v[24:27], v[136:139], v[202:205], v[24:27]
	v_mfma_f32_16x16x32_bf16 v[12:15], v[124:127], v[210:213], v[12:15]
	v_mfma_f32_16x16x32_bf16 v[8:11], v[136:139], v[210:213], v[8:11]
	v_mfma_f32_16x16x32_bf16 v[60:63], v[132:135], v[190:193], v[60:63]
	v_mfma_f32_16x16x32_bf16 v[56:59], v[140:143], v[190:193], v[56:59]
	v_mfma_f32_16x16x32_bf16 v[44:47], v[132:135], v[198:201], v[44:47]
	v_mfma_f32_16x16x32_bf16 v[40:43], v[140:143], v[198:201], v[40:43]
	v_mfma_f32_16x16x32_bf16 v[28:31], v[132:135], v[206:209], v[28:31]
	v_mfma_f32_16x16x32_bf16 v[24:27], v[140:143], v[206:209], v[24:27]
	v_mfma_f32_16x16x32_bf16 v[12:15], v[132:135], v[214:217], v[12:15]
	v_mfma_f32_16x16x32_bf16 v[8:11], v[140:143], v[214:217], v[8:11]
	v_mfma_f32_16x16x32_bf16 v[52:55], v[144:147], v[186:189], v[52:55]
	v_mfma_f32_16x16x32_bf16 v[48:51], v[160:163], v[186:189], v[48:51]
	v_mfma_f32_16x16x32_bf16 v[36:39], v[144:147], v[194:197], v[36:39]
	v_mfma_f32_16x16x32_bf16 v[32:35], v[160:163], v[194:197], v[32:35]
	v_mfma_f32_16x16x32_bf16 v[20:23], v[144:147], v[202:205], v[20:23]
	v_mfma_f32_16x16x32_bf16 v[16:19], v[160:163], v[202:205], v[16:19]
	v_mfma_f32_16x16x32_bf16 v[4:7], v[144:147], v[210:213], v[4:7]
	v_mfma_f32_16x16x32_bf16 v[0:3], v[160:163], v[210:213], v[0:3]
	v_mfma_f32_16x16x32_bf16 v[52:55], v[156:159], v[190:193], v[52:55]
	v_mfma_f32_16x16x32_bf16 v[48:51], v[182:185], v[190:193], v[48:51]
	v_mfma_f32_16x16x32_bf16 v[36:39], v[156:159], v[198:201], v[36:39]
	v_mfma_f32_16x16x32_bf16 v[32:35], v[182:185], v[198:201], v[32:35]
	v_mfma_f32_16x16x32_bf16 v[20:23], v[156:159], v[206:209], v[20:23]
	v_mfma_f32_16x16x32_bf16 v[16:19], v[182:185], v[206:209], v[16:19]
	v_mfma_f32_16x16x32_bf16 v[4:7], v[156:159], v[214:217], v[4:7]
	v_mfma_f32_16x16x32_bf16 v[0:3], v[182:185], v[214:217], v[0:3]
	s_barrier
	s_add_i32 s96, 0, 0x18000
	s_add_i32 s97, 0, 0x1c000
	v_add_u32_e32 v140, s96, v167
	v_add_u32_e32 v173, s97, v167
	ds_read_b128 v[124:127], v140
	ds_read_b128 v[132:135], v140 offset:1024
	ds_read_b128 v[136:139], v140 offset:2048
	ds_read_b128 v[140:143], v140 offset:3072
	ds_read_b128 v[144:147], v173
	ds_read_b128 v[156:159], v173 offset:1024
	ds_read_b128 v[160:163], v173 offset:2048
	ds_read_b128 v[182:185], v173 offset:3072
	s_add_u32 s20, s26, 0x160000
	s_addc_u32 s21, s27, 0
	s_mov_b32 m0, s33
	v_lshl_add_u64 v[222:223], s[20:21], 0, v[148:149]
	ds_read_b128 v[186:189], v171 offset:32768
	ds_read_b128 v[190:193], v171 offset:33792
	ds_read_b128 v[194:197], v171 offset:34816
	ds_read_b128 v[198:201], v171 offset:35840
	ds_read_b128 v[202:205], v171 offset:36864
	ds_read_b128 v[206:209], v171 offset:37888
	ds_read_b128 v[210:213], v171 offset:38912
	ds_read_b128 v[214:217], v171 offset:39936
	global_load_lds_dwordx4 v[222:223], off
	v_lshl_add_u64 v[222:223], s[20:21], 0, v[150:151]
	s_mov_b32 m0, s35
	s_nop 0
	global_load_lds_dwordx4 v[222:223], off
	s_waitcnt vmcnt(8)
	s_waitcnt lgkmcnt(0)
	s_barrier
; #define PG8_STAGE(bufoff, gbase, voff) do { _Pragma("unroll") for (int _i = 0; _i < 2; ++_i) \
;         __builtin_amdgcn_global_load_lds((const unsigned*)((const char*)(gbase) + (voff)[_i]), (LAS unsigned*)(lds + (bufoff) + ldsw + _i * 8192), 16, 0, 0); } while (0)
; #define PG8_LDA(dst, b, h) do { _Pragma("unroll") for (int m = 0; m < 4; ++m) _Pragma("unroll") for (int k = 0; k < 2; ++k) dst[m][k] = *(const LAS bf16x8*)(lds + PG8_SA(b, h) + aoff + m * 2048 + k * 1024); } while (0)
; #define PG8_MMA(ai, bj, At, Bt) do { __builtin_amdgcn_s_setprio(1); _Pragma("unroll") for (int m = 0; m < 4; ++m) _Pragma("unroll") for (int n = 0; n < 2; ++n) _Pragma("unroll") for (int k = 0; k < 2; ++k) \
;         acc[ai][bj][m][n] = __builtin_amdgcn_mfma_f32_16x16x32_bf16(Bt[n][k], At[m][k], acc[ai][bj][m][n], 0, 0, 0); __builtin_amdgcn_s_setprio(0); } while (0)
; #define PG8_WAIT_V(n) asm volatile("s_waitcnt vmcnt(" #n ")" ::: "memory")
; #define PG8_WAIT_L(n) asm volatile("s_waitcnt lgkmcnt(" #n ")" ::: "memory")
; #define PG8_BAR __builtin_amdgcn_s_barrier()
; #define PG8_SCHED __builtin_amdgcn_sched_barrier(0)
; template <class Sched, class Epi, bool ALIGN_EPI, bool SP2>
; __device__ __forceinline__ void gemm_phase(LAS unsigned char* lds, const int K, const int lda, const int ldb, const Sched& S, const Epi& E) {
;     ...
;         for (int t = 0; t < nt; t += 2) {
;             const bool last = (t == nt - 2);
;             const char* a1 = cA + (size_t)(t + 1) * kstep;
;             const char* a2 = last ? nA : cA + (size_t)(t + 2) * kstep; const char* b2 = last ? nB : cB + (size_t)(t + 2) * kstep;
;     ...
;             PG8_WAIT_V(8); PG8_WAIT_L(0); PG8_BAR; PG8_MMA(0, 0, At, B0); PG8_MMA(0, 1, At, B1); PG8_BAR; PG8_SCHED;
;             PG8_LDA(At, 1, 1); PG8_STAGE(PG8_SB(1, 0), b3, voffB); PG8_STAGE(PG8_SB(1, 1), b3 + hstepB, voffB); PG8_STAGE(PG8_SA(1, 0), a3, voffA);
;             PG8_WAIT_V(8); PG8_WAIT_L(0); PG8_BAR; PG8_MMA(1, 0, At, B0); PG8_MMA(1, 1, At, B1); PG8_BAR; PG8_SCHED;
	s_waitcnt lgkmcnt(0)
	v_mfma_f32_16x16x32_bf16 v[128:131], v[124:127], v[186:189], v[128:131]
	v_mfma_f32_16x16x32_bf16 v[120:123], v[136:139], v[186:189], v[120:123]
	v_mfma_f32_16x16x32_bf16 v[108:111], v[124:127], v[194:197], v[108:111]
	v_mfma_f32_16x16x32_bf16 v[104:107], v[136:139], v[194:197], v[104:107]
	v_mfma_f32_16x16x32_bf16 v[92:95], v[124:127], v[202:205], v[92:95]
	v_mfma_f32_16x16x32_bf16 v[88:91], v[136:139], v[202:205], v[88:91]
	v_mfma_f32_16x16x32_bf16 v[76:79], v[124:127], v[210:213], v[76:79]
	v_mfma_f32_16x16x32_bf16 v[72:75], v[136:139], v[210:213], v[72:75]
	v_mfma_f32_16x16x32_bf16 v[128:131], v[132:135], v[190:193], v[128:131]
	v_mfma_f32_16x16x32_bf16 v[120:123], v[140:143], v[190:193], v[120:123]
	v_mfma_f32_16x16x32_bf16 v[108:111], v[132:135], v[198:201], v[108:111]
	v_mfma_f32_16x16x32_bf16 v[104:107], v[140:143], v[198:201], v[104:107]
	v_mfma_f32_16x16x32_bf16 v[92:95], v[132:135], v[206:209], v[92:95]
	v_mfma_f32_16x16x32_bf16 v[88:91], v[140:143], v[206:209], v[88:91]
	v_mfma_f32_16x16x32_bf16 v[76:79], v[132:135], v[214:217], v[76:79]
	v_mfma_f32_16x16x32_bf16 v[72:75], v[140:143], v[214:217], v[72:75]
	v_mfma_f32_16x16x32_bf16 v[116:119], v[144:147], v[186:189], v[116:119]
	v_mfma_f32_16x16x32_bf16 v[112:115], v[160:163], v[186:189], v[112:115]
	v_mfma_f32_16x16x32_bf16 v[100:103], v[144:147], v[194:197], v[100:103]
	v_mfma_f32_16x16x32_bf16 v[96:99], v[160:163], v[194:197], v[96:99]
	v_mfma_f32_16x16x32_bf16 v[84:87], v[144:147], v[202:205], v[84:87]
	v_mfma_f32_16x16x32_bf16 v[80:83], v[160:163], v[202:205], v[80:83]
	v_mfma_f32_16x16x32_bf16 v[68:71], v[144:147], v[210:213], v[68:71]
	v_mfma_f32_16x16x32_bf16 v[64:67], v[160:163], v[210:213], v[64:67]
	v_mfma_f32_16x16x32_bf16 v[116:119], v[156:159], v[190:193], v[116:119]
	v_mfma_f32_16x16x32_bf16 v[112:115], v[182:185], v[190:193], v[112:115]
	v_mfma_f32_16x16x32_bf16 v[100:103], v[156:159], v[198:201], v[100:103]
	v_mfma_f32_16x16x32_bf16 v[96:99], v[182:185], v[198:201], v[96:99]
	v_mfma_f32_16x16x32_bf16 v[84:87], v[156:159], v[206:209], v[84:87]
	v_mfma_f32_16x16x32_bf16 v[80:83], v[182:185], v[206:209], v[80:83]
	v_mfma_f32_16x16x32_bf16 v[68:71], v[156:159], v[214:217], v[68:71]
	v_mfma_f32_16x16x32_bf16 v[64:67], v[182:185], v[214:217], v[64:67]
	s_barrier
	s_add_i32 s20, s96, s13
	v_lshl_add_u64 v[164:165], v[164:165], 0, s[6:7]
	s_mov_b32 m0, s20
	ds_read_b128 v[186:189], v171 offset:49152
	ds_read_b128 v[190:193], v171 offset:50176
	ds_read_b128 v[194:197], v171 offset:51200
	ds_read_b128 v[198:201], v171 offset:52224
	ds_read_b128 v[202:205], v171 offset:53248
	ds_read_b128 v[206:209], v171 offset:54272
	ds_read_b128 v[210:213], v171 offset:55296
	ds_read_b128 v[214:217], v171 offset:56320
	global_load_lds_dwordx4 v[164:165], off
	s_add_i32 m0, s20, 0x2000
	s_add_u32 s20, s24, 0x160080
	v_lshl_add_u64 v[164:165], v[174:175], 0, s[6:7]
	s_addc_u32 s21, s25, 0
	s_add_i32 s24, s97, s13
	global_load_lds_dwordx4 v[164:165], off
	v_lshl_add_u64 v[164:165], s[20:21], 0, v[148:149]
	s_mov_b32 m0, s24
	s_nop 0
	global_load_lds_dwordx4 v[164:165], off
	v_lshl_add_u64 v[164:165], s[20:21], 0, v[150:151]
	s_add_i32 m0, s24, 0x2000
	s_nop 0
	global_load_lds_dwordx4 v[164:165], off
	v_lshl_add_u64 v[164:165], v[218:219], 0, s[6:7]
	s_mov_b32 m0, s51
	s_nop 0
	global_load_lds_dwordx4 v[164:165], off
	v_lshl_add_u64 v[164:165], v[220:221], 0, s[6:7]
	s_mov_b32 m0, s52
	s_nop 0
	global_load_lds_dwordx4 v[164:165], off
	s_waitcnt vmcnt(8)
	s_waitcnt lgkmcnt(0)
	s_barrier
	s_waitcnt lgkmcnt(0)
	v_mfma_f32_16x16x32_bf16 v[60:63], v[124:127], v[186:189], v[60:63]
	v_mfma_f32_16x16x32_bf16 v[56:59], v[136:139], v[186:189], v[56:59]
	v_mfma_f32_16x16x32_bf16 v[44:47], v[124:127], v[194:197], v[44:47]
	v_mfma_f32_16x16x32_bf16 v[40:43], v[136:139], v[194:197], v[40:43]
	v_mfma_f32_16x16x32_bf16 v[28:31], v[124:127], v[202:205], v[28:31]
	v_mfma_f32_16x16x32_bf16 v[24:27], v[136:139], v[202:205], v[24:27]
	v_mfma_f32_16x16x32_bf16 v[12:15], v[124:127], v[210:213], v[12:15]
	v_mfma_f32_16x16x32_bf16 v[8:11], v[136:139], v[210:213], v[8:11]
	v_mfma_f32_16x16x32_bf16 v[60:63], v[132:135], v[190:193], v[60:63]
	v_mfma_f32_16x16x32_bf16 v[56:59], v[140:143], v[190:193], v[56:59]
	v_mfma_f32_16x16x32_bf16 v[44:47], v[132:135], v[198:201], v[44:47]
	v_mfma_f32_16x16x32_bf16 v[40:43], v[140:143], v[198:201], v[40:43]
	v_mfma_f32_16x16x32_bf16 v[28:31], v[132:135], v[206:209], v[28:31]
	v_mfma_f32_16x16x32_bf16 v[24:27], v[140:143], v[206:209], v[24:27]
	v_mfma_f32_16x16x32_bf16 v[12:15], v[132:135], v[214:217], v[12:15]
	v_mfma_f32_16x16x32_bf16 v[8:11], v[140:143], v[214:217], v[8:11]
	v_mfma_f32_16x16x32_bf16 v[52:55], v[144:147], v[186:189], v[52:55]
	v_mfma_f32_16x16x32_bf16 v[48:51], v[160:163], v[186:189], v[48:51]
	v_mfma_f32_16x16x32_bf16 v[36:39], v[144:147], v[194:197], v[36:39]
	v_mfma_f32_16x16x32_bf16 v[32:35], v[160:163], v[194:197], v[32:35]
	v_mfma_f32_16x16x32_bf16 v[20:23], v[144:147], v[202:205], v[20:23]
	v_mfma_f32_16x16x32_bf16 v[16:19], v[160:163], v[202:205], v[16:19]
	v_mfma_f32_16x16x32_bf16 v[4:7], v[144:147], v[210:213], v[4:7]
	v_mfma_f32_16x16x32_bf16 v[0:3], v[160:163], v[210:213], v[0:3]
	v_mfma_f32_16x16x32_bf16 v[52:55], v[156:159], v[190:193], v[52:55]
	v_mfma_f32_16x16x32_bf16 v[48:51], v[182:185], v[190:193], v[48:51]
	v_mfma_f32_16x16x32_bf16 v[36:39], v[156:159], v[198:201], v[36:39]
	v_mfma_f32_16x16x32_bf16 v[32:35], v[182:185], v[198:201], v[32:35]
	v_mfma_f32_16x16x32_bf16 v[20:23], v[156:159], v[206:209], v[20:23]
	v_mfma_f32_16x16x32_bf16 v[16:19], v[182:185], v[206:209], v[16:19]
	v_mfma_f32_16x16x32_bf16 v[4:7], v[156:159], v[214:217], v[4:7]
	v_mfma_f32_16x16x32_bf16 v[0:3], v[182:185], v[214:217], v[0:3]
	s_barrier
	s_add_i32 s91, s91, 2
	s_add_u32 s89, s89, 0x100
	s_addc_u32 s90, s90, 0
	s_cmpk_gt_u32 s91, 0x55
	s_mov_b64 s[20:21], s[22:23]
	s_cbranch_scc0 .LBB0_243
	s_setprio 0
	s_and_b64 vcc, exec, s[10:11]
	s_cbranch_vccz .LBB0_246
	s_barrier

; #define PG8_STAGE(bufoff, gbase, voff) do { _Pragma("unroll") for (int _i = 0; _i < 2; ++_i) \
;         __builtin_amdgcn_global_load_lds((const unsigned*)((const char*)(gbase) + (voff)[_i]), (LAS unsigned*)(lds + (bufoff) + ldsw + _i * 8192), 16, 0, 0); } while (0)
; #define PG8_LDA(dst, b, h) do { _Pragma("unroll") for (int m = 0; m < 4; ++m) _Pragma("unroll") for (int k = 0; k < 2; ++k) dst[m][k] = *(const LAS bf16x8*)(lds + PG8_SA(b, h) + aoff + m * 2048 + k * 1024); } while (0)
; #define PG8_LDB(dst, b, h) do { _Pragma("unroll") for (int n = 0; n < 2; ++n) _Pragma("unroll") for (int k = 0; k < 2; ++k) dst[n][k] = *(const LAS bf16x8*)(lds + PG8_SB(b, h) + boff + n * 2048 + k * 1024); } while (0)
; #define PG8_MMA(ai, bj, At, Bt) do { __builtin_amdgcn_s_setprio(1); _Pragma("unroll") for (int m = 0; m < 4; ++m) _Pragma("unroll") for (int n = 0; n < 2; ++n) _Pragma("unroll") for (int k = 0; k < 2; ++k) \
;         acc[ai][bj][m][n] = __builtin_amdgcn_mfma_f32_16x16x32_bf16(Bt[n][k], At[m][k], acc[ai][bj][m][n], 0, 0, 0); __builtin_amdgcn_s_setprio(0); } while (0)
; #define PG8_WAIT_V(n) asm volatile("s_waitcnt vmcnt(" #n ")" ::: "memory")
; #define PG8_WAIT_L(n) asm volatile("s_waitcnt lgkmcnt(" #n ")" ::: "memory")
; template <class Sched, class Epi, bool ALIGN_EPI, bool SP2>
; __device__ __forceinline__ void gemm_phase(LAS unsigned char* lds, const int K, const int lda, const int ldb, const Sched& S, const Epi& E) {
;     ...
;             const bool last = (t == nt - 2);
;             const char* a1 = cA + (size_t)(t + 1) * kstep;
;             const char* a2 = last ? nA : cA + (size_t)(t + 2) * kstep; const char* b2 = last ? nB : cB + (size_t)(t + 2) * kstep;
;             const char* a3 = a2 + kstep; const char* b3 = b2 + kstep;
;             if constexpr (SP2) {
;             PG8_LDB(B0, 0, 0); PG8_LDB(B1, 0, 1); PG8_SCHED; PG8_LDA(At, 0, 0); PG8_STAGE(PG8_SA(1, 1), a1 + hstepA, voffA);
;             PG8_WAIT_V(8); PG8_WAIT_L(0); PG8_BAR; PG8_MMA(0, 0, At, B0); PG8_MMA(0, 1, At, B1); PG8_BAR; PG8_SCHED;
;     ...
; #pragma unroll
;         for (int a = 0; a < 2; ++a)
; #pragma unroll
;             for (int b = 0; b < 2; ++b)
; #pragma unroll
;                 for (int m = 0; m < 4; ++m)
; #pragma unroll
;                     for (int n = 0; n < 2; ++n) acc[a][b][m][n] = (f32x4){0.f, 0.f, 0.f, 0.f};
;         }
;         cur = nxt; cA = nA; cB = nB; ++ui;
.LBB0_352:
	s_and_b64 s[6:7], s[24:25], exec
	s_cselect_b32 s1, s19, s27
	s_cselect_b32 s4, s18, s26
	s_cselect_b32 s21, s23, s29
	s_cselect_b32 vcc_lo, s22, s28
	s_add_u32 s26, s26, 0x80080
	s_addc_u32 s27, s27, 0
	s_add_u32 vcc_hi, s28, 0x100
	v_mov_b32_e32 v0, 0
	s_addc_u32 s6, s29, 0
	s_mov_b32 s7, -2
	v_mov_b32_e32 v1, v0
	v_mov_b32_e32 v2, v0
	v_mov_b32_e32 v3, v0
	v_mov_b32_e32 v4, v0
	v_mov_b32_e32 v5, v0
	v_mov_b32_e32 v6, v0
	v_mov_b32_e32 v7, v0
	v_mov_b32_e32 v16, v0
	v_mov_b32_e32 v17, v0
	v_mov_b32_e32 v18, v0
	v_mov_b32_e32 v19, v0
	v_mov_b32_e32 v20, v0
	v_mov_b32_e32 v21, v0
	v_mov_b32_e32 v22, v0
	v_mov_b32_e32 v23, v0
	v_mov_b32_e32 v40, v0
	v_mov_b32_e32 v41, v0
	v_mov_b32_e32 v42, v0
	v_mov_b32_e32 v43, v0
	v_mov_b32_e32 v44, v0
	v_mov_b32_e32 v45, v0
	v_mov_b32_e32 v46, v0
	v_mov_b32_e32 v47, v0
	v_mov_b32_e32 v96, v0
	v_mov_b32_e32 v97, v0
	v_mov_b32_e32 v98, v0
	v_mov_b32_e32 v99, v0
	v_mov_b32_e32 v100, v0
	v_mov_b32_e32 v101, v0
	v_mov_b32_e32 v102, v0
	v_mov_b32_e32 v103, v0
	v_mov_b32_e32 v8, v0
	v_mov_b32_e32 v9, v0
	v_mov_b32_e32 v10, v0
	v_mov_b32_e32 v11, v0
	v_mov_b32_e32 v12, v0
	v_mov_b32_e32 v13, v0
	v_mov_b32_e32 v14, v0
	v_mov_b32_e32 v15, v0
	v_mov_b32_e32 v24, v0
	v_mov_b32_e32 v25, v0
	v_mov_b32_e32 v26, v0
	v_mov_b32_e32 v27, v0
	v_mov_b32_e32 v28, v0
	v_mov_b32_e32 v29, v0
	v_mov_b32_e32 v30, v0
	v_mov_b32_e32 v31, v0
	v_mov_b32_e32 v72, v0
	v_mov_b32_e32 v73, v0
	v_mov_b32_e32 v74, v0
	v_mov_b32_e32 v75, v0
	v_mov_b32_e32 v84, v0
	v_mov_b32_e32 v85, v0
	v_mov_b32_e32 v86, v0
	v_mov_b32_e32 v87, v0
	v_mov_b32_e32 v104, v0
	v_mov_b32_e32 v105, v0
	v_mov_b32_e32 v106, v0
	v_mov_b32_e32 v107, v0
	v_mov_b32_e32 v108, v0
	v_mov_b32_e32 v109, v0
	v_mov_b32_e32 v110, v0
	v_mov_b32_e32 v111, v0
	v_mov_b32_e32 v112, v0
	v_mov_b32_e32 v113, v0
	v_mov_b32_e32 v114, v0
	v_mov_b32_e32 v115, v0
	v_mov_b32_e32 v116, v0
	v_mov_b32_e32 v117, v0
	v_mov_b32_e32 v118, v0
	v_mov_b32_e32 v119, v0
	v_mov_b32_e32 v128, v0
	v_mov_b32_e32 v129, v0
	v_mov_b32_e32 v130, v0
	v_mov_b32_e32 v131, v0
	v_mov_b32_e32 v132, v0
	v_mov_b32_e32 v133, v0
	v_mov_b32_e32 v134, v0
	v_mov_b32_e32 v135, v0
	v_mov_b32_e32 v144, v0
	v_mov_b32_e32 v145, v0
	v_mov_b32_e32 v146, v0
	v_mov_b32_e32 v147, v0
	v_mov_b32_e32 v148, v0
	v_mov_b32_e32 v149, v0
	v_mov_b32_e32 v150, v0
	v_mov_b32_e32 v151, v0
	v_mov_b32_e32 v160, v0
	v_mov_b32_e32 v161, v0
	v_mov_b32_e32 v162, v0
	v_mov_b32_e32 v163, v0
	v_mov_b32_e32 v164, v0
	v_mov_b32_e32 v165, v0
	v_mov_b32_e32 v166, v0
	v_mov_b32_e32 v167, v0
	v_mov_b32_e32 v120, v0
	v_mov_b32_e32 v121, v0
	v_mov_b32_e32 v122, v0
	v_mov_b32_e32 v123, v0
	v_mov_b32_e32 v124, v0
	v_mov_b32_e32 v125, v0
	v_mov_b32_e32 v126, v0
	v_mov_b32_e32 v127, v0
	v_mov_b32_e32 v136, v0
	v_mov_b32_e32 v137, v0
	v_mov_b32_e32 v138, v0
	v_mov_b32_e32 v139, v0
	v_mov_b32_e32 v140, v0
	v_mov_b32_e32 v141, v0
	v_mov_b32_e32 v142, v0
	v_mov_b32_e32 v143, v0
	v_mov_b32_e32 v152, v0
	v_mov_b32_e32 v153, v0
	v_mov_b32_e32 v154, v0
	v_mov_b32_e32 v155, v0
	v_mov_b32_e32 v156, v0
	v_mov_b32_e32 v157, v0
	v_mov_b32_e32 v158, v0
	v_mov_b32_e32 v159, v0
	v_mov_b32_e32 v168, v0
	v_mov_b32_e32 v169, v0
	v_mov_b32_e32 v170, v0
	v_mov_b32_e32 v171, v0
	v_mov_b32_e32 v172, v0
	v_mov_b32_e32 v173, v0
	v_mov_b32_e32 v174, v0
	v_mov_b32_e32 v175, v0
	v_readlane_b32 s98, v255, 13
	s_nop 4
	s_cmp_lt_u32 s98, 4
	s_cbranch_scc1 .Lprio_skip_353
	s_setprio 1
.Lprio_skip_353:
.LBB0_353:
	s_waitcnt lgkmcnt(0)
	ds_read_b128 v[32:35], v211
	ds_read_b128 v[36:39], v211 offset:1024
	ds_read_b128 v[48:51], v211 offset:2048
	ds_read_b128 v[52:55], v211 offset:3072
	ds_read_b128 v[56:59], v212
	ds_read_b128 v[60:63], v212 offset:1024
	ds_read_b128 v[64:67], v212 offset:2048
	ds_read_b128 v[68:71], v212 offset:3072
	s_add_u32 s8, s26, 0xfff80080
	s_addc_u32 s9, s27, -1
	s_cmp_eq_u32 s7, 28
	s_cselect_b32 s37, s1, s9
	s_cselect_b32 s36, s4, s8
	s_cselect_b32 s29, s21, s6
	s_cselect_b32 s28, vcc_lo, vcc_hi
	v_lshl_add_u64 v[208:209], s[26:27], 0, v[192:193]
	s_add_i32 m0, s89, 0xc000
	ds_read_b128 v[76:79], v213
	ds_read_b128 v[80:83], v213 offset:1024
	ds_read_b128 v[88:91], v213 offset:2048
	ds_read_b128 v[92:95], v213 offset:3072
	ds_read_b128 v[196:199], v213 offset:4096
	ds_read_b128 v[200:203], v213 offset:5120
	ds_read_b128 v[204:207], v213 offset:6144
	ds_read_b128 v[216:219], v213 offset:7168
	global_load_lds_dwordx4 v[208:209], off
	v_lshl_add_u64 v[208:209], s[26:27], 0, v[194:195]
	s_add_i32 m0, s89, 0xe000
	s_nop 0
	global_load_lds_dwordx4 v[208:209], off
	s_waitcnt vmcnt(8)
	s_waitcnt lgkmcnt(0)
	s_barrier
; #define PG8_STAGE(bufoff, gbase, voff) do { _Pragma("unroll") for (int _i = 0; _i < 2; ++_i) \
;         __builtin_amdgcn_global_load_lds((const unsigned*)((const char*)(gbase) + (voff)[_i]), (LAS unsigned*)(lds + (bufoff) + ldsw + _i * 8192), 16, 0, 0); } while (0)
; #define PG8_LDA(dst, b, h) do { _Pragma("unroll") for (int m = 0; m < 4; ++m) _Pragma("unroll") for (int k = 0; k < 2; ++k) dst[m][k] = *(const LAS bf16x8*)(lds + PG8_SA(b, h) + aoff + m * 2048 + k * 1024); } while (0)
; #define PG8_MMA(ai, bj, At, Bt) do { __builtin_amdgcn_s_setprio(1); _Pragma("unroll") for (int m = 0; m < 4; ++m) _Pragma("unroll") for (int n = 0; n < 2; ++n) _Pragma("unroll") for (int k = 0; k < 2; ++k) \
;         acc[ai][bj][m][n] = __builtin_amdgcn_mfma_f32_16x16x32_bf16(Bt[n][k], At[m][k], acc[ai][bj][m][n], 0, 0, 0); __builtin_amdgcn_s_setprio(0); } while (0)
; #define PG8_WAIT_V(n) asm volatile("s_waitcnt vmcnt(" #n ")" ::: "memory")
; #define PG8_WAIT_L(n) asm volatile("s_waitcnt lgkmcnt(" #n ")" ::: "memory")
; #define PG8_BAR __builtin_amdgcn_s_barrier()
; #define PG8_SCHED __builtin_amdgcn_sched_barrier(0)
; template <class Sched, class Epi, bool ALIGN_EPI, bool SP2>
; __device__ __forceinline__ void gemm_phase(LAS unsigned char* lds, const int K, const int lda, const int ldb, const Sched& S, const Epi& E) {
;     ...
;             PG8_WAIT_V(8); PG8_WAIT_L(0); PG8_BAR; PG8_MMA(0, 0, At, B0); PG8_MMA(0, 1, At, B1); PG8_BAR; PG8_SCHED;
;             PG8_LDA(At, 0, 1); PG8_STAGE(PG8_SB(0, 0), b2, voffB); PG8_STAGE(PG8_SB(0, 1), b2 + hstepB, voffB); PG8_STAGE(PG8_SA(0, 0), a2, voffA);
;             PG8_WAIT_V(8); PG8_WAIT_L(0); PG8_BAR; PG8_MMA(1, 0, At, B0); PG8_MMA(1, 1, At, B1); PG8_BAR; PG8_SCHED;
	s_waitcnt lgkmcnt(0)
	v_mfma_f32_16x16x32_bf16 v[172:175], v[32:35], v[76:79], v[172:175]
	v_mfma_f32_16x16x32_bf16 v[168:171], v[48:51], v[76:79], v[168:171]
	v_mfma_f32_16x16x32_bf16 v[156:159], v[32:35], v[88:91], v[156:159]
	v_mfma_f32_16x16x32_bf16 v[152:155], v[48:51], v[88:91], v[152:155]
	v_mfma_f32_16x16x32_bf16 v[140:143], v[32:35], v[196:199], v[140:143]
	v_mfma_f32_16x16x32_bf16 v[136:139], v[48:51], v[196:199], v[136:139]
	v_mfma_f32_16x16x32_bf16 v[124:127], v[32:35], v[204:207], v[124:127]
	v_mfma_f32_16x16x32_bf16 v[120:123], v[48:51], v[204:207], v[120:123]
	v_mfma_f32_16x16x32_bf16 v[172:175], v[36:39], v[80:83], v[172:175]
	v_mfma_f32_16x16x32_bf16 v[168:171], v[52:55], v[80:83], v[168:171]
	v_mfma_f32_16x16x32_bf16 v[156:159], v[36:39], v[92:95], v[156:159]
	v_mfma_f32_16x16x32_bf16 v[152:155], v[52:55], v[92:95], v[152:155]
	v_mfma_f32_16x16x32_bf16 v[140:143], v[36:39], v[200:203], v[140:143]
	v_mfma_f32_16x16x32_bf16 v[136:139], v[52:55], v[200:203], v[136:139]
	v_mfma_f32_16x16x32_bf16 v[124:127], v[36:39], v[216:219], v[124:127]
	v_mfma_f32_16x16x32_bf16 v[120:123], v[52:55], v[216:219], v[120:123]
	v_mfma_f32_16x16x32_bf16 v[164:167], v[56:59], v[76:79], v[164:167]
	v_mfma_f32_16x16x32_bf16 v[76:79], v[64:67], v[76:79], v[160:163]
	v_mfma_f32_16x16x32_bf16 v[164:167], v[60:63], v[80:83], v[164:167]
	v_mfma_f32_16x16x32_bf16 v[76:79], v[68:71], v[80:83], v[76:79]
	v_mfma_f32_16x16x32_bf16 v[80:83], v[56:59], v[88:91], v[148:151]
	v_mfma_f32_16x16x32_bf16 v[88:91], v[64:67], v[88:91], v[144:147]
	v_mfma_f32_16x16x32_bf16 v[128:131], v[64:67], v[196:199], v[128:131]
	v_mfma_f32_16x16x32_bf16 v[116:119], v[56:59], v[204:207], v[116:119]
	v_mfma_f32_16x16x32_bf16 v[112:115], v[64:67], v[204:207], v[112:115]
	v_mfma_f32_16x16x32_bf16 v[80:83], v[60:63], v[92:95], v[80:83]
	v_mfma_f32_16x16x32_bf16 v[88:91], v[68:71], v[92:95], v[88:91]
	v_mfma_f32_16x16x32_bf16 v[92:95], v[56:59], v[196:199], v[132:135]
	v_mfma_f32_16x16x32_bf16 v[128:131], v[68:71], v[200:203], v[128:131]
	v_mfma_f32_16x16x32_bf16 v[116:119], v[60:63], v[216:219], v[116:119]
	v_mfma_f32_16x16x32_bf16 v[112:115], v[68:71], v[216:219], v[112:115]
	v_mfma_f32_16x16x32_bf16 v[92:95], v[60:63], v[200:203], v[92:95]
	s_barrier
	s_add_i32 s8, s85, s88
	v_lshl_add_u64 v[208:209], s[28:29], 0, v[186:187]
	s_mov_b32 m0, s8
	ds_read_b128 v[132:135], v213 offset:16384
	ds_read_b128 v[144:147], v213 offset:17408
	ds_read_b128 v[148:151], v213 offset:18432
	ds_read_b128 v[160:163], v213 offset:19456
	ds_read_b128 v[196:199], v213 offset:20480
	ds_read_b128 v[200:203], v213 offset:21504
	ds_read_b128 v[204:207], v213 offset:22528
	ds_read_b128 v[216:219], v213 offset:23552
	global_load_lds_dwordx4 v[208:209], off
	s_add_i32 m0, s8, 0x2000
	s_add_u32 s8, s28, 0x80000
	v_lshl_add_u64 v[228:229], s[28:29], 0, v[190:191]
	s_addc_u32 s9, s29, 0
	s_add_i32 s51, s50, s88
	global_load_lds_dwordx4 v[228:229], off
	v_lshl_add_u64 v[220:221], s[8:9], 0, v[186:187]
	s_mov_b32 m0, s51
	v_lshl_add_u64 v[230:231], s[36:37], 0, v[184:185]
	global_load_lds_dwordx4 v[220:221], off
	v_lshl_add_u64 v[220:221], s[8:9], 0, v[190:191]
	s_add_i32 m0, s51, 0x2000
	v_lshl_add_u64 v[232:233], s[36:37], 0, v[188:189]
	global_load_lds_dwordx4 v[220:221], off
	s_mov_b32 m0, s89
	s_nop 0
	global_load_lds_dwordx4 v[230:231], off
	s_mov_b32 m0, s90
	s_nop 0
	global_load_lds_dwordx4 v[232:233], off
	s_waitcnt vmcnt(8)
	s_waitcnt lgkmcnt(0)
	s_barrier
	s_waitcnt lgkmcnt(0)
	v_mfma_f32_16x16x32_bf16 v[108:111], v[32:35], v[132:135], v[108:111]
	v_mfma_f32_16x16x32_bf16 v[104:107], v[48:51], v[132:135], v[104:107]
	v_mfma_f32_16x16x32_bf16 v[84:87], v[32:35], v[148:151], v[84:87]
	v_mfma_f32_16x16x32_bf16 v[72:75], v[48:51], v[148:151], v[72:75]
	v_mfma_f32_16x16x32_bf16 v[28:31], v[32:35], v[196:199], v[28:31]
	v_mfma_f32_16x16x32_bf16 v[24:27], v[48:51], v[196:199], v[24:27]
	v_mfma_f32_16x16x32_bf16 v[12:15], v[32:35], v[204:207], v[12:15]
	v_mfma_f32_16x16x32_bf16 v[8:11], v[48:51], v[204:207], v[8:11]
	v_mfma_f32_16x16x32_bf16 v[108:111], v[36:39], v[144:147], v[108:111]
	v_mfma_f32_16x16x32_bf16 v[104:107], v[52:55], v[144:147], v[104:107]
	v_mfma_f32_16x16x32_bf16 v[84:87], v[36:39], v[160:163], v[84:87]
	v_mfma_f32_16x16x32_bf16 v[72:75], v[52:55], v[160:163], v[72:75]
	v_mfma_f32_16x16x32_bf16 v[28:31], v[36:39], v[200:203], v[28:31]
	v_mfma_f32_16x16x32_bf16 v[24:27], v[52:55], v[200:203], v[24:27]
	v_mfma_f32_16x16x32_bf16 v[12:15], v[36:39], v[216:219], v[12:15]
	v_mfma_f32_16x16x32_bf16 v[8:11], v[52:55], v[216:219], v[8:11]
	v_mfma_f32_16x16x32_bf16 v[44:47], v[56:59], v[148:151], v[44:47]
	v_mfma_f32_16x16x32_bf16 v[40:43], v[64:67], v[148:151], v[40:43]
	v_mfma_f32_16x16x32_bf16 v[20:23], v[56:59], v[196:199], v[20:23]
	v_mfma_f32_16x16x32_bf16 v[16:19], v[64:67], v[196:199], v[16:19]
	v_mfma_f32_16x16x32_bf16 v[4:7], v[56:59], v[204:207], v[4:7]
	v_mfma_f32_16x16x32_bf16 v[0:3], v[64:67], v[204:207], v[0:3]
	v_mfma_f32_16x16x32_bf16 v[32:35], v[56:59], v[132:135], v[100:103]
	v_mfma_f32_16x16x32_bf16 v[36:39], v[64:67], v[132:135], v[96:99]
	v_mfma_f32_16x16x32_bf16 v[44:47], v[60:63], v[160:163], v[44:47]
	v_mfma_f32_16x16x32_bf16 v[40:43], v[68:71], v[160:163], v[40:43]
	v_mfma_f32_16x16x32_bf16 v[20:23], v[60:63], v[200:203], v[20:23]
	v_mfma_f32_16x16x32_bf16 v[16:19], v[68:71], v[200:203], v[16:19]
	v_mfma_f32_16x16x32_bf16 v[4:7], v[60:63], v[216:219], v[4:7]
	v_mfma_f32_16x16x32_bf16 v[0:3], v[68:71], v[216:219], v[0:3]
	v_mfma_f32_16x16x32_bf16 v[32:35], v[60:63], v[144:147], v[32:35]
	v_mfma_f32_16x16x32_bf16 v[36:39], v[68:71], v[144:147], v[36:39]
	s_barrier
; #define PG8_STAGE(bufoff, gbase, voff) do { _Pragma("unroll") for (int _i = 0; _i < 2; ++_i) \
;         __builtin_amdgcn_global_load_lds((const unsigned*)((const char*)(gbase) + (voff)[_i]), (LAS unsigned*)(lds + (bufoff) + ldsw + _i * 8192), 16, 0, 0); } while (0)
; #define PG8_LDA(dst, b, h) do { _Pragma("unroll") for (int m = 0; m < 4; ++m) _Pragma("unroll") for (int k = 0; k < 2; ++k) dst[m][k] = *(const LAS bf16x8*)(lds + PG8_SA(b, h) + aoff + m * 2048 + k * 1024); } while (0)
; #define PG8_LDB(dst, b, h) do { _Pragma("unroll") for (int n = 0; n < 2; ++n) _Pragma("unroll") for (int k = 0; k < 2; ++k) dst[n][k] = *(const LAS bf16x8*)(lds + PG8_SB(b, h) + boff + n * 2048 + k * 1024); } while (0)
; #define PG8_MMA(ai, bj, At, Bt) do { __builtin_amdgcn_s_setprio(1); _Pragma("unroll") for (int m = 0; m < 4; ++m) _Pragma("unroll") for (int n = 0; n < 2; ++n) _Pragma("unroll") for (int k = 0; k < 2; ++k) \
;         acc[ai][bj][m][n] = __builtin_amdgcn_mfma_f32_16x16x32_bf16(Bt[n][k], At[m][k], acc[ai][bj][m][n], 0, 0, 0); __builtin_amdgcn_s_setprio(0); } while (0)
; #define PG8_WAIT_V(n) asm volatile("s_waitcnt vmcnt(" #n ")" ::: "memory")
; #define PG8_WAIT_L(n) asm volatile("s_waitcnt lgkmcnt(" #n ")" ::: "memory")
; #define PG8_BAR __builtin_amdgcn_s_barrier()
; #define PG8_SCHED __builtin_amdgcn_sched_barrier(0)
; template <class Sched, class Epi, bool ALIGN_EPI, bool SP2>
; __device__ __forceinline__ void gemm_phase(LAS unsigned char* lds, const int K, const int lda, const int ldb, const Sched& S, const Epi& E) {
;     ...
;         for (int t = 0; t < nt; t += 2) {
;             const bool last = (t == nt - 2);
;             const char* a1 = cA + (size_t)(t + 1) * kstep;
;             const char* a2 = last ? nA : cA + (size_t)(t + 2) * kstep; const char* b2 = last ? nB : cB + (size_t)(t + 2) * kstep;
;     ...
;             PG8_LDB(B0, 1, 0); PG8_LDB(B1, 1, 1); PG8_SCHED; PG8_LDA(At, 1, 0); PG8_STAGE(PG8_SA(0, 1), a2 + hstepA, voffA);
;             PG8_WAIT_V(8); PG8_WAIT_L(0); PG8_BAR; PG8_MMA(0, 0, At, B0); PG8_MMA(0, 1, At, B1); PG8_BAR; PG8_SCHED;
;             PG8_LDA(At, 1, 1); PG8_STAGE(PG8_SB(1, 0), b3, voffB); PG8_STAGE(PG8_SB(1, 1), b3 + hstepB, voffB); PG8_STAGE(PG8_SA(1, 0), a3, voffA);
;             PG8_WAIT_V(8); PG8_WAIT_L(0); PG8_BAR; PG8_MMA(1, 0, At, B0); PG8_MMA(1, 1, At, B1); PG8_BAR; PG8_SCHED;
	s_add_i32 s51, 0, 0x18000
	s_add_i32 s17, 0, 0x1c000
	v_add_u32_e32 v60, s51, v183
	v_add_u32_e32 v96, s17, v183
	ds_read_b128 v[48:51], v60
	ds_read_b128 v[52:55], v60 offset:1024
	ds_read_b128 v[56:59], v60 offset:2048
	ds_read_b128 v[60:63], v60 offset:3072
	ds_read_b128 v[64:67], v96
	ds_read_b128 v[68:71], v96 offset:1024
	ds_read_b128 v[196:199], v96 offset:2048
	ds_read_b128 v[200:203], v96 offset:3072
	s_add_u32 s8, s36, 0x80000
	s_addc_u32 s9, s37, 0
	s_mov_b32 m0, s91
	v_lshl_add_u64 v[148:149], s[8:9], 0, v[184:185]
	ds_read_b128 v[96:99], v213 offset:32768
	ds_read_b128 v[100:103], v213 offset:33792
	ds_read_b128 v[132:135], v213 offset:34816
	ds_read_b128 v[144:147], v213 offset:35840
	ds_read_b128 v[204:207], v213 offset:36864
	ds_read_b128 v[216:219], v213 offset:37888
	ds_read_b128 v[220:223], v213 offset:38912
	ds_read_b128 v[224:227], v213 offset:39936
	global_load_lds_dwordx4 v[148:149], off
	v_lshl_add_u64 v[148:149], s[8:9], 0, v[188:189]
	s_mov_b32 m0, s96
	s_nop 0
	global_load_lds_dwordx4 v[148:149], off
	s_waitcnt vmcnt(8)
	s_waitcnt lgkmcnt(0)
	s_barrier
	s_waitcnt lgkmcnt(0)
	v_mfma_f32_16x16x32_bf16 v[148:151], v[48:51], v[96:99], v[172:175]
	v_mfma_f32_16x16x32_bf16 v[172:175], v[52:55], v[100:103], v[148:151]
	v_mfma_f32_16x16x32_bf16 v[148:151], v[56:59], v[96:99], v[168:171]
	v_mfma_f32_16x16x32_bf16 v[168:171], v[60:63], v[100:103], v[148:151]
	v_mfma_f32_16x16x32_bf16 v[148:151], v[48:51], v[132:135], v[156:159]
	v_mfma_f32_16x16x32_bf16 v[156:159], v[52:55], v[144:147], v[148:151]
	v_mfma_f32_16x16x32_bf16 v[148:151], v[56:59], v[132:135], v[152:155]
	v_mfma_f32_16x16x32_bf16 v[140:143], v[48:51], v[204:207], v[140:143]
	v_mfma_f32_16x16x32_bf16 v[136:139], v[56:59], v[204:207], v[136:139]
	v_mfma_f32_16x16x32_bf16 v[124:127], v[48:51], v[220:223], v[124:127]
	v_mfma_f32_16x16x32_bf16 v[120:123], v[56:59], v[220:223], v[120:123]
	v_mfma_f32_16x16x32_bf16 v[152:155], v[60:63], v[144:147], v[148:151]
	v_mfma_f32_16x16x32_bf16 v[140:143], v[52:55], v[216:219], v[140:143]
	v_mfma_f32_16x16x32_bf16 v[136:139], v[60:63], v[216:219], v[136:139]
	v_mfma_f32_16x16x32_bf16 v[124:127], v[52:55], v[224:227], v[124:127]
	v_mfma_f32_16x16x32_bf16 v[120:123], v[60:63], v[224:227], v[120:123]
	v_mfma_f32_16x16x32_bf16 v[76:79], v[196:199], v[96:99], v[76:79]
	v_mfma_f32_16x16x32_bf16 v[148:151], v[64:67], v[96:99], v[164:167]
	v_mfma_f32_16x16x32_bf16 v[160:163], v[200:203], v[100:103], v[76:79]
	v_mfma_f32_16x16x32_bf16 v[76:79], v[64:67], v[132:135], v[80:83]
	v_mfma_f32_16x16x32_bf16 v[164:167], v[68:71], v[100:103], v[148:151]
	v_mfma_f32_16x16x32_bf16 v[148:151], v[68:71], v[144:147], v[76:79]
	v_mfma_f32_16x16x32_bf16 v[76:79], v[196:199], v[132:135], v[88:91]
	v_mfma_f32_16x16x32_bf16 v[144:147], v[200:203], v[144:147], v[76:79]
	v_mfma_f32_16x16x32_bf16 v[76:79], v[64:67], v[204:207], v[92:95]
	v_mfma_f32_16x16x32_bf16 v[132:135], v[68:71], v[216:219], v[76:79]
	v_mfma_f32_16x16x32_bf16 v[76:79], v[196:199], v[204:207], v[128:131]
	v_mfma_f32_16x16x32_bf16 v[128:131], v[200:203], v[216:219], v[76:79]
	v_mfma_f32_16x16x32_bf16 v[76:79], v[64:67], v[220:223], v[116:119]
	v_mfma_f32_16x16x32_bf16 v[116:119], v[68:71], v[224:227], v[76:79]
	v_mfma_f32_16x16x32_bf16 v[76:79], v[196:199], v[220:223], v[112:115]
	v_mfma_f32_16x16x32_bf16 v[112:115], v[200:203], v[224:227], v[76:79]
	s_barrier
	s_add_i32 s8, s51, s88
	v_lshl_add_u64 v[96:97], v[208:209], 0, s[10:11]
	s_mov_b32 m0, s8
	s_nop 1
	ds_read_b128 v[76:79], v213 offset:49152
	ds_read_b128 v[80:83], v213 offset:50176
	ds_read_b128 v[88:91], v213 offset:51200
	ds_read_b128 v[92:95], v213 offset:52224
	ds_read_b128 v[204:207], v213 offset:53248
	ds_read_b128 v[216:219], v213 offset:54272
	ds_read_b128 v[220:223], v213 offset:55296
	ds_read_b128 v[224:227], v213 offset:56320
	global_load_lds_dwordx4 v[96:97], off
	s_add_i32 m0, s8, 0x2000
	s_add_u32 s8, s28, 0x80080
	v_lshl_add_u64 v[96:97], v[228:229], 0, s[10:11]
	s_addc_u32 s9, s29, 0
	s_add_i32 s17, s17, s88
	global_load_lds_dwordx4 v[96:97], off
	v_lshl_add_u64 v[96:97], s[8:9], 0, v[186:187]
	s_mov_b32 m0, s17
	s_nop 0
	global_load_lds_dwordx4 v[96:97], off
	v_lshl_add_u64 v[96:97], s[8:9], 0, v[190:191]
	s_add_i32 m0, s17, 0x2000
	s_nop 0
	global_load_lds_dwordx4 v[96:97], off
	v_lshl_add_u64 v[96:97], v[230:231], 0, s[10:11]
	s_mov_b32 m0, s97
	s_nop 0
	global_load_lds_dwordx4 v[96:97], off
	v_lshl_add_u64 v[96:97], v[232:233], 0, s[10:11]
	s_mov_b32 m0, s84
	s_nop 0
	global_load_lds_dwordx4 v[96:97], off
	s_waitcnt vmcnt(8)
	s_waitcnt lgkmcnt(0)
	s_barrier
	s_waitcnt lgkmcnt(0)
	v_mfma_f32_16x16x32_bf16 v[96:99], v[48:51], v[76:79], v[108:111]
	v_mfma_f32_16x16x32_bf16 v[108:111], v[52:55], v[80:83], v[96:99]
	v_mfma_f32_16x16x32_bf16 v[96:99], v[56:59], v[76:79], v[104:107]
	v_mfma_f32_16x16x32_bf16 v[84:87], v[48:51], v[88:91], v[84:87]
	v_mfma_f32_16x16x32_bf16 v[72:75], v[56:59], v[88:91], v[72:75]
	v_mfma_f32_16x16x32_bf16 v[28:31], v[48:51], v[204:207], v[28:31]
	v_mfma_f32_16x16x32_bf16 v[24:27], v[56:59], v[204:207], v[24:27]
	v_mfma_f32_16x16x32_bf16 v[12:15], v[48:51], v[220:223], v[12:15]
	v_mfma_f32_16x16x32_bf16 v[8:11], v[56:59], v[220:223], v[8:11]
	v_mfma_f32_16x16x32_bf16 v[104:107], v[60:63], v[80:83], v[96:99]
	v_mfma_f32_16x16x32_bf16 v[84:87], v[52:55], v[92:95], v[84:87]
	v_mfma_f32_16x16x32_bf16 v[72:75], v[60:63], v[92:95], v[72:75]
	v_mfma_f32_16x16x32_bf16 v[28:31], v[52:55], v[216:219], v[28:31]
	v_mfma_f32_16x16x32_bf16 v[24:27], v[60:63], v[216:219], v[24:27]
	v_mfma_f32_16x16x32_bf16 v[12:15], v[52:55], v[224:227], v[12:15]
	v_mfma_f32_16x16x32_bf16 v[8:11], v[60:63], v[224:227], v[8:11]
	v_mfma_f32_16x16x32_bf16 v[32:35], v[64:67], v[76:79], v[32:35]
	v_mfma_f32_16x16x32_bf16 v[100:103], v[68:71], v[80:83], v[32:35]
	v_mfma_f32_16x16x32_bf16 v[32:35], v[196:199], v[76:79], v[36:39]
	v_mfma_f32_16x16x32_bf16 v[96:99], v[200:203], v[80:83], v[32:35]
	v_mfma_f32_16x16x32_bf16 v[32:35], v[64:67], v[88:91], v[44:47]
	v_mfma_f32_16x16x32_bf16 v[44:47], v[68:71], v[92:95], v[32:35]
	v_mfma_f32_16x16x32_bf16 v[32:35], v[196:199], v[88:91], v[40:43]
	v_mfma_f32_16x16x32_bf16 v[20:23], v[64:67], v[204:207], v[20:23]
	v_mfma_f32_16x16x32_bf16 v[16:19], v[196:199], v[204:207], v[16:19]
	v_mfma_f32_16x16x32_bf16 v[4:7], v[64:67], v[220:223], v[4:7]
	v_mfma_f32_16x16x32_bf16 v[0:3], v[196:199], v[220:223], v[0:3]
	v_mfma_f32_16x16x32_bf16 v[40:43], v[200:203], v[92:95], v[32:35]
	v_mfma_f32_16x16x32_bf16 v[20:23], v[68:71], v[216:219], v[20:23]
	v_mfma_f32_16x16x32_bf16 v[16:19], v[200:203], v[216:219], v[16:19]
	v_mfma_f32_16x16x32_bf16 v[4:7], v[68:71], v[224:227], v[4:7]
	v_mfma_f32_16x16x32_bf16 v[0:3], v[200:203], v[224:227], v[0:3]
	s_barrier
	s_add_i32 s7, s7, 2
	s_add_u32 s26, s26, 0x100
	s_addc_u32 s27, s27, 0
	s_add_u32 vcc_hi, vcc_hi, 0x100
	s_addc_u32 s6, s6, 0
	s_cmp_gt_u32 s7, 29
	s_cbranch_scc0 .LBB0_353
	s_setprio 0
	s_and_b64 vcc, exec, s[12:13]
	s_cbranch_vccz .LBB0_356
	s_barrier

; #define PG8_STAGE(bufoff, gbase, voff) do { _Pragma("unroll") for (int _i = 0; _i < 2; ++_i) \
;         __builtin_amdgcn_global_load_lds((const unsigned*)((const char*)(gbase) + (voff)[_i]), (LAS unsigned*)(lds + (bufoff) + ldsw + _i * 8192), 16, 0, 0); } while (0)
; #define PG8_LDA(dst, b, h) do { _Pragma("unroll") for (int m = 0; m < 4; ++m) _Pragma("unroll") for (int k = 0; k < 2; ++k) dst[m][k] = *(const LAS bf16x8*)(lds + PG8_SA(b, h) + aoff + m * 2048 + k * 1024); } while (0)
; #define PG8_LDB(dst, b, h) do { _Pragma("unroll") for (int n = 0; n < 2; ++n) _Pragma("unroll") for (int k = 0; k < 2; ++k) dst[n][k] = *(const LAS bf16x8*)(lds + PG8_SB(b, h) + boff + n * 2048 + k * 1024); } while (0)
; #define PG8_MMA(ai, bj, At, Bt) do { __builtin_amdgcn_s_setprio(1); _Pragma("unroll") for (int m = 0; m < 4; ++m) _Pragma("unroll") for (int n = 0; n < 2; ++n) _Pragma("unroll") for (int k = 0; k < 2; ++k) \
;         acc[ai][bj][m][n] = __builtin_amdgcn_mfma_f32_16x16x32_bf16(Bt[n][k], At[m][k], acc[ai][bj][m][n], 0, 0, 0); __builtin_amdgcn_s_setprio(0); } while (0)
; #define PG8_WAIT_V(n) asm volatile("s_waitcnt vmcnt(" #n ")" ::: "memory")
; #define PG8_WAIT_L(n) asm volatile("s_waitcnt lgkmcnt(" #n ")" ::: "memory")
; #define PG8_BAR __builtin_amdgcn_s_barrier()
; #define PG8_SCHED __builtin_amdgcn_sched_barrier(0)
; template <class Sched, class Epi, bool ALIGN_EPI, bool SP2>
; __device__ __forceinline__ void gemm_phase(LAS unsigned char* lds, const int K, const int lda, const int ldb, const Sched& S, const Epi& E) {
;     ...
;             const bool last = (t == nt - 2);
;             const char* a1 = cA + (size_t)(t + 1) * kstep;
;             const char* a2 = last ? nA : cA + (size_t)(t + 2) * kstep; const char* b2 = last ? nB : cB + (size_t)(t + 2) * kstep;
;             const char* a3 = a2 + kstep; const char* b3 = b2 + kstep;
;             if constexpr (SP2) {
;             PG8_LDB(B0, 0, 0); PG8_LDB(B1, 0, 1); PG8_SCHED; PG8_LDA(At, 0, 0); PG8_STAGE(PG8_SA(1, 1), a1 + hstepA, voffA);
;             PG8_WAIT_V(8); PG8_WAIT_L(0); PG8_BAR; PG8_MMA(0, 0, At, B0); PG8_MMA(0, 1, At, B1); PG8_BAR; PG8_SCHED;
;             PG8_LDA(At, 0, 1); PG8_STAGE(PG8_SB(0, 0), b2, voffB); PG8_STAGE(PG8_SB(0, 1), b2 + hstepB, voffB); PG8_STAGE(PG8_SA(0, 0), a2, voffA);
.LBB0_820:
	s_add_u32 s53, s20, 0x100
	s_addc_u32 s60, s21, 0
	s_mov_b32 s61, -2
	v_readlane_b32 s98, v255, 13
	s_nop 4
	s_cmp_lt_u32 s98, 4
	s_cbranch_scc1 .Lprio_skip_821
	s_setprio 1
.Lprio_skip_821:
.LBB0_821:
	v_add_u32_e32 v140, s44, v181
	v_add_u32_e32 v170, s45, v181
	ds_read_b128 v[128:131], v140
	ds_read_b128 v[132:135], v140 offset:1024
	ds_read_b128 v[136:139], v140 offset:2048
	ds_read_b128 v[140:143], v140 offset:3072
	ds_read_b128 v[144:147], v170
	ds_read_b128 v[148:151], v170 offset:1024
	ds_read_b128 v[166:169], v170 offset:2048
	ds_read_b128 v[170:173], v170 offset:3072
	s_add_u32 s20, s4, 0x100
	s_addc_u32 s21, s5, 0
	s_cmp_eq_u32 s61, 12
	s_cselect_b32 s25, s15, s21
	s_cselect_b32 s24, s14, s20
	s_cselect_b32 s23, s17, s60
	s_cselect_b32 s22, s16, s53
	v_lshl_add_u64 v[174:175], s[4:5], 0, v[162:163]
	s_add_i32 m0, s29, 0xc000
	ds_read_b128 v[184:187], v183
	ds_read_b128 v[188:191], v183 offset:1024
	ds_read_b128 v[192:195], v183 offset:2048
	ds_read_b128 v[196:199], v183 offset:3072
	ds_read_b128 v[200:203], v183 offset:4096
	ds_read_b128 v[204:207], v183 offset:5120
	ds_read_b128 v[208:211], v183 offset:6144
	ds_read_b128 v[212:215], v183 offset:7168
	global_load_lds_dwordx4 v[174:175], off
	v_lshl_add_u64 v[174:175], s[4:5], 0, v[164:165]
	s_add_i32 m0, s29, 0xe000
	s_nop 0
	global_load_lds_dwordx4 v[174:175], off
	s_waitcnt vmcnt(8)
	s_waitcnt lgkmcnt(0)
	s_barrier
	s_waitcnt lgkmcnt(0)
	v_mfma_f32_16x16x32_bf16 v[124:127], v[128:131], v[184:187], v[124:127]
	v_mfma_f32_16x16x32_bf16 v[120:123], v[136:139], v[184:187], v[120:123]
	v_mfma_f32_16x16x32_bf16 v[116:119], v[128:131], v[192:195], v[116:119]
	v_mfma_f32_16x16x32_bf16 v[112:115], v[136:139], v[192:195], v[112:115]
	v_mfma_f32_16x16x32_bf16 v[108:111], v[128:131], v[200:203], v[108:111]
	v_mfma_f32_16x16x32_bf16 v[104:107], v[136:139], v[200:203], v[104:107]
	v_mfma_f32_16x16x32_bf16 v[100:103], v[128:131], v[208:211], v[100:103]
	v_mfma_f32_16x16x32_bf16 v[96:99], v[136:139], v[208:211], v[96:99]
	v_mfma_f32_16x16x32_bf16 v[124:127], v[132:135], v[188:191], v[124:127]
	v_mfma_f32_16x16x32_bf16 v[120:123], v[140:143], v[188:191], v[120:123]
	v_mfma_f32_16x16x32_bf16 v[116:119], v[132:135], v[196:199], v[116:119]
	v_mfma_f32_16x16x32_bf16 v[112:115], v[140:143], v[196:199], v[112:115]
	v_mfma_f32_16x16x32_bf16 v[108:111], v[132:135], v[204:207], v[108:111]
	v_mfma_f32_16x16x32_bf16 v[104:107], v[140:143], v[204:207], v[104:107]
	v_mfma_f32_16x16x32_bf16 v[100:103], v[132:135], v[212:215], v[100:103]
	v_mfma_f32_16x16x32_bf16 v[96:99], v[140:143], v[212:215], v[96:99]
	v_mfma_f32_16x16x32_bf16 v[92:95], v[144:147], v[184:187], v[92:95]
	v_mfma_f32_16x16x32_bf16 v[88:91], v[166:169], v[184:187], v[88:91]
	v_mfma_f32_16x16x32_bf16 v[84:87], v[144:147], v[192:195], v[84:87]
	v_mfma_f32_16x16x32_bf16 v[80:83], v[166:169], v[192:195], v[80:83]
	v_mfma_f32_16x16x32_bf16 v[76:79], v[144:147], v[200:203], v[76:79]
	v_mfma_f32_16x16x32_bf16 v[72:75], v[166:169], v[200:203], v[72:75]
	v_mfma_f32_16x16x32_bf16 v[68:71], v[144:147], v[208:211], v[68:71]
	v_mfma_f32_16x16x32_bf16 v[64:67], v[166:169], v[208:211], v[64:67]
	v_mfma_f32_16x16x32_bf16 v[92:95], v[148:151], v[188:191], v[92:95]
	v_mfma_f32_16x16x32_bf16 v[88:91], v[170:173], v[188:191], v[88:91]
	v_mfma_f32_16x16x32_bf16 v[84:87], v[148:151], v[196:199], v[84:87]
	v_mfma_f32_16x16x32_bf16 v[80:83], v[170:173], v[196:199], v[80:83]
	v_mfma_f32_16x16x32_bf16 v[76:79], v[148:151], v[204:207], v[76:79]
	v_mfma_f32_16x16x32_bf16 v[72:75], v[170:173], v[204:207], v[72:75]
	v_mfma_f32_16x16x32_bf16 v[68:71], v[148:151], v[212:215], v[68:71]
	v_mfma_f32_16x16x32_bf16 v[64:67], v[170:173], v[212:215], v[64:67]
	s_barrier
	s_add_i32 s4, s44, s28
	v_lshl_add_u64 v[174:175], s[22:23], 0, v[156:157]
	s_mov_b32 m0, s4
	ds_read_b128 v[184:187], v183 offset:16384
	ds_read_b128 v[188:191], v183 offset:17408
	ds_read_b128 v[192:195], v183 offset:18432
	ds_read_b128 v[196:199], v183 offset:19456
	ds_read_b128 v[200:203], v183 offset:20480
	ds_read_b128 v[204:207], v183 offset:21504
	ds_read_b128 v[208:211], v183 offset:22528
	ds_read_b128 v[212:215], v183 offset:23552
	global_load_lds_dwordx4 v[174:175], off
	s_add_i32 m0, s4, 0x2000
	s_add_u32 s4, s22, 0x40000
	v_lshl_add_u64 v[216:217], s[22:23], 0, v[160:161]
	s_addc_u32 s5, s23, 0
	s_add_i32 s62, s45, s28
	global_load_lds_dwordx4 v[216:217], off
	v_lshl_add_u64 v[218:219], s[4:5], 0, v[156:157]
	s_mov_b32 m0, s62
	v_lshl_add_u64 v[220:221], s[24:25], 0, v[158:159]
	global_load_lds_dwordx4 v[218:219], off
	v_lshl_add_u64 v[218:219], s[4:5], 0, v[160:161]
	s_add_i32 m0, s62, 0x2000
	s_nop 0
	global_load_lds_dwordx4 v[218:219], off
	v_lshl_add_u64 v[218:219], s[24:25], 0, v[154:155]
	s_mov_b32 m0, s29
	s_nop 0
	global_load_lds_dwordx4 v[218:219], off
	s_mov_b32 m0, s33
	s_nop 0
	global_load_lds_dwordx4 v[220:221], off
	s_waitcnt vmcnt(8)
	s_waitcnt lgkmcnt(0)
	s_barrier
; #define PG8_STAGE(bufoff, gbase, voff) do { _Pragma("unroll") for (int _i = 0; _i < 2; ++_i) \
;         __builtin_amdgcn_global_load_lds((const unsigned*)((const char*)(gbase) + (voff)[_i]), (LAS unsigned*)(lds + (bufoff) + ldsw + _i * 8192), 16, 0, 0); } while (0)
; #define PG8_LDA(dst, b, h) do { _Pragma("unroll") for (int m = 0; m < 4; ++m) _Pragma("unroll") for (int k = 0; k < 2; ++k) dst[m][k] = *(const LAS bf16x8*)(lds + PG8_SA(b, h) + aoff + m * 2048 + k * 1024); } while (0)
; #define PG8_LDB(dst, b, h) do { _Pragma("unroll") for (int n = 0; n < 2; ++n) _Pragma("unroll") for (int k = 0; k < 2; ++k) dst[n][k] = *(const LAS bf16x8*)(lds + PG8_SB(b, h) + boff + n * 2048 + k * 1024); } while (0)
; #define PG8_MMA(ai, bj, At, Bt) do { __builtin_amdgcn_s_setprio(1); _Pragma("unroll") for (int m = 0; m < 4; ++m) _Pragma("unroll") for (int n = 0; n < 2; ++n) _Pragma("unroll") for (int k = 0; k < 2; ++k) \
;         acc[ai][bj][m][n] = __builtin_amdgcn_mfma_f32_16x16x32_bf16(Bt[n][k], At[m][k], acc[ai][bj][m][n], 0, 0, 0); __builtin_amdgcn_s_setprio(0); } while (0)
; #define PG8_WAIT_V(n) asm volatile("s_waitcnt vmcnt(" #n ")" ::: "memory")
; #define PG8_WAIT_L(n) asm volatile("s_waitcnt lgkmcnt(" #n ")" ::: "memory")
; #define PG8_BAR __builtin_amdgcn_s_barrier()
; #define PG8_SCHED __builtin_amdgcn_sched_barrier(0)
; template <class Sched, class Epi, bool ALIGN_EPI, bool SP2>
; __device__ __forceinline__ void gemm_phase(LAS unsigned char* lds, const int K, const int lda, const int ldb, const Sched& S, const Epi& E) {
;     ...
;             PG8_WAIT_V(8); PG8_WAIT_L(0); PG8_BAR; PG8_MMA(1, 0, At, B0); PG8_MMA(1, 1, At, B1); PG8_BAR; PG8_SCHED;
;             PG8_LDB(B0, 1, 0); PG8_LDB(B1, 1, 1); PG8_SCHED; PG8_LDA(At, 1, 0); PG8_STAGE(PG8_SA(0, 1), a2 + hstepA, voffA);
;             PG8_WAIT_V(8); PG8_WAIT_L(0); PG8_BAR; PG8_MMA(0, 0, At, B0); PG8_MMA(0, 1, At, B1); PG8_BAR; PG8_SCHED;
	s_waitcnt lgkmcnt(0)
	v_mfma_f32_16x16x32_bf16 v[60:63], v[128:131], v[184:187], v[60:63]
	v_mfma_f32_16x16x32_bf16 v[56:59], v[136:139], v[184:187], v[56:59]
	v_mfma_f32_16x16x32_bf16 v[52:55], v[128:131], v[192:195], v[52:55]
	v_mfma_f32_16x16x32_bf16 v[48:51], v[136:139], v[192:195], v[48:51]
	v_mfma_f32_16x16x32_bf16 v[44:47], v[128:131], v[200:203], v[44:47]
	v_mfma_f32_16x16x32_bf16 v[40:43], v[136:139], v[200:203], v[40:43]
	v_mfma_f32_16x16x32_bf16 v[36:39], v[128:131], v[208:211], v[36:39]
	v_mfma_f32_16x16x32_bf16 v[32:35], v[136:139], v[208:211], v[32:35]
	v_mfma_f32_16x16x32_bf16 v[60:63], v[132:135], v[188:191], v[60:63]
	v_mfma_f32_16x16x32_bf16 v[56:59], v[140:143], v[188:191], v[56:59]
	v_mfma_f32_16x16x32_bf16 v[52:55], v[132:135], v[196:199], v[52:55]
	v_mfma_f32_16x16x32_bf16 v[48:51], v[140:143], v[196:199], v[48:51]
	v_mfma_f32_16x16x32_bf16 v[44:47], v[132:135], v[204:207], v[44:47]
	v_mfma_f32_16x16x32_bf16 v[40:43], v[140:143], v[204:207], v[40:43]
	v_mfma_f32_16x16x32_bf16 v[36:39], v[132:135], v[212:215], v[36:39]
	v_mfma_f32_16x16x32_bf16 v[32:35], v[140:143], v[212:215], v[32:35]
	v_mfma_f32_16x16x32_bf16 v[28:31], v[144:147], v[184:187], v[28:31]
	v_mfma_f32_16x16x32_bf16 v[24:27], v[166:169], v[184:187], v[24:27]
	v_mfma_f32_16x16x32_bf16 v[20:23], v[144:147], v[192:195], v[20:23]
	v_mfma_f32_16x16x32_bf16 v[16:19], v[166:169], v[192:195], v[16:19]
	v_mfma_f32_16x16x32_bf16 v[12:15], v[144:147], v[200:203], v[12:15]
	v_mfma_f32_16x16x32_bf16 v[8:11], v[166:169], v[200:203], v[8:11]
	v_mfma_f32_16x16x32_bf16 v[4:7], v[144:147], v[208:211], v[4:7]
	v_mfma_f32_16x16x32_bf16 v[0:3], v[166:169], v[208:211], v[0:3]
	v_mfma_f32_16x16x32_bf16 v[28:31], v[148:151], v[188:191], v[28:31]
	v_mfma_f32_16x16x32_bf16 v[24:27], v[170:173], v[188:191], v[24:27]
	v_mfma_f32_16x16x32_bf16 v[20:23], v[148:151], v[196:199], v[20:23]
	v_mfma_f32_16x16x32_bf16 v[16:19], v[170:173], v[196:199], v[16:19]
	v_mfma_f32_16x16x32_bf16 v[12:15], v[148:151], v[204:207], v[12:15]
	v_mfma_f32_16x16x32_bf16 v[8:11], v[170:173], v[204:207], v[8:11]
	v_mfma_f32_16x16x32_bf16 v[4:7], v[148:151], v[212:215], v[4:7]
	v_mfma_f32_16x16x32_bf16 v[0:3], v[170:173], v[212:215], v[0:3]
	s_barrier
	s_add_i32 s62, 0, 0x18000
	s_add_i32 s63, 0, 0x1c000
	v_add_u32_e32 v140, s62, v181
	v_add_u32_e32 v170, s63, v181
	ds_read_b128 v[128:131], v140
	ds_read_b128 v[132:135], v140 offset:1024
	ds_read_b128 v[136:139], v140 offset:2048
	ds_read_b128 v[140:143], v140 offset:3072
	ds_read_b128 v[144:147], v170
	ds_read_b128 v[148:151], v170 offset:1024
	ds_read_b128 v[166:169], v170 offset:2048
	ds_read_b128 v[170:173], v170 offset:3072
	s_add_u32 s4, s24, 0xc0000
	s_addc_u32 s5, s25, 0
	s_mov_b32 m0, s35
	v_lshl_add_u64 v[222:223], s[4:5], 0, v[154:155]
	ds_read_b128 v[184:187], v183 offset:32768
	ds_read_b128 v[188:191], v183 offset:33792
	ds_read_b128 v[192:195], v183 offset:34816
	ds_read_b128 v[196:199], v183 offset:35840
	ds_read_b128 v[200:203], v183 offset:36864
	ds_read_b128 v[204:207], v183 offset:37888
	ds_read_b128 v[208:211], v183 offset:38912
	ds_read_b128 v[212:215], v183 offset:39936
	global_load_lds_dwordx4 v[222:223], off
	v_lshl_add_u64 v[222:223], s[4:5], 0, v[158:159]
	s_mov_b32 m0, s36
	s_nop 0
	global_load_lds_dwordx4 v[222:223], off
	s_waitcnt vmcnt(8)
	s_waitcnt lgkmcnt(0)
	s_barrier
	s_waitcnt lgkmcnt(0)
	v_mfma_f32_16x16x32_bf16 v[124:127], v[128:131], v[184:187], v[124:127]
	v_mfma_f32_16x16x32_bf16 v[120:123], v[136:139], v[184:187], v[120:123]
	v_mfma_f32_16x16x32_bf16 v[116:119], v[128:131], v[192:195], v[116:119]
	v_mfma_f32_16x16x32_bf16 v[112:115], v[136:139], v[192:195], v[112:115]
	v_mfma_f32_16x16x32_bf16 v[108:111], v[128:131], v[200:203], v[108:111]
	v_mfma_f32_16x16x32_bf16 v[104:107], v[136:139], v[200:203], v[104:107]
	v_mfma_f32_16x16x32_bf16 v[100:103], v[128:131], v[208:211], v[100:103]
	v_mfma_f32_16x16x32_bf16 v[96:99], v[136:139], v[208:211], v[96:99]
	v_mfma_f32_16x16x32_bf16 v[124:127], v[132:135], v[188:191], v[124:127]
	v_mfma_f32_16x16x32_bf16 v[120:123], v[140:143], v[188:191], v[120:123]
	v_mfma_f32_16x16x32_bf16 v[116:119], v[132:135], v[196:199], v[116:119]
	v_mfma_f32_16x16x32_bf16 v[112:115], v[140:143], v[196:199], v[112:115]
	v_mfma_f32_16x16x32_bf16 v[108:111], v[132:135], v[204:207], v[108:111]
	v_mfma_f32_16x16x32_bf16 v[104:107], v[140:143], v[204:207], v[104:107]
	v_mfma_f32_16x16x32_bf16 v[100:103], v[132:135], v[212:215], v[100:103]
	v_mfma_f32_16x16x32_bf16 v[96:99], v[140:143], v[212:215], v[96:99]
	v_mfma_f32_16x16x32_bf16 v[92:95], v[144:147], v[184:187], v[92:95]
	v_mfma_f32_16x16x32_bf16 v[88:91], v[166:169], v[184:187], v[88:91]
	v_mfma_f32_16x16x32_bf16 v[84:87], v[144:147], v[192:195], v[84:87]
	v_mfma_f32_16x16x32_bf16 v[80:83], v[166:169], v[192:195], v[80:83]
	v_mfma_f32_16x16x32_bf16 v[76:79], v[144:147], v[200:203], v[76:79]
	v_mfma_f32_16x16x32_bf16 v[72:75], v[166:169], v[200:203], v[72:75]
	v_mfma_f32_16x16x32_bf16 v[68:71], v[144:147], v[208:211], v[68:71]
	v_mfma_f32_16x16x32_bf16 v[64:67], v[166:169], v[208:211], v[64:67]
	v_mfma_f32_16x16x32_bf16 v[92:95], v[148:151], v[188:191], v[92:95]
	v_mfma_f32_16x16x32_bf16 v[88:91], v[170:173], v[188:191], v[88:91]
	v_mfma_f32_16x16x32_bf16 v[84:87], v[148:151], v[196:199], v[84:87]
	v_mfma_f32_16x16x32_bf16 v[80:83], v[170:173], v[196:199], v[80:83]
	v_mfma_f32_16x16x32_bf16 v[76:79], v[148:151], v[204:207], v[76:79]
	v_mfma_f32_16x16x32_bf16 v[72:75], v[170:173], v[204:207], v[72:75]
	v_mfma_f32_16x16x32_bf16 v[68:71], v[148:151], v[212:215], v[68:71]
	v_mfma_f32_16x16x32_bf16 v[64:67], v[170:173], v[212:215], v[64:67]
	s_barrier
; #define PG8_STAGE(bufoff, gbase, voff) do { _Pragma("unroll") for (int _i = 0; _i < 2; ++_i) \
;         __builtin_amdgcn_global_load_lds((const unsigned*)((const char*)(gbase) + (voff)[_i]), (LAS unsigned*)(lds + (bufoff) + ldsw + _i * 8192), 16, 0, 0); } while (0)
; #define PG8_LDA(dst, b, h) do { _Pragma("unroll") for (int m = 0; m < 4; ++m) _Pragma("unroll") for (int k = 0; k < 2; ++k) dst[m][k] = *(const LAS bf16x8*)(lds + PG8_SA(b, h) + aoff + m * 2048 + k * 1024); } while (0)
; #define PG8_MMA(ai, bj, At, Bt) do { __builtin_amdgcn_s_setprio(1); _Pragma("unroll") for (int m = 0; m < 4; ++m) _Pragma("unroll") for (int n = 0; n < 2; ++n) _Pragma("unroll") for (int k = 0; k < 2; ++k) \
;         acc[ai][bj][m][n] = __builtin_amdgcn_mfma_f32_16x16x32_bf16(Bt[n][k], At[m][k], acc[ai][bj][m][n], 0, 0, 0); __builtin_amdgcn_s_setprio(0); } while (0)
; #define PG8_WAIT_V(n) asm volatile("s_waitcnt vmcnt(" #n ")" ::: "memory")
; #define PG8_WAIT_L(n) asm volatile("s_waitcnt lgkmcnt(" #n ")" ::: "memory")
; #define PG8_BAR __builtin_amdgcn_s_barrier()
; #define PG8_SCHED __builtin_amdgcn_sched_barrier(0)
; template <class Sched, class Epi, bool ALIGN_EPI, bool SP2>
; __device__ __forceinline__ void gemm_phase(LAS unsigned char* lds, const int K, const int lda, const int ldb, const Sched& S, const Epi& E) {
;     ...
;         for (int t = 0; t < nt; t += 2) {
;             const bool last = (t == nt - 2);
;             const char* a1 = cA + (size_t)(t + 1) * kstep;
;             const char* a2 = last ? nA : cA + (size_t)(t + 2) * kstep; const char* b2 = last ? nB : cB + (size_t)(t + 2) * kstep;
;     ...
;             PG8_LDA(At, 1, 1); PG8_STAGE(PG8_SB(1, 0), b3, voffB); PG8_STAGE(PG8_SB(1, 1), b3 + hstepB, voffB); PG8_STAGE(PG8_SA(1, 0), a3, voffA);
;             PG8_WAIT_V(8); PG8_WAIT_L(0); PG8_BAR; PG8_MMA(1, 0, At, B0); PG8_MMA(1, 1, At, B1); PG8_BAR; PG8_SCHED;
	s_add_i32 s4, s62, s28
	v_lshl_add_u64 v[174:175], v[174:175], 0, s[8:9]
	s_mov_b32 m0, s4
	ds_read_b128 v[184:187], v183 offset:49152
	ds_read_b128 v[188:191], v183 offset:50176
	ds_read_b128 v[192:195], v183 offset:51200
	ds_read_b128 v[196:199], v183 offset:52224
	ds_read_b128 v[200:203], v183 offset:53248
	ds_read_b128 v[204:207], v183 offset:54272
	ds_read_b128 v[208:211], v183 offset:55296
	ds_read_b128 v[212:215], v183 offset:56320
	global_load_lds_dwordx4 v[174:175], off
	s_add_i32 m0, s4, 0x2000
	s_add_u32 s4, s22, 0x40080
	v_lshl_add_u64 v[174:175], v[216:217], 0, s[8:9]
	s_addc_u32 s5, s23, 0
	s_add_i32 s22, s63, s28
	global_load_lds_dwordx4 v[174:175], off
	v_lshl_add_u64 v[174:175], s[4:5], 0, v[156:157]
	s_mov_b32 m0, s22
	s_nop 0
	global_load_lds_dwordx4 v[174:175], off
	v_lshl_add_u64 v[174:175], s[4:5], 0, v[160:161]
	s_add_i32 m0, s22, 0x2000
	s_nop 0
	global_load_lds_dwordx4 v[174:175], off
	v_lshl_add_u64 v[174:175], v[218:219], 0, s[8:9]
	s_mov_b32 m0, s42
	s_nop 0
	global_load_lds_dwordx4 v[174:175], off
	v_lshl_add_u64 v[174:175], v[220:221], 0, s[8:9]
	s_mov_b32 m0, s43
	s_nop 0
	global_load_lds_dwordx4 v[174:175], off
	s_waitcnt vmcnt(8)
	s_waitcnt lgkmcnt(0)
	s_barrier
	s_waitcnt lgkmcnt(0)
	v_mfma_f32_16x16x32_bf16 v[60:63], v[128:131], v[184:187], v[60:63]
	v_mfma_f32_16x16x32_bf16 v[56:59], v[136:139], v[184:187], v[56:59]
	v_mfma_f32_16x16x32_bf16 v[52:55], v[128:131], v[192:195], v[52:55]
	v_mfma_f32_16x16x32_bf16 v[48:51], v[136:139], v[192:195], v[48:51]
	v_mfma_f32_16x16x32_bf16 v[44:47], v[128:131], v[200:203], v[44:47]
	v_mfma_f32_16x16x32_bf16 v[40:43], v[136:139], v[200:203], v[40:43]
	v_mfma_f32_16x16x32_bf16 v[36:39], v[128:131], v[208:211], v[36:39]
	v_mfma_f32_16x16x32_bf16 v[32:35], v[136:139], v[208:211], v[32:35]
	v_mfma_f32_16x16x32_bf16 v[60:63], v[132:135], v[188:191], v[60:63]
	v_mfma_f32_16x16x32_bf16 v[56:59], v[140:143], v[188:191], v[56:59]
	v_mfma_f32_16x16x32_bf16 v[52:55], v[132:135], v[196:199], v[52:55]
	v_mfma_f32_16x16x32_bf16 v[48:51], v[140:143], v[196:199], v[48:51]
	v_mfma_f32_16x16x32_bf16 v[44:47], v[132:135], v[204:207], v[44:47]
	v_mfma_f32_16x16x32_bf16 v[40:43], v[140:143], v[204:207], v[40:43]
	v_mfma_f32_16x16x32_bf16 v[36:39], v[132:135], v[212:215], v[36:39]
	v_mfma_f32_16x16x32_bf16 v[32:35], v[140:143], v[212:215], v[32:35]
	v_mfma_f32_16x16x32_bf16 v[28:31], v[144:147], v[184:187], v[28:31]
	v_mfma_f32_16x16x32_bf16 v[24:27], v[166:169], v[184:187], v[24:27]
	v_mfma_f32_16x16x32_bf16 v[20:23], v[144:147], v[192:195], v[20:23]
	v_mfma_f32_16x16x32_bf16 v[16:19], v[166:169], v[192:195], v[16:19]
	v_mfma_f32_16x16x32_bf16 v[12:15], v[144:147], v[200:203], v[12:15]
	v_mfma_f32_16x16x32_bf16 v[8:11], v[166:169], v[200:203], v[8:11]
	v_mfma_f32_16x16x32_bf16 v[4:7], v[144:147], v[208:211], v[4:7]
	v_mfma_f32_16x16x32_bf16 v[0:3], v[166:169], v[208:211], v[0:3]
	v_mfma_f32_16x16x32_bf16 v[28:31], v[148:151], v[188:191], v[28:31]
	v_mfma_f32_16x16x32_bf16 v[24:27], v[170:173], v[188:191], v[24:27]
	v_mfma_f32_16x16x32_bf16 v[20:23], v[148:151], v[196:199], v[20:23]
	v_mfma_f32_16x16x32_bf16 v[16:19], v[170:173], v[196:199], v[16:19]
	v_mfma_f32_16x16x32_bf16 v[12:15], v[148:151], v[204:207], v[12:15]
	v_mfma_f32_16x16x32_bf16 v[8:11], v[170:173], v[204:207], v[8:11]
	v_mfma_f32_16x16x32_bf16 v[4:7], v[148:151], v[212:215], v[4:7]
	v_mfma_f32_16x16x32_bf16 v[0:3], v[170:173], v[212:215], v[0:3]
	s_barrier
	s_add_i32 s61, s61, 2
	s_add_u32 s53, s53, 0x100
	s_addc_u32 s60, s60, 0
	s_cmp_gt_u32 s61, 13
	s_mov_b64 s[4:5], s[20:21]
	s_cbranch_scc0 .LBB0_821
	s_setprio 0
	s_and_b64 vcc, exec, s[10:11]
	s_cbranch_vccz .LBB0_824
	s_barrier

; #define PG8_STAGE(bufoff, gbase, voff) do { _Pragma("unroll") for (int _i = 0; _i < 2; ++_i) \
;         __builtin_amdgcn_global_load_lds((const unsigned*)((const char*)(gbase) + (voff)[_i]), (LAS unsigned*)(lds + (bufoff) + ldsw + _i * 8192), 16, 0, 0); } while (0)
; #define PG8_LDA(dst, b, h) do { _Pragma("unroll") for (int m = 0; m < 4; ++m) _Pragma("unroll") for (int k = 0; k < 2; ++k) dst[m][k] = *(const LAS bf16x8*)(lds + PG8_SA(b, h) + aoff + m * 2048 + k * 1024); } while (0)
; #define PG8_LDB(dst, b, h) do { _Pragma("unroll") for (int n = 0; n < 2; ++n) _Pragma("unroll") for (int k = 0; k < 2; ++k) dst[n][k] = *(const LAS bf16x8*)(lds + PG8_SB(b, h) + boff + n * 2048 + k * 1024); } while (0)
; #define PG8_MMA(ai, bj, At, Bt) do { __builtin_amdgcn_s_setprio(1); _Pragma("unroll") for (int m = 0; m < 4; ++m) _Pragma("unroll") for (int n = 0; n < 2; ++n) _Pragma("unroll") for (int k = 0; k < 2; ++k) \
;         acc[ai][bj][m][n] = __builtin_amdgcn_mfma_f32_16x16x32_bf16(Bt[n][k], At[m][k], acc[ai][bj][m][n], 0, 0, 0); __builtin_amdgcn_s_setprio(0); } while (0)
; #define PG8_WAIT_V(n) asm volatile("s_waitcnt vmcnt(" #n ")" ::: "memory")
; #define PG8_WAIT_L(n) asm volatile("s_waitcnt lgkmcnt(" #n ")" ::: "memory")
; template <class Sched, class Epi, bool ALIGN_EPI, bool SP2>
; __device__ __forceinline__ void gemm_phase(LAS unsigned char* lds, const int K, const int lda, const int ldb, const Sched& S, const Epi& E) {
;     ...
;             const bool last = (t == nt - 2);
;             const char* a1 = cA + (size_t)(t + 1) * kstep;
;             const char* a2 = last ? nA : cA + (size_t)(t + 2) * kstep; const char* b2 = last ? nB : cB + (size_t)(t + 2) * kstep;
;             const char* a3 = a2 + kstep; const char* b3 = b2 + kstep;
;             if constexpr (SP2) {
;             PG8_LDB(B0, 0, 0); PG8_LDB(B1, 0, 1); PG8_SCHED; PG8_LDA(At, 0, 0); PG8_STAGE(PG8_SA(1, 1), a1 + hstepA, voffA);
;             PG8_WAIT_V(8); PG8_WAIT_L(0); PG8_BAR; PG8_MMA(0, 0, At, B0); PG8_MMA(0, 1, At, B1); PG8_BAR; PG8_SCHED;
;     ...
; #pragma unroll
;         for (int a = 0; a < 2; ++a)
; #pragma unroll
;             for (int b = 0; b < 2; ++b)
; #pragma unroll
;                 for (int m = 0; m < 4; ++m)
; #pragma unroll
;                     for (int n = 0; n < 2; ++n) acc[a][b][m][n] = (f32x4){0.f, 0.f, 0.f, 0.f};
;         }
;         cur = nxt; cA = nA; cB = nB; ++ui;
.LBB0_944:
	s_add_u32 s36, s36, 0x80080
	s_addc_u32 s37, s37, 0
	s_add_u32 s1, s42, 0x100
	v_mov_b32_e32 v0, 0
	s_addc_u32 s25, s43, 0
	s_mov_b32 s61, -2
	v_mov_b32_e32 v1, v0
	s_waitcnt lgkmcnt(0)
	v_mov_b32_e32 v2, v0
	v_mov_b32_e32 v3, v0
	v_mov_b32_e32 v4, v0
	v_mov_b32_e32 v5, v0
	v_mov_b32_e32 v6, v0
	v_mov_b32_e32 v7, v0
	v_mov_b32_e32 v16, v0
	v_mov_b32_e32 v17, v0
	v_mov_b32_e32 v18, v0
	v_mov_b32_e32 v19, v0
	v_mov_b32_e32 v20, v0
	v_mov_b32_e32 v21, v0
	v_mov_b32_e32 v22, v0
	v_mov_b32_e32 v23, v0
	v_mov_b32_e32 v32, v0
	v_mov_b32_e32 v33, v0
	v_mov_b32_e32 v34, v0
	v_mov_b32_e32 v35, v0
	v_mov_b32_e32 v36, v0
	v_mov_b32_e32 v37, v0
	v_mov_b32_e32 v38, v0
	v_mov_b32_e32 v39, v0
	v_mov_b32_e32 v48, v0
	v_mov_b32_e32 v49, v0
	v_mov_b32_e32 v50, v0
	v_mov_b32_e32 v51, v0
	v_mov_b32_e32 v60, v0
	v_mov_b32_e32 v61, v0
	v_mov_b32_e32 v62, v0
	v_mov_b32_e32 v63, v0
	v_mov_b32_e32 v8, v0
	v_mov_b32_e32 v9, v0
	v_mov_b32_e32 v10, v0
	v_mov_b32_e32 v11, v0
	v_mov_b32_e32 v12, v0
	v_mov_b32_e32 v13, v0
	v_mov_b32_e32 v14, v0
	v_mov_b32_e32 v15, v0
	v_mov_b32_e32 v24, v0
	v_mov_b32_e32 v25, v0
	v_mov_b32_e32 v26, v0
	v_mov_b32_e32 v27, v0
	v_mov_b32_e32 v28, v0
	v_mov_b32_e32 v29, v0
	v_mov_b32_e32 v30, v0
	v_mov_b32_e32 v31, v0
	v_mov_b32_e32 v40, v0
	v_mov_b32_e32 v41, v0
	v_mov_b32_e32 v42, v0
	v_mov_b32_e32 v43, v0
	v_mov_b32_e32 v44, v0
	v_mov_b32_e32 v45, v0
	v_mov_b32_e32 v46, v0
	v_mov_b32_e32 v47, v0
	v_mov_b32_e32 v80, v0
	v_mov_b32_e32 v81, v0
	v_mov_b32_e32 v82, v0
	v_mov_b32_e32 v83, v0
	v_mov_b32_e32 v84, v0
	v_mov_b32_e32 v85, v0
	v_mov_b32_e32 v86, v0
	v_mov_b32_e32 v87, v0
	v_mov_b32_e32 v96, v0
	v_mov_b32_e32 v97, v0
	v_mov_b32_e32 v98, v0
	v_mov_b32_e32 v99, v0
	v_mov_b32_e32 v100, v0
	v_mov_b32_e32 v101, v0
	v_mov_b32_e32 v102, v0
	v_mov_b32_e32 v103, v0
	v_mov_b32_e32 v112, v0
	v_mov_b32_e32 v113, v0
	v_mov_b32_e32 v114, v0
	v_mov_b32_e32 v115, v0
	v_mov_b32_e32 v116, v0
	v_mov_b32_e32 v117, v0
	v_mov_b32_e32 v118, v0
	v_mov_b32_e32 v119, v0
	v_mov_b32_e32 v128, v0
	v_mov_b32_e32 v129, v0
	v_mov_b32_e32 v130, v0
	v_mov_b32_e32 v131, v0
	v_mov_b32_e32 v132, v0
	v_mov_b32_e32 v133, v0
	v_mov_b32_e32 v134, v0
	v_mov_b32_e32 v135, v0
	v_mov_b32_e32 v144, v0
	v_mov_b32_e32 v145, v0
	v_mov_b32_e32 v146, v0
	v_mov_b32_e32 v147, v0
	v_mov_b32_e32 v148, v0
	v_mov_b32_e32 v149, v0
	v_mov_b32_e32 v150, v0
	v_mov_b32_e32 v151, v0
	v_mov_b32_e32 v104, v0
	v_mov_b32_e32 v105, v0
	v_mov_b32_e32 v106, v0
	v_mov_b32_e32 v107, v0
	v_mov_b32_e32 v108, v0
	v_mov_b32_e32 v109, v0
	v_mov_b32_e32 v110, v0
	v_mov_b32_e32 v111, v0
	v_mov_b32_e32 v120, v0
	v_mov_b32_e32 v121, v0
	v_mov_b32_e32 v122, v0
	v_mov_b32_e32 v123, v0
	v_mov_b32_e32 v124, v0
	v_mov_b32_e32 v125, v0
	v_mov_b32_e32 v126, v0
	v_mov_b32_e32 v127, v0
	v_mov_b32_e32 v136, v0
	v_mov_b32_e32 v137, v0
	v_mov_b32_e32 v138, v0
	v_mov_b32_e32 v139, v0
	v_mov_b32_e32 v140, v0
	v_mov_b32_e32 v141, v0
	v_mov_b32_e32 v142, v0
	v_mov_b32_e32 v143, v0
	v_mov_b32_e32 v152, v0
	v_mov_b32_e32 v153, v0
	v_mov_b32_e32 v154, v0
	v_mov_b32_e32 v155, v0
	v_mov_b32_e32 v156, v0
	v_mov_b32_e32 v157, v0
	v_mov_b32_e32 v158, v0
	v_mov_b32_e32 v159, v0
	v_readlane_b32 s98, v255, 13
	s_nop 4
	s_cmp_lt_u32 s98, 4
	s_cbranch_scc1 .Lprio_skip_945
	s_setprio 1
.Lprio_skip_945:
.LBB0_945:
	ds_read_b128 v[52:55], v209
	ds_read_b128 v[56:59], v209 offset:1024
	ds_read_b128 v[64:67], v209 offset:2048
	ds_read_b128 v[68:71], v209 offset:3072
	ds_read_b128 v[72:75], v210
	ds_read_b128 v[76:79], v210 offset:1024
	ds_read_b128 v[88:91], v210 offset:2048
	ds_read_b128 v[92:95], v210 offset:3072
	s_add_u32 s42, s36, 0xfff80080
	s_addc_u32 s43, s37, -1
	s_cmp_eq_u32 s61, 28
	s_cselect_b32 s45, s27, s43
	s_cselect_b32 s44, s26, s42
	s_cselect_b32 s43, s29, s25
	s_cselect_b32 s42, s28, s1
	v_lshl_add_u64 v[206:207], s[36:37], 0, v[186:187]
	s_add_i32 m0, s21, 0xc000
	ds_read_b128 v[160:163], v211
	ds_read_b128 v[164:167], v211 offset:1024
	ds_read_b128 v[168:171], v211 offset:2048
	ds_read_b128 v[172:175], v211 offset:3072
	ds_read_b128 v[190:193], v211 offset:4096
	ds_read_b128 v[194:197], v211 offset:5120
	ds_read_b128 v[198:201], v211 offset:6144
	ds_read_b128 v[202:205], v211 offset:7168
	global_load_lds_dwordx4 v[206:207], off
	v_lshl_add_u64 v[206:207], s[36:37], 0, v[188:189]
	s_add_i32 m0, s21, 0xe000
	s_nop 0
	global_load_lds_dwordx4 v[206:207], off
	s_waitcnt vmcnt(8)
	s_waitcnt lgkmcnt(0)
	s_barrier
	s_waitcnt lgkmcnt(0)
	v_mfma_f32_16x16x32_bf16 v[156:159], v[52:55], v[160:163], v[156:159]
	v_mfma_f32_16x16x32_bf16 v[152:155], v[64:67], v[160:163], v[152:155]
	v_mfma_f32_16x16x32_bf16 v[140:143], v[52:55], v[168:171], v[140:143]
	v_mfma_f32_16x16x32_bf16 v[136:139], v[64:67], v[168:171], v[136:139]
	v_mfma_f32_16x16x32_bf16 v[124:127], v[52:55], v[190:193], v[124:127]
	v_mfma_f32_16x16x32_bf16 v[120:123], v[64:67], v[190:193], v[120:123]
	v_mfma_f32_16x16x32_bf16 v[108:111], v[52:55], v[198:201], v[108:111]
	v_mfma_f32_16x16x32_bf16 v[104:107], v[64:67], v[198:201], v[104:107]
	v_mfma_f32_16x16x32_bf16 v[156:159], v[56:59], v[164:167], v[156:159]
	v_mfma_f32_16x16x32_bf16 v[152:155], v[68:71], v[164:167], v[152:155]
	v_mfma_f32_16x16x32_bf16 v[140:143], v[56:59], v[172:175], v[140:143]
	v_mfma_f32_16x16x32_bf16 v[136:139], v[68:71], v[172:175], v[136:139]
	v_mfma_f32_16x16x32_bf16 v[124:127], v[56:59], v[194:197], v[124:127]
	v_mfma_f32_16x16x32_bf16 v[120:123], v[68:71], v[194:197], v[120:123]
	v_mfma_f32_16x16x32_bf16 v[108:111], v[56:59], v[202:205], v[108:111]
	v_mfma_f32_16x16x32_bf16 v[104:107], v[68:71], v[202:205], v[104:107]
	v_mfma_f32_16x16x32_bf16 v[148:151], v[72:75], v[160:163], v[148:151]
	v_mfma_f32_16x16x32_bf16 v[144:147], v[88:91], v[160:163], v[144:147]
	v_mfma_f32_16x16x32_bf16 v[132:135], v[72:75], v[168:171], v[132:135]
	v_mfma_f32_16x16x32_bf16 v[128:131], v[88:91], v[168:171], v[128:131]
	v_mfma_f32_16x16x32_bf16 v[116:119], v[72:75], v[190:193], v[116:119]
	v_mfma_f32_16x16x32_bf16 v[112:115], v[88:91], v[190:193], v[112:115]
	v_mfma_f32_16x16x32_bf16 v[100:103], v[72:75], v[198:201], v[100:103]
	v_mfma_f32_16x16x32_bf16 v[96:99], v[88:91], v[198:201], v[96:99]
	v_mfma_f32_16x16x32_bf16 v[148:151], v[76:79], v[164:167], v[148:151]
	v_mfma_f32_16x16x32_bf16 v[144:147], v[92:95], v[164:167], v[144:147]
	v_mfma_f32_16x16x32_bf16 v[132:135], v[76:79], v[172:175], v[132:135]
	v_mfma_f32_16x16x32_bf16 v[128:131], v[92:95], v[172:175], v[128:131]
	v_mfma_f32_16x16x32_bf16 v[116:119], v[76:79], v[194:197], v[116:119]
	v_mfma_f32_16x16x32_bf16 v[112:115], v[92:95], v[194:197], v[112:115]
	v_mfma_f32_16x16x32_bf16 v[100:103], v[76:79], v[202:205], v[100:103]
	v_mfma_f32_16x16x32_bf16 v[96:99], v[92:95], v[202:205], v[96:99]
	s_barrier
; #define PG8_STAGE(bufoff, gbase, voff) do { _Pragma("unroll") for (int _i = 0; _i < 2; ++_i) \
;         __builtin_amdgcn_global_load_lds((const unsigned*)((const char*)(gbase) + (voff)[_i]), (LAS unsigned*)(lds + (bufoff) + ldsw + _i * 8192), 16, 0, 0); } while (0)
; #define PG8_LDA(dst, b, h) do { _Pragma("unroll") for (int m = 0; m < 4; ++m) _Pragma("unroll") for (int k = 0; k < 2; ++k) dst[m][k] = *(const LAS bf16x8*)(lds + PG8_SA(b, h) + aoff + m * 2048 + k * 1024); } while (0)
; #define PG8_LDB(dst, b, h) do { _Pragma("unroll") for (int n = 0; n < 2; ++n) _Pragma("unroll") for (int k = 0; k < 2; ++k) dst[n][k] = *(const LAS bf16x8*)(lds + PG8_SB(b, h) + boff + n * 2048 + k * 1024); } while (0)
; #define PG8_MMA(ai, bj, At, Bt) do { __builtin_amdgcn_s_setprio(1); _Pragma("unroll") for (int m = 0; m < 4; ++m) _Pragma("unroll") for (int n = 0; n < 2; ++n) _Pragma("unroll") for (int k = 0; k < 2; ++k) \
;         acc[ai][bj][m][n] = __builtin_amdgcn_mfma_f32_16x16x32_bf16(Bt[n][k], At[m][k], acc[ai][bj][m][n], 0, 0, 0); __builtin_amdgcn_s_setprio(0); } while (0)
; #define PG8_WAIT_V(n) asm volatile("s_waitcnt vmcnt(" #n ")" ::: "memory")
; #define PG8_WAIT_L(n) asm volatile("s_waitcnt lgkmcnt(" #n ")" ::: "memory")
; #define PG8_BAR __builtin_amdgcn_s_barrier()
; #define PG8_SCHED __builtin_amdgcn_sched_barrier(0)
; template <class Sched, class Epi, bool ALIGN_EPI, bool SP2>
; __device__ __forceinline__ void gemm_phase(LAS unsigned char* lds, const int K, const int lda, const int ldb, const Sched& S, const Epi& E) {
;     ...
;             PG8_LDA(At, 0, 1); PG8_STAGE(PG8_SB(0, 0), b2, voffB); PG8_STAGE(PG8_SB(0, 1), b2 + hstepB, voffB); PG8_STAGE(PG8_SA(0, 0), a2, voffA);
;             PG8_WAIT_V(8); PG8_WAIT_L(0); PG8_BAR; PG8_MMA(1, 0, At, B0); PG8_MMA(1, 1, At, B1); PG8_BAR; PG8_SCHED;
;             PG8_LDB(B0, 1, 0); PG8_LDB(B1, 1, 1); PG8_SCHED; PG8_LDA(At, 1, 0); PG8_STAGE(PG8_SA(0, 1), a2 + hstepA, voffA);
	s_add_i32 s62, s50, s19
	v_lshl_add_u64 v[206:207], s[42:43], 0, v[182:183]
	s_mov_b32 m0, s62
	ds_read_b128 v[160:163], v211 offset:16384
	ds_read_b128 v[164:167], v211 offset:17408
	ds_read_b128 v[168:171], v211 offset:18432
	ds_read_b128 v[172:175], v211 offset:19456
	ds_read_b128 v[190:193], v211 offset:20480
	ds_read_b128 v[194:197], v211 offset:21504
	ds_read_b128 v[198:201], v211 offset:22528
	ds_read_b128 v[202:205], v211 offset:23552
	global_load_lds_dwordx4 v[206:207], off
	s_add_i32 m0, s62, 0x2000
	s_add_u32 s62, s42, 0x80000
	v_lshl_add_u64 v[214:215], s[42:43], 0, v[184:185]
	s_addc_u32 s63, s43, 0
	s_add_i32 s64, s51, s19
	global_load_lds_dwordx4 v[214:215], off
	v_lshl_add_u64 v[216:217], s[62:63], 0, v[182:183]
	s_mov_b32 m0, s64
	v_lshl_add_u64 v[218:219], s[44:45], 0, v[184:185]
	global_load_lds_dwordx4 v[216:217], off
	v_lshl_add_u64 v[216:217], s[62:63], 0, v[184:185]
	s_add_i32 m0, s64, 0x2000
	s_nop 0
	global_load_lds_dwordx4 v[216:217], off
	v_lshl_add_u64 v[216:217], s[44:45], 0, v[182:183]
	s_mov_b32 m0, s21
	s_nop 0
	global_load_lds_dwordx4 v[216:217], off
	s_mov_b32 m0, s33
	s_nop 0
	global_load_lds_dwordx4 v[218:219], off
	s_waitcnt vmcnt(8)
	s_waitcnt lgkmcnt(0)
	s_barrier
	s_waitcnt lgkmcnt(0)
	v_mfma_f32_16x16x32_bf16 v[84:87], v[52:55], v[160:163], v[84:87]
	v_mfma_f32_16x16x32_bf16 v[80:83], v[64:67], v[160:163], v[80:83]
	v_mfma_f32_16x16x32_bf16 v[44:47], v[52:55], v[168:171], v[44:47]
	v_mfma_f32_16x16x32_bf16 v[40:43], v[64:67], v[168:171], v[40:43]
	v_mfma_f32_16x16x32_bf16 v[28:31], v[52:55], v[190:193], v[28:31]
	v_mfma_f32_16x16x32_bf16 v[24:27], v[64:67], v[190:193], v[24:27]
	v_mfma_f32_16x16x32_bf16 v[12:15], v[52:55], v[198:201], v[12:15]
	v_mfma_f32_16x16x32_bf16 v[8:11], v[64:67], v[198:201], v[8:11]
	v_mfma_f32_16x16x32_bf16 v[84:87], v[56:59], v[164:167], v[84:87]
	v_mfma_f32_16x16x32_bf16 v[80:83], v[68:71], v[164:167], v[80:83]
	v_mfma_f32_16x16x32_bf16 v[44:47], v[56:59], v[172:175], v[44:47]
	v_mfma_f32_16x16x32_bf16 v[40:43], v[68:71], v[172:175], v[40:43]
	v_mfma_f32_16x16x32_bf16 v[28:31], v[56:59], v[194:197], v[28:31]
	v_mfma_f32_16x16x32_bf16 v[24:27], v[68:71], v[194:197], v[24:27]
	v_mfma_f32_16x16x32_bf16 v[12:15], v[56:59], v[202:205], v[12:15]
	v_mfma_f32_16x16x32_bf16 v[8:11], v[68:71], v[202:205], v[8:11]
	v_mfma_f32_16x16x32_bf16 v[48:51], v[88:91], v[160:163], v[48:51]
	v_mfma_f32_16x16x32_bf16 v[36:39], v[72:75], v[168:171], v[36:39]
	v_mfma_f32_16x16x32_bf16 v[32:35], v[88:91], v[168:171], v[32:35]
	v_mfma_f32_16x16x32_bf16 v[20:23], v[72:75], v[190:193], v[20:23]
	v_mfma_f32_16x16x32_bf16 v[16:19], v[88:91], v[190:193], v[16:19]
	v_mfma_f32_16x16x32_bf16 v[4:7], v[72:75], v[198:201], v[4:7]
	v_mfma_f32_16x16x32_bf16 v[0:3], v[88:91], v[198:201], v[0:3]
	v_mfma_f32_16x16x32_bf16 v[52:55], v[72:75], v[160:163], v[60:63]
	v_mfma_f32_16x16x32_bf16 v[48:51], v[92:95], v[164:167], v[48:51]
	v_mfma_f32_16x16x32_bf16 v[36:39], v[76:79], v[172:175], v[36:39]
	v_mfma_f32_16x16x32_bf16 v[32:35], v[92:95], v[172:175], v[32:35]
	v_mfma_f32_16x16x32_bf16 v[20:23], v[76:79], v[194:197], v[20:23]
	v_mfma_f32_16x16x32_bf16 v[16:19], v[92:95], v[194:197], v[16:19]
	v_mfma_f32_16x16x32_bf16 v[4:7], v[76:79], v[202:205], v[4:7]
	v_mfma_f32_16x16x32_bf16 v[0:3], v[92:95], v[202:205], v[0:3]
	v_mfma_f32_16x16x32_bf16 v[52:55], v[76:79], v[164:167], v[52:55]
	s_barrier
	s_add_i32 s62, 0, 0x18000
	s_add_i32 s63, 0, 0x1c000
	v_add_u32_e32 v68, s62, v181
	v_add_u32_e32 v92, s63, v181
	ds_read_b128 v[56:59], v68
	ds_read_b128 v[60:63], v68 offset:1024
	ds_read_b128 v[64:67], v68 offset:2048
	ds_read_b128 v[68:71], v68 offset:3072
	ds_read_b128 v[72:75], v92
	ds_read_b128 v[76:79], v92 offset:1024
	ds_read_b128 v[88:91], v92 offset:2048
	ds_read_b128 v[92:95], v92 offset:3072
	s_add_u32 s44, s44, 0x80000
	s_addc_u32 s45, s45, 0
	s_mov_b32 m0, s35
	v_lshl_add_u64 v[220:221], s[44:45], 0, v[182:183]
	ds_read_b128 v[160:163], v211 offset:32768
	ds_read_b128 v[164:167], v211 offset:33792
	ds_read_b128 v[168:171], v211 offset:34816
	ds_read_b128 v[172:175], v211 offset:35840
	ds_read_b128 v[190:193], v211 offset:36864
	ds_read_b128 v[194:197], v211 offset:37888
	ds_read_b128 v[198:201], v211 offset:38912
	ds_read_b128 v[202:205], v211 offset:39936
	global_load_lds_dwordx4 v[220:221], off
	v_lshl_add_u64 v[220:221], s[44:45], 0, v[184:185]
	s_mov_b32 m0, s46
	s_nop 0
	global_load_lds_dwordx4 v[220:221], off
	s_waitcnt vmcnt(8)
	s_waitcnt lgkmcnt(0)
	s_barrier
; #define PG8_STAGE(bufoff, gbase, voff) do { _Pragma("unroll") for (int _i = 0; _i < 2; ++_i) \
;         __builtin_amdgcn_global_load_lds((const unsigned*)((const char*)(gbase) + (voff)[_i]), (LAS unsigned*)(lds + (bufoff) + ldsw + _i * 8192), 16, 0, 0); } while (0)
; #define PG8_LDA(dst, b, h) do { _Pragma("unroll") for (int m = 0; m < 4; ++m) _Pragma("unroll") for (int k = 0; k < 2; ++k) dst[m][k] = *(const LAS bf16x8*)(lds + PG8_SA(b, h) + aoff + m * 2048 + k * 1024); } while (0)
; #define PG8_MMA(ai, bj, At, Bt) do { __builtin_amdgcn_s_setprio(1); _Pragma("unroll") for (int m = 0; m < 4; ++m) _Pragma("unroll") for (int n = 0; n < 2; ++n) _Pragma("unroll") for (int k = 0; k < 2; ++k) \
;         acc[ai][bj][m][n] = __builtin_amdgcn_mfma_f32_16x16x32_bf16(Bt[n][k], At[m][k], acc[ai][bj][m][n], 0, 0, 0); __builtin_amdgcn_s_setprio(0); } while (0)
; #define PG8_WAIT_V(n) asm volatile("s_waitcnt vmcnt(" #n ")" ::: "memory")
; #define PG8_WAIT_L(n) asm volatile("s_waitcnt lgkmcnt(" #n ")" ::: "memory")
; #define PG8_BAR __builtin_amdgcn_s_barrier()
; #define PG8_SCHED __builtin_amdgcn_sched_barrier(0)
; template <class Sched, class Epi, bool ALIGN_EPI, bool SP2>
; __device__ __forceinline__ void gemm_phase(LAS unsigned char* lds, const int K, const int lda, const int ldb, const Sched& S, const Epi& E) {
;     ...
;         for (int t = 0; t < nt; t += 2) {
;             const bool last = (t == nt - 2);
;             const char* a1 = cA + (size_t)(t + 1) * kstep;
;             const char* a2 = last ? nA : cA + (size_t)(t + 2) * kstep; const char* b2 = last ? nB : cB + (size_t)(t + 2) * kstep;
;     ...
;             PG8_WAIT_V(8); PG8_WAIT_L(0); PG8_BAR; PG8_MMA(0, 0, At, B0); PG8_MMA(0, 1, At, B1); PG8_BAR; PG8_SCHED;
;             PG8_LDA(At, 1, 1); PG8_STAGE(PG8_SB(1, 0), b3, voffB); PG8_STAGE(PG8_SB(1, 1), b3 + hstepB, voffB); PG8_STAGE(PG8_SA(1, 0), a3, voffA);
;             PG8_WAIT_V(8); PG8_WAIT_L(0); PG8_BAR; PG8_MMA(1, 0, At, B0); PG8_MMA(1, 1, At, B1); PG8_BAR; PG8_SCHED;
	s_waitcnt lgkmcnt(0)
	v_mfma_f32_16x16x32_bf16 v[156:159], v[56:59], v[160:163], v[156:159]
	v_mfma_f32_16x16x32_bf16 v[152:155], v[64:67], v[160:163], v[152:155]
	v_mfma_f32_16x16x32_bf16 v[140:143], v[56:59], v[168:171], v[140:143]
	v_mfma_f32_16x16x32_bf16 v[136:139], v[64:67], v[168:171], v[136:139]
	v_mfma_f32_16x16x32_bf16 v[124:127], v[56:59], v[190:193], v[124:127]
	v_mfma_f32_16x16x32_bf16 v[120:123], v[64:67], v[190:193], v[120:123]
	v_mfma_f32_16x16x32_bf16 v[108:111], v[56:59], v[198:201], v[108:111]
	v_mfma_f32_16x16x32_bf16 v[104:107], v[64:67], v[198:201], v[104:107]
	v_mfma_f32_16x16x32_bf16 v[156:159], v[60:63], v[164:167], v[156:159]
	v_mfma_f32_16x16x32_bf16 v[152:155], v[68:71], v[164:167], v[152:155]
	v_mfma_f32_16x16x32_bf16 v[140:143], v[60:63], v[172:175], v[140:143]
	v_mfma_f32_16x16x32_bf16 v[136:139], v[68:71], v[172:175], v[136:139]
	v_mfma_f32_16x16x32_bf16 v[124:127], v[60:63], v[194:197], v[124:127]
	v_mfma_f32_16x16x32_bf16 v[120:123], v[68:71], v[194:197], v[120:123]
	v_mfma_f32_16x16x32_bf16 v[108:111], v[60:63], v[202:205], v[108:111]
	v_mfma_f32_16x16x32_bf16 v[104:107], v[68:71], v[202:205], v[104:107]
	v_mfma_f32_16x16x32_bf16 v[148:151], v[72:75], v[160:163], v[148:151]
	v_mfma_f32_16x16x32_bf16 v[144:147], v[88:91], v[160:163], v[144:147]
	v_mfma_f32_16x16x32_bf16 v[132:135], v[72:75], v[168:171], v[132:135]
	v_mfma_f32_16x16x32_bf16 v[128:131], v[88:91], v[168:171], v[128:131]
	v_mfma_f32_16x16x32_bf16 v[116:119], v[72:75], v[190:193], v[116:119]
	v_mfma_f32_16x16x32_bf16 v[112:115], v[88:91], v[190:193], v[112:115]
	v_mfma_f32_16x16x32_bf16 v[100:103], v[72:75], v[198:201], v[100:103]
	v_mfma_f32_16x16x32_bf16 v[96:99], v[88:91], v[198:201], v[96:99]
	v_mfma_f32_16x16x32_bf16 v[148:151], v[76:79], v[164:167], v[148:151]
	v_mfma_f32_16x16x32_bf16 v[144:147], v[92:95], v[164:167], v[144:147]
	v_mfma_f32_16x16x32_bf16 v[132:135], v[76:79], v[172:175], v[132:135]
	v_mfma_f32_16x16x32_bf16 v[128:131], v[92:95], v[172:175], v[128:131]
	v_mfma_f32_16x16x32_bf16 v[116:119], v[76:79], v[194:197], v[116:119]
	v_mfma_f32_16x16x32_bf16 v[112:115], v[92:95], v[194:197], v[112:115]
	v_mfma_f32_16x16x32_bf16 v[100:103], v[76:79], v[202:205], v[100:103]
	v_mfma_f32_16x16x32_bf16 v[96:99], v[92:95], v[202:205], v[96:99]
	s_barrier
	s_add_i32 s44, s62, s19
	v_lshl_add_u64 v[206:207], v[206:207], 0, s[14:15]
	s_mov_b32 m0, s44
	ds_read_b128 v[160:163], v211 offset:49152
	ds_read_b128 v[164:167], v211 offset:50176
	ds_read_b128 v[168:171], v211 offset:51200
	ds_read_b128 v[172:175], v211 offset:52224
	ds_read_b128 v[190:193], v211 offset:53248
	ds_read_b128 v[194:197], v211 offset:54272
	ds_read_b128 v[198:201], v211 offset:55296
	ds_read_b128 v[202:205], v211 offset:56320
	global_load_lds_dwordx4 v[206:207], off
	s_add_i32 m0, s44, 0x2000
	s_add_u32 s42, s42, 0x80080
	v_lshl_add_u64 v[206:207], v[214:215], 0, s[14:15]
	s_addc_u32 s43, s43, 0
	s_add_i32 s44, s63, s19
	global_load_lds_dwordx4 v[206:207], off
	v_lshl_add_u64 v[206:207], s[42:43], 0, v[182:183]
	s_mov_b32 m0, s44
	s_nop 0
	global_load_lds_dwordx4 v[206:207], off
	v_lshl_add_u64 v[206:207], s[42:43], 0, v[184:185]
	s_add_i32 m0, s44, 0x2000
	s_nop 0
	global_load_lds_dwordx4 v[206:207], off
	v_lshl_add_u64 v[206:207], v[216:217], 0, s[14:15]
	s_mov_b32 m0, s48
	s_nop 0
	global_load_lds_dwordx4 v[206:207], off
	v_lshl_add_u64 v[206:207], v[218:219], 0, s[14:15]
	s_mov_b32 m0, s49
	s_nop 0
	global_load_lds_dwordx4 v[206:207], off
	s_waitcnt vmcnt(8)
	s_waitcnt lgkmcnt(0)
	s_barrier
	s_waitcnt lgkmcnt(0)
	v_mfma_f32_16x16x32_bf16 v[84:87], v[56:59], v[160:163], v[84:87]
	v_mfma_f32_16x16x32_bf16 v[80:83], v[64:67], v[160:163], v[80:83]
	v_mfma_f32_16x16x32_bf16 v[44:47], v[56:59], v[168:171], v[44:47]
	v_mfma_f32_16x16x32_bf16 v[40:43], v[64:67], v[168:171], v[40:43]
	v_mfma_f32_16x16x32_bf16 v[28:31], v[56:59], v[190:193], v[28:31]
	v_mfma_f32_16x16x32_bf16 v[24:27], v[64:67], v[190:193], v[24:27]
	v_mfma_f32_16x16x32_bf16 v[12:15], v[56:59], v[198:201], v[12:15]
	v_mfma_f32_16x16x32_bf16 v[8:11], v[64:67], v[198:201], v[8:11]
	v_mfma_f32_16x16x32_bf16 v[84:87], v[60:63], v[164:167], v[84:87]
	v_mfma_f32_16x16x32_bf16 v[80:83], v[68:71], v[164:167], v[80:83]
	v_mfma_f32_16x16x32_bf16 v[44:47], v[60:63], v[172:175], v[44:47]
	v_mfma_f32_16x16x32_bf16 v[40:43], v[68:71], v[172:175], v[40:43]
	v_mfma_f32_16x16x32_bf16 v[28:31], v[60:63], v[194:197], v[28:31]
	v_mfma_f32_16x16x32_bf16 v[24:27], v[68:71], v[194:197], v[24:27]
	v_mfma_f32_16x16x32_bf16 v[12:15], v[60:63], v[202:205], v[12:15]
	v_mfma_f32_16x16x32_bf16 v[8:11], v[68:71], v[202:205], v[8:11]
	v_mfma_f32_16x16x32_bf16 v[52:55], v[72:75], v[160:163], v[52:55]
	v_mfma_f32_16x16x32_bf16 v[48:51], v[88:91], v[160:163], v[48:51]
	v_mfma_f32_16x16x32_bf16 v[36:39], v[72:75], v[168:171], v[36:39]
	v_mfma_f32_16x16x32_bf16 v[32:35], v[88:91], v[168:171], v[32:35]
	v_mfma_f32_16x16x32_bf16 v[20:23], v[72:75], v[190:193], v[20:23]
	v_mfma_f32_16x16x32_bf16 v[16:19], v[88:91], v[190:193], v[16:19]
	v_mfma_f32_16x16x32_bf16 v[4:7], v[72:75], v[198:201], v[4:7]
	v_mfma_f32_16x16x32_bf16 v[0:3], v[88:91], v[198:201], v[0:3]
	v_mfma_f32_16x16x32_bf16 v[60:63], v[76:79], v[164:167], v[52:55]
	v_mfma_f32_16x16x32_bf16 v[48:51], v[92:95], v[164:167], v[48:51]
	v_mfma_f32_16x16x32_bf16 v[36:39], v[76:79], v[172:175], v[36:39]
	v_mfma_f32_16x16x32_bf16 v[32:35], v[92:95], v[172:175], v[32:35]
	v_mfma_f32_16x16x32_bf16 v[20:23], v[76:79], v[194:197], v[20:23]
	v_mfma_f32_16x16x32_bf16 v[16:19], v[92:95], v[194:197], v[16:19]
	v_mfma_f32_16x16x32_bf16 v[4:7], v[76:79], v[202:205], v[4:7]
	v_mfma_f32_16x16x32_bf16 v[0:3], v[92:95], v[202:205], v[0:3]
	s_barrier
	s_add_i32 s61, s61, 2
	s_add_u32 s36, s36, 0x100
	s_addc_u32 s37, s37, 0
	s_add_u32 s1, s1, 0x100
	s_addc_u32 s25, s25, 0
	s_cmp_gt_u32 s61, 29
	s_cbranch_scc0 .LBB0_945
	s_setprio 0
	s_and_b64 vcc, exec, s[16:17]
	s_cbranch_vccz .LBB0_948
	s_barrier

; #define PG8_STAGE(bufoff, gbase, voff) do { _Pragma("unroll") for (int _i = 0; _i < 2; ++_i) \
;         __builtin_amdgcn_global_load_lds((const unsigned*)((const char*)(gbase) + (voff)[_i]), (LAS unsigned*)(lds + (bufoff) + ldsw + _i * 8192), 16, 0, 0); } while (0)
; #define PG8_LDA(dst, b, h) do { _Pragma("unroll") for (int m = 0; m < 4; ++m) _Pragma("unroll") for (int k = 0; k < 2; ++k) dst[m][k] = *(const LAS bf16x8*)(lds + PG8_SA(b, h) + aoff + m * 2048 + k * 1024); } while (0)
; #define PG8_LDB(dst, b, h) do { _Pragma("unroll") for (int n = 0; n < 2; ++n) _Pragma("unroll") for (int k = 0; k < 2; ++k) dst[n][k] = *(const LAS bf16x8*)(lds + PG8_SB(b, h) + boff + n * 2048 + k * 1024); } while (0)
; #define PG8_MMA(ai, bj, At, Bt) do { __builtin_amdgcn_s_setprio(1); _Pragma("unroll") for (int m = 0; m < 4; ++m) _Pragma("unroll") for (int n = 0; n < 2; ++n) _Pragma("unroll") for (int k = 0; k < 2; ++k) \
;         acc[ai][bj][m][n] = __builtin_amdgcn_mfma_f32_16x16x32_bf16(Bt[n][k], At[m][k], acc[ai][bj][m][n], 0, 0, 0); __builtin_amdgcn_s_setprio(0); } while (0)
; #define PG8_WAIT_V(n) asm volatile("s_waitcnt vmcnt(" #n ")" ::: "memory")
; template <class Sched, class Epi, bool ALIGN_EPI, bool SP2>
; __device__ __forceinline__ void gemm_phase(LAS unsigned char* lds, const int K, const int lda, const int ldb, const Sched& S, const Epi& E) {
;     ...
;         for (int t = 0; t < nt; t += 2) {
;             const bool last = (t == nt - 2);
;             const char* a1 = cA + (size_t)(t + 1) * kstep;
;             const char* a2 = last ? nA : cA + (size_t)(t + 2) * kstep; const char* b2 = last ? nB : cB + (size_t)(t + 2) * kstep;
;             const char* a3 = a2 + kstep; const char* b3 = b2 + kstep;
;             if constexpr (SP2) {
;             PG8_LDB(B0, 0, 0); PG8_LDB(B1, 0, 1); PG8_SCHED; PG8_LDA(At, 0, 0); PG8_STAGE(PG8_SA(1, 1), a1 + hstepA, voffA);
;             PG8_WAIT_V(8); PG8_WAIT_L(0); PG8_BAR; PG8_MMA(0, 0, At, B0); PG8_MMA(0, 1, At, B1); PG8_BAR; PG8_SCHED;
;     ...
;         if (!keep) {
; #pragma unroll
;         for (int a = 0; a < 2; ++a)
; #pragma unroll
;             for (int b = 0; b < 2; ++b)
; #pragma unroll
;                 for (int m = 0; m < 4; ++m)
; #pragma unroll
;                     for (int n = 0; n < 2; ++n) acc[a][b][m][n] = (f32x4){0.f, 0.f, 0.f, 0.f};
;         }
;         cur = nxt; cA = nA; cB = nB; ++ui;
.LBB0_1036:
	s_add_u32 s36, s36, 0x80080
	s_addc_u32 s37, s37, 0
	s_add_u32 s25, s42, 0x100
	v_mov_b32_e32 v4, 0
	s_addc_u32 s56, s43, 0
	s_mov_b32 s57, -2
	v_mov_b32_e32 v5, v4
	v_mov_b32_e32 v6, v4
	v_mov_b32_e32 v7, v4
	v_mov_b32_e32 v12, v4
	v_mov_b32_e32 v13, v4
	v_mov_b32_e32 v14, v4
	v_mov_b32_e32 v15, v4
	v_mov_b32_e32 v16, v4
	v_mov_b32_e32 v17, v4
	v_mov_b32_e32 v18, v4
	v_mov_b32_e32 v19, v4
	v_mov_b32_e32 v28, v4
	v_mov_b32_e32 v29, v4
	v_mov_b32_e32 v30, v4
	v_mov_b32_e32 v31, v4
	v_mov_b32_e32 v32, v4
	v_mov_b32_e32 v33, v4
	v_mov_b32_e32 v34, v4
	v_mov_b32_e32 v35, v4
	v_mov_b32_e32 v36, v4
	v_mov_b32_e32 v37, v4
	v_mov_b32_e32 v38, v4
	v_mov_b32_e32 v39, v4
	v_mov_b32_e32 v48, v4
	v_mov_b32_e32 v49, v4
	v_mov_b32_e32 v50, v4
	v_mov_b32_e32 v51, v4
	v_mov_b32_e32 v52, v4
	v_mov_b32_e32 v53, v4
	v_mov_b32_e32 v54, v4
	v_mov_b32_e32 v55, v4
	v_mov_b32_e32 v0, v4
	v_mov_b32_e32 v1, v4
	v_mov_b32_e32 v2, v4
	v_mov_b32_e32 v3, v4
	v_mov_b32_e32 v8, v4
	v_mov_b32_e32 v9, v4
	v_mov_b32_e32 v10, v4
	v_mov_b32_e32 v11, v4
	v_mov_b32_e32 v20, v4
	v_mov_b32_e32 v21, v4
	v_mov_b32_e32 v22, v4
	v_mov_b32_e32 v23, v4
	v_mov_b32_e32 v24, v4
	v_mov_b32_e32 v25, v4
	v_mov_b32_e32 v26, v4
	v_mov_b32_e32 v27, v4
	v_mov_b32_e32 v40, v4
	v_mov_b32_e32 v41, v4
	v_mov_b32_e32 v42, v4
	v_mov_b32_e32 v43, v4
	v_mov_b32_e32 v44, v4
	v_mov_b32_e32 v45, v4
	v_mov_b32_e32 v46, v4
	v_mov_b32_e32 v47, v4
	v_mov_b32_e32 v56, v4
	v_mov_b32_e32 v57, v4
	v_mov_b32_e32 v58, v4
	v_mov_b32_e32 v59, v4
	v_mov_b32_e32 v60, v4
	v_mov_b32_e32 v61, v4
	v_mov_b32_e32 v62, v4
	v_mov_b32_e32 v63, v4
	v_mov_b32_e32 v80, v4
	v_mov_b32_e32 v81, v4
	v_mov_b32_e32 v82, v4
	v_mov_b32_e32 v83, v4
	v_mov_b32_e32 v84, v4
	v_mov_b32_e32 v85, v4
	v_mov_b32_e32 v86, v4
	v_mov_b32_e32 v87, v4
	v_mov_b32_e32 v96, v4
	v_mov_b32_e32 v97, v4
	v_mov_b32_e32 v98, v4
	v_mov_b32_e32 v99, v4
	v_mov_b32_e32 v100, v4
	v_mov_b32_e32 v101, v4
	v_mov_b32_e32 v102, v4
	v_mov_b32_e32 v103, v4
	v_mov_b32_e32 v112, v4
	v_mov_b32_e32 v113, v4
	v_mov_b32_e32 v114, v4
	v_mov_b32_e32 v115, v4
	v_mov_b32_e32 v116, v4
	v_mov_b32_e32 v117, v4
	v_mov_b32_e32 v118, v4
	v_mov_b32_e32 v119, v4
	v_mov_b32_e32 v128, v4
	v_mov_b32_e32 v129, v4
	v_mov_b32_e32 v130, v4
	v_mov_b32_e32 v131, v4
	v_mov_b32_e32 v132, v4
	v_mov_b32_e32 v133, v4
	v_mov_b32_e32 v134, v4
	v_mov_b32_e32 v135, v4
	v_mov_b32_e32 v88, v4
	v_mov_b32_e32 v89, v4
	v_mov_b32_e32 v90, v4
	v_mov_b32_e32 v91, v4
	v_mov_b32_e32 v92, v4
	v_mov_b32_e32 v93, v4
	v_mov_b32_e32 v94, v4
	v_mov_b32_e32 v95, v4
	v_mov_b32_e32 v104, v4
	v_mov_b32_e32 v105, v4
	v_mov_b32_e32 v106, v4
	v_mov_b32_e32 v107, v4
	v_mov_b32_e32 v108, v4
	v_mov_b32_e32 v109, v4
	v_mov_b32_e32 v110, v4
	v_mov_b32_e32 v111, v4
	v_mov_b32_e32 v120, v4
	v_mov_b32_e32 v121, v4
	v_mov_b32_e32 v122, v4
	v_mov_b32_e32 v123, v4
	v_mov_b32_e32 v124, v4
	v_mov_b32_e32 v125, v4
	v_mov_b32_e32 v126, v4
	v_mov_b32_e32 v127, v4
	v_mov_b32_e32 v136, v4
	v_mov_b32_e32 v137, v4
	v_mov_b32_e32 v138, v4
	v_mov_b32_e32 v139, v4
	v_mov_b32_e32 v140, v4
	v_mov_b32_e32 v141, v4
	v_mov_b32_e32 v142, v4
	v_mov_b32_e32 v143, v4
	v_readlane_b32 s98, v255, 13
	s_nop 4
	s_cmp_lt_u32 s98, 4
	s_cbranch_scc1 .Lprio_skip_1037
	s_setprio 1
.Lprio_skip_1037:
.LBB0_1037:
	ds_read_b128 v[64:67], v183
	ds_read_b128 v[68:71], v183 offset:1024
	ds_read_b128 v[72:75], v183 offset:2048
	ds_read_b128 v[76:79], v183 offset:3072
	ds_read_b128 v[144:147], v184
	ds_read_b128 v[160:163], v184 offset:1024
	ds_read_b128 v[164:167], v184 offset:2048
	ds_read_b128 v[168:171], v184 offset:3072
	s_add_u32 s42, s36, 0xfff80080
	s_addc_u32 s43, s37, -1
	s_cmp_eq_u32 s57, 28
	s_cselect_b32 s45, s27, s43
	s_cselect_b32 s44, s26, s42
	s_cselect_b32 s43, s29, s56
	s_cselect_b32 s42, s28, s25
	v_lshl_add_u64 v[216:217], s[36:37], 0, v[156:157]
	s_add_i32 m0, s33, 0xc000
	ds_read_b128 v[172:175], v185
	ds_read_b128 v[188:191], v185 offset:1024
	ds_read_b128 v[192:195], v185 offset:2048
	ds_read_b128 v[196:199], v185 offset:3072
	ds_read_b128 v[200:203], v185 offset:4096
	ds_read_b128 v[204:207], v185 offset:5120
	ds_read_b128 v[208:211], v185 offset:6144
	ds_read_b128 v[212:215], v185 offset:7168
	global_load_lds_dwordx4 v[216:217], off
	v_lshl_add_u64 v[216:217], s[36:37], 0, v[158:159]
	s_add_i32 m0, s33, 0xe000
	s_nop 0
	global_load_lds_dwordx4 v[216:217], off
	s_waitcnt vmcnt(8)
	s_waitcnt lgkmcnt(0)
	s_barrier
	s_waitcnt lgkmcnt(0)
	v_mfma_f32_16x16x32_bf16 v[140:143], v[64:67], v[172:175], v[140:143]
	v_mfma_f32_16x16x32_bf16 v[136:139], v[72:75], v[172:175], v[136:139]
	v_mfma_f32_16x16x32_bf16 v[124:127], v[64:67], v[192:195], v[124:127]
	v_mfma_f32_16x16x32_bf16 v[120:123], v[72:75], v[192:195], v[120:123]
	v_mfma_f32_16x16x32_bf16 v[108:111], v[64:67], v[200:203], v[108:111]
	v_mfma_f32_16x16x32_bf16 v[104:107], v[72:75], v[200:203], v[104:107]
	v_mfma_f32_16x16x32_bf16 v[92:95], v[64:67], v[208:211], v[92:95]
	v_mfma_f32_16x16x32_bf16 v[88:91], v[72:75], v[208:211], v[88:91]
	v_mfma_f32_16x16x32_bf16 v[140:143], v[68:71], v[188:191], v[140:143]
	v_mfma_f32_16x16x32_bf16 v[136:139], v[76:79], v[188:191], v[136:139]
	v_mfma_f32_16x16x32_bf16 v[124:127], v[68:71], v[196:199], v[124:127]
	v_mfma_f32_16x16x32_bf16 v[120:123], v[76:79], v[196:199], v[120:123]
	v_mfma_f32_16x16x32_bf16 v[108:111], v[68:71], v[204:207], v[108:111]
	v_mfma_f32_16x16x32_bf16 v[104:107], v[76:79], v[204:207], v[104:107]
	v_mfma_f32_16x16x32_bf16 v[92:95], v[68:71], v[212:215], v[92:95]
	v_mfma_f32_16x16x32_bf16 v[88:91], v[76:79], v[212:215], v[88:91]
	v_mfma_f32_16x16x32_bf16 v[132:135], v[144:147], v[172:175], v[132:135]
	v_mfma_f32_16x16x32_bf16 v[128:131], v[164:167], v[172:175], v[128:131]
	v_mfma_f32_16x16x32_bf16 v[116:119], v[144:147], v[192:195], v[116:119]
	v_mfma_f32_16x16x32_bf16 v[112:115], v[164:167], v[192:195], v[112:115]
	v_mfma_f32_16x16x32_bf16 v[100:103], v[144:147], v[200:203], v[100:103]
	v_mfma_f32_16x16x32_bf16 v[96:99], v[164:167], v[200:203], v[96:99]
	v_mfma_f32_16x16x32_bf16 v[84:87], v[144:147], v[208:211], v[84:87]
	v_mfma_f32_16x16x32_bf16 v[80:83], v[164:167], v[208:211], v[80:83]
	v_mfma_f32_16x16x32_bf16 v[132:135], v[160:163], v[188:191], v[132:135]
	v_mfma_f32_16x16x32_bf16 v[128:131], v[168:171], v[188:191], v[128:131]
	v_mfma_f32_16x16x32_bf16 v[116:119], v[160:163], v[196:199], v[116:119]
	v_mfma_f32_16x16x32_bf16 v[112:115], v[168:171], v[196:199], v[112:115]
	v_mfma_f32_16x16x32_bf16 v[100:103], v[160:163], v[204:207], v[100:103]
	v_mfma_f32_16x16x32_bf16 v[96:99], v[168:171], v[204:207], v[96:99]
	v_mfma_f32_16x16x32_bf16 v[84:87], v[160:163], v[212:215], v[84:87]
	v_mfma_f32_16x16x32_bf16 v[80:83], v[168:171], v[212:215], v[80:83]
	s_barrier
; #define PG8_STAGE(bufoff, gbase, voff) do { _Pragma("unroll") for (int _i = 0; _i < 2; ++_i) \
;         __builtin_amdgcn_global_load_lds((const unsigned*)((const char*)(gbase) + (voff)[_i]), (LAS unsigned*)(lds + (bufoff) + ldsw + _i * 8192), 16, 0, 0); } while (0)
; #define PG8_LDA(dst, b, h) do { _Pragma("unroll") for (int m = 0; m < 4; ++m) _Pragma("unroll") for (int k = 0; k < 2; ++k) dst[m][k] = *(const LAS bf16x8*)(lds + PG8_SA(b, h) + aoff + m * 2048 + k * 1024); } while (0)
; #define PG8_LDB(dst, b, h) do { _Pragma("unroll") for (int n = 0; n < 2; ++n) _Pragma("unroll") for (int k = 0; k < 2; ++k) dst[n][k] = *(const LAS bf16x8*)(lds + PG8_SB(b, h) + boff + n * 2048 + k * 1024); } while (0)
; #define PG8_MMA(ai, bj, At, Bt) do { __builtin_amdgcn_s_setprio(1); _Pragma("unroll") for (int m = 0; m < 4; ++m) _Pragma("unroll") for (int n = 0; n < 2; ++n) _Pragma("unroll") for (int k = 0; k < 2; ++k) \
;         acc[ai][bj][m][n] = __builtin_amdgcn_mfma_f32_16x16x32_bf16(Bt[n][k], At[m][k], acc[ai][bj][m][n], 0, 0, 0); __builtin_amdgcn_s_setprio(0); } while (0)
; #define PG8_WAIT_V(n) asm volatile("s_waitcnt vmcnt(" #n ")" ::: "memory")
; #define PG8_WAIT_L(n) asm volatile("s_waitcnt lgkmcnt(" #n ")" ::: "memory")
; #define PG8_BAR __builtin_amdgcn_s_barrier()
; #define PG8_SCHED __builtin_amdgcn_sched_barrier(0)
; template <class Sched, class Epi, bool ALIGN_EPI, bool SP2>
; __device__ __forceinline__ void gemm_phase(LAS unsigned char* lds, const int K, const int lda, const int ldb, const Sched& S, const Epi& E) {
;     ...
;             PG8_WAIT_V(8); PG8_WAIT_L(0); PG8_BAR; PG8_MMA(0, 0, At, B0); PG8_MMA(0, 1, At, B1); PG8_BAR; PG8_SCHED;
;             PG8_LDA(At, 0, 1); PG8_STAGE(PG8_SB(0, 0), b2, voffB); PG8_STAGE(PG8_SB(0, 1), b2 + hstepB, voffB); PG8_STAGE(PG8_SA(0, 0), a2, voffA);
;             PG8_WAIT_V(8); PG8_WAIT_L(0); PG8_BAR; PG8_MMA(1, 0, At, B0); PG8_MMA(1, 1, At, B1); PG8_BAR; PG8_SCHED;
;             PG8_LDB(B0, 1, 0); PG8_LDB(B1, 1, 1); PG8_SCHED; PG8_LDA(At, 1, 0); PG8_STAGE(PG8_SA(0, 1), a2 + hstepA, voffA);
;             PG8_WAIT_V(8); PG8_WAIT_L(0); PG8_BAR; PG8_MMA(0, 0, At, B0); PG8_MMA(0, 1, At, B1); PG8_BAR; PG8_SCHED;
	s_add_i32 s58, s51, s21
	v_lshl_add_u64 v[216:217], s[42:43], 0, v[150:151]
	s_mov_b32 m0, s58
	ds_read_b128 v[172:175], v185 offset:16384
	ds_read_b128 v[188:191], v185 offset:17408
	ds_read_b128 v[192:195], v185 offset:18432
	ds_read_b128 v[196:199], v185 offset:19456
	ds_read_b128 v[200:203], v185 offset:20480
	ds_read_b128 v[204:207], v185 offset:21504
	ds_read_b128 v[208:211], v185 offset:22528
	ds_read_b128 v[212:215], v185 offset:23552
	global_load_lds_dwordx4 v[216:217], off
	s_add_i32 m0, s58, 0x2000
	s_add_u32 s58, s42, 0x80000
	v_lshl_add_u64 v[218:219], s[42:43], 0, v[154:155]
	s_addc_u32 s59, s43, 0
	s_add_i32 s60, s52, s21
	global_load_lds_dwordx4 v[218:219], off
	v_lshl_add_u64 v[220:221], s[58:59], 0, v[150:151]
	s_mov_b32 m0, s60
	v_lshl_add_u64 v[222:223], s[44:45], 0, v[152:153]
	global_load_lds_dwordx4 v[220:221], off
	v_lshl_add_u64 v[220:221], s[58:59], 0, v[154:155]
	s_add_i32 m0, s60, 0x2000
	s_nop 0
	global_load_lds_dwordx4 v[220:221], off
	v_lshl_add_u64 v[220:221], s[44:45], 0, v[148:149]
	s_mov_b32 m0, s33
	s_nop 0
	global_load_lds_dwordx4 v[220:221], off
	s_mov_b32 m0, s35
	s_nop 0
	global_load_lds_dwordx4 v[222:223], off
	s_waitcnt vmcnt(8)
	s_waitcnt lgkmcnt(0)
	s_barrier
	s_waitcnt lgkmcnt(0)
	v_mfma_f32_16x16x32_bf16 v[60:63], v[64:67], v[172:175], v[60:63]
	v_mfma_f32_16x16x32_bf16 v[56:59], v[72:75], v[172:175], v[56:59]
	v_mfma_f32_16x16x32_bf16 v[44:47], v[64:67], v[192:195], v[44:47]
	v_mfma_f32_16x16x32_bf16 v[40:43], v[72:75], v[192:195], v[40:43]
	v_mfma_f32_16x16x32_bf16 v[24:27], v[64:67], v[200:203], v[24:27]
	v_mfma_f32_16x16x32_bf16 v[20:23], v[72:75], v[200:203], v[20:23]
	v_mfma_f32_16x16x32_bf16 v[8:11], v[64:67], v[208:211], v[8:11]
	v_mfma_f32_16x16x32_bf16 v[0:3], v[72:75], v[208:211], v[0:3]
	v_mfma_f32_16x16x32_bf16 v[60:63], v[68:71], v[188:191], v[60:63]
	v_mfma_f32_16x16x32_bf16 v[56:59], v[76:79], v[188:191], v[56:59]
	v_mfma_f32_16x16x32_bf16 v[44:47], v[68:71], v[196:199], v[44:47]
	v_mfma_f32_16x16x32_bf16 v[40:43], v[76:79], v[196:199], v[40:43]
	v_mfma_f32_16x16x32_bf16 v[24:27], v[68:71], v[204:207], v[24:27]
	v_mfma_f32_16x16x32_bf16 v[20:23], v[76:79], v[204:207], v[20:23]
	v_mfma_f32_16x16x32_bf16 v[8:11], v[68:71], v[212:215], v[8:11]
	v_mfma_f32_16x16x32_bf16 v[0:3], v[76:79], v[212:215], v[0:3]
	v_mfma_f32_16x16x32_bf16 v[52:55], v[144:147], v[172:175], v[52:55]
	v_mfma_f32_16x16x32_bf16 v[48:51], v[164:167], v[172:175], v[48:51]
	v_mfma_f32_16x16x32_bf16 v[36:39], v[144:147], v[192:195], v[36:39]
	v_mfma_f32_16x16x32_bf16 v[32:35], v[164:167], v[192:195], v[32:35]
	v_mfma_f32_16x16x32_bf16 v[28:31], v[144:147], v[200:203], v[28:31]
	v_mfma_f32_16x16x32_bf16 v[16:19], v[164:167], v[200:203], v[16:19]
	v_mfma_f32_16x16x32_bf16 v[12:15], v[144:147], v[208:211], v[12:15]
	v_mfma_f32_16x16x32_bf16 v[4:7], v[164:167], v[208:211], v[4:7]
	v_mfma_f32_16x16x32_bf16 v[52:55], v[160:163], v[188:191], v[52:55]
	v_mfma_f32_16x16x32_bf16 v[48:51], v[168:171], v[188:191], v[48:51]
	v_mfma_f32_16x16x32_bf16 v[36:39], v[160:163], v[196:199], v[36:39]
	v_mfma_f32_16x16x32_bf16 v[32:35], v[168:171], v[196:199], v[32:35]
	v_mfma_f32_16x16x32_bf16 v[28:31], v[160:163], v[204:207], v[28:31]
	v_mfma_f32_16x16x32_bf16 v[16:19], v[168:171], v[204:207], v[16:19]
	v_mfma_f32_16x16x32_bf16 v[12:15], v[160:163], v[212:215], v[12:15]
	v_mfma_f32_16x16x32_bf16 v[4:7], v[168:171], v[212:215], v[4:7]
	s_barrier
	s_add_i32 s58, 0, 0x18000
	s_add_i32 s59, 0, 0x1c000
	v_add_u32_e32 v76, s58, v181
	v_add_u32_e32 v168, s59, v181
	ds_read_b128 v[64:67], v76
	ds_read_b128 v[68:71], v76 offset:1024
	ds_read_b128 v[72:75], v76 offset:2048
	ds_read_b128 v[76:79], v76 offset:3072
	ds_read_b128 v[144:147], v168
	ds_read_b128 v[160:163], v168 offset:1024
	ds_read_b128 v[164:167], v168 offset:2048
	ds_read_b128 v[168:171], v168 offset:3072
	s_add_u32 s44, s44, 0x80000
	s_addc_u32 s45, s45, 0
	s_mov_b32 m0, s46
	v_lshl_add_u64 v[224:225], s[44:45], 0, v[148:149]
	ds_read_b128 v[172:175], v185 offset:32768
	ds_read_b128 v[188:191], v185 offset:33792
	ds_read_b128 v[192:195], v185 offset:34816
	ds_read_b128 v[196:199], v185 offset:35840
	ds_read_b128 v[200:203], v185 offset:36864
	ds_read_b128 v[204:207], v185 offset:37888
	ds_read_b128 v[208:211], v185 offset:38912
	ds_read_b128 v[212:215], v185 offset:39936
	global_load_lds_dwordx4 v[224:225], off
	v_lshl_add_u64 v[224:225], s[44:45], 0, v[152:153]
	s_mov_b32 m0, s47
	s_nop 0
	global_load_lds_dwordx4 v[224:225], off
	s_waitcnt vmcnt(8)
	s_waitcnt lgkmcnt(0)
	s_barrier
; #define PG8_STAGE(bufoff, gbase, voff) do { _Pragma("unroll") for (int _i = 0; _i < 2; ++_i) \
;         __builtin_amdgcn_global_load_lds((const unsigned*)((const char*)(gbase) + (voff)[_i]), (LAS unsigned*)(lds + (bufoff) + ldsw + _i * 8192), 16, 0, 0); } while (0)
; #define PG8_LDA(dst, b, h) do { _Pragma("unroll") for (int m = 0; m < 4; ++m) _Pragma("unroll") for (int k = 0; k < 2; ++k) dst[m][k] = *(const LAS bf16x8*)(lds + PG8_SA(b, h) + aoff + m * 2048 + k * 1024); } while (0)
; #define PG8_MMA(ai, bj, At, Bt) do { __builtin_amdgcn_s_setprio(1); _Pragma("unroll") for (int m = 0; m < 4; ++m) _Pragma("unroll") for (int n = 0; n < 2; ++n) _Pragma("unroll") for (int k = 0; k < 2; ++k) \
;         acc[ai][bj][m][n] = __builtin_amdgcn_mfma_f32_16x16x32_bf16(Bt[n][k], At[m][k], acc[ai][bj][m][n], 0, 0, 0); __builtin_amdgcn_s_setprio(0); } while (0)
; #define PG8_WAIT_V(n) asm volatile("s_waitcnt vmcnt(" #n ")" ::: "memory")
; #define PG8_WAIT_L(n) asm volatile("s_waitcnt lgkmcnt(" #n ")" ::: "memory")
; #define PG8_BAR __builtin_amdgcn_s_barrier()
; #define PG8_SCHED __builtin_amdgcn_sched_barrier(0)
; template <class Sched, class Epi, bool ALIGN_EPI, bool SP2>
; __device__ __forceinline__ void gemm_phase(LAS unsigned char* lds, const int K, const int lda, const int ldb, const Sched& S, const Epi& E) {
;     ...
;             PG8_WAIT_V(8); PG8_WAIT_L(0); PG8_BAR; PG8_MMA(0, 0, At, B0); PG8_MMA(0, 1, At, B1); PG8_BAR; PG8_SCHED;
;             PG8_LDA(At, 1, 1); PG8_STAGE(PG8_SB(1, 0), b3, voffB); PG8_STAGE(PG8_SB(1, 1), b3 + hstepB, voffB); PG8_STAGE(PG8_SA(1, 0), a3, voffA);
;             PG8_WAIT_V(8); PG8_WAIT_L(0); PG8_BAR; PG8_MMA(1, 0, At, B0); PG8_MMA(1, 1, At, B1); PG8_BAR; PG8_SCHED;
	s_waitcnt lgkmcnt(0)
	v_mfma_f32_16x16x32_bf16 v[140:143], v[64:67], v[172:175], v[140:143]
	v_mfma_f32_16x16x32_bf16 v[136:139], v[72:75], v[172:175], v[136:139]
	v_mfma_f32_16x16x32_bf16 v[124:127], v[64:67], v[192:195], v[124:127]
	v_mfma_f32_16x16x32_bf16 v[120:123], v[72:75], v[192:195], v[120:123]
	v_mfma_f32_16x16x32_bf16 v[108:111], v[64:67], v[200:203], v[108:111]
	v_mfma_f32_16x16x32_bf16 v[104:107], v[72:75], v[200:203], v[104:107]
	v_mfma_f32_16x16x32_bf16 v[92:95], v[64:67], v[208:211], v[92:95]
	v_mfma_f32_16x16x32_bf16 v[88:91], v[72:75], v[208:211], v[88:91]
	v_mfma_f32_16x16x32_bf16 v[140:143], v[68:71], v[188:191], v[140:143]
	v_mfma_f32_16x16x32_bf16 v[136:139], v[76:79], v[188:191], v[136:139]
	v_mfma_f32_16x16x32_bf16 v[124:127], v[68:71], v[196:199], v[124:127]
	v_mfma_f32_16x16x32_bf16 v[120:123], v[76:79], v[196:199], v[120:123]
	v_mfma_f32_16x16x32_bf16 v[108:111], v[68:71], v[204:207], v[108:111]
	v_mfma_f32_16x16x32_bf16 v[104:107], v[76:79], v[204:207], v[104:107]
	v_mfma_f32_16x16x32_bf16 v[92:95], v[68:71], v[212:215], v[92:95]
	v_mfma_f32_16x16x32_bf16 v[88:91], v[76:79], v[212:215], v[88:91]
	v_mfma_f32_16x16x32_bf16 v[132:135], v[144:147], v[172:175], v[132:135]
	v_mfma_f32_16x16x32_bf16 v[128:131], v[164:167], v[172:175], v[128:131]
	v_mfma_f32_16x16x32_bf16 v[116:119], v[144:147], v[192:195], v[116:119]
	v_mfma_f32_16x16x32_bf16 v[112:115], v[164:167], v[192:195], v[112:115]
	v_mfma_f32_16x16x32_bf16 v[100:103], v[144:147], v[200:203], v[100:103]
	v_mfma_f32_16x16x32_bf16 v[96:99], v[164:167], v[200:203], v[96:99]
	v_mfma_f32_16x16x32_bf16 v[84:87], v[144:147], v[208:211], v[84:87]
	v_mfma_f32_16x16x32_bf16 v[80:83], v[164:167], v[208:211], v[80:83]
	v_mfma_f32_16x16x32_bf16 v[132:135], v[160:163], v[188:191], v[132:135]
	v_mfma_f32_16x16x32_bf16 v[128:131], v[168:171], v[188:191], v[128:131]
	v_mfma_f32_16x16x32_bf16 v[116:119], v[160:163], v[196:199], v[116:119]
	v_mfma_f32_16x16x32_bf16 v[112:115], v[168:171], v[196:199], v[112:115]
	v_mfma_f32_16x16x32_bf16 v[100:103], v[160:163], v[204:207], v[100:103]
	v_mfma_f32_16x16x32_bf16 v[96:99], v[168:171], v[204:207], v[96:99]
	v_mfma_f32_16x16x32_bf16 v[84:87], v[160:163], v[212:215], v[84:87]
	v_mfma_f32_16x16x32_bf16 v[80:83], v[168:171], v[212:215], v[80:83]
	s_barrier
	s_add_i32 s44, s58, s21
	v_lshl_add_u64 v[216:217], v[216:217], 0, s[14:15]
	s_mov_b32 m0, s44
	ds_read_b128 v[172:175], v185 offset:49152
	ds_read_b128 v[188:191], v185 offset:50176
	ds_read_b128 v[192:195], v185 offset:51200
	ds_read_b128 v[196:199], v185 offset:52224
	ds_read_b128 v[200:203], v185 offset:53248
	ds_read_b128 v[204:207], v185 offset:54272
	ds_read_b128 v[208:211], v185 offset:55296
	ds_read_b128 v[212:215], v185 offset:56320
	global_load_lds_dwordx4 v[216:217], off
	s_add_i32 m0, s44, 0x2000
	s_add_u32 s42, s42, 0x80080
	v_lshl_add_u64 v[216:217], v[218:219], 0, s[14:15]
	s_addc_u32 s43, s43, 0
	s_add_i32 s44, s59, s21
	global_load_lds_dwordx4 v[216:217], off
	v_lshl_add_u64 v[216:217], s[42:43], 0, v[150:151]
	s_mov_b32 m0, s44
	s_nop 0
	global_load_lds_dwordx4 v[216:217], off
	v_lshl_add_u64 v[216:217], s[42:43], 0, v[154:155]
	s_add_i32 m0, s44, 0x2000
	s_nop 0
	global_load_lds_dwordx4 v[216:217], off
	v_lshl_add_u64 v[216:217], v[220:221], 0, s[14:15]
	s_mov_b32 m0, s49
	s_nop 0
	global_load_lds_dwordx4 v[216:217], off
	v_lshl_add_u64 v[216:217], v[222:223], 0, s[14:15]
	s_mov_b32 m0, s50
	s_nop 0
	global_load_lds_dwordx4 v[216:217], off
	s_waitcnt vmcnt(8)
	s_waitcnt lgkmcnt(0)
	s_barrier
	s_waitcnt lgkmcnt(0)
	v_mfma_f32_16x16x32_bf16 v[60:63], v[64:67], v[172:175], v[60:63]
	v_mfma_f32_16x16x32_bf16 v[56:59], v[72:75], v[172:175], v[56:59]
	v_mfma_f32_16x16x32_bf16 v[44:47], v[64:67], v[192:195], v[44:47]
	v_mfma_f32_16x16x32_bf16 v[40:43], v[72:75], v[192:195], v[40:43]
	v_mfma_f32_16x16x32_bf16 v[24:27], v[64:67], v[200:203], v[24:27]
	v_mfma_f32_16x16x32_bf16 v[20:23], v[72:75], v[200:203], v[20:23]
	v_mfma_f32_16x16x32_bf16 v[8:11], v[64:67], v[208:211], v[8:11]
	v_mfma_f32_16x16x32_bf16 v[0:3], v[72:75], v[208:211], v[0:3]
	v_mfma_f32_16x16x32_bf16 v[60:63], v[68:71], v[188:191], v[60:63]
	v_mfma_f32_16x16x32_bf16 v[56:59], v[76:79], v[188:191], v[56:59]
	v_mfma_f32_16x16x32_bf16 v[44:47], v[68:71], v[196:199], v[44:47]
	v_mfma_f32_16x16x32_bf16 v[40:43], v[76:79], v[196:199], v[40:43]
	v_mfma_f32_16x16x32_bf16 v[24:27], v[68:71], v[204:207], v[24:27]
	v_mfma_f32_16x16x32_bf16 v[20:23], v[76:79], v[204:207], v[20:23]
	v_mfma_f32_16x16x32_bf16 v[8:11], v[68:71], v[212:215], v[8:11]
	v_mfma_f32_16x16x32_bf16 v[0:3], v[76:79], v[212:215], v[0:3]
	v_mfma_f32_16x16x32_bf16 v[52:55], v[144:147], v[172:175], v[52:55]
	v_mfma_f32_16x16x32_bf16 v[48:51], v[164:167], v[172:175], v[48:51]
	v_mfma_f32_16x16x32_bf16 v[36:39], v[144:147], v[192:195], v[36:39]
	v_mfma_f32_16x16x32_bf16 v[32:35], v[164:167], v[192:195], v[32:35]
	v_mfma_f32_16x16x32_bf16 v[28:31], v[144:147], v[200:203], v[28:31]
	v_mfma_f32_16x16x32_bf16 v[16:19], v[164:167], v[200:203], v[16:19]
	v_mfma_f32_16x16x32_bf16 v[12:15], v[144:147], v[208:211], v[12:15]
	v_mfma_f32_16x16x32_bf16 v[4:7], v[164:167], v[208:211], v[4:7]
	v_mfma_f32_16x16x32_bf16 v[52:55], v[160:163], v[188:191], v[52:55]
	v_mfma_f32_16x16x32_bf16 v[48:51], v[168:171], v[188:191], v[48:51]
	v_mfma_f32_16x16x32_bf16 v[36:39], v[160:163], v[196:199], v[36:39]
	v_mfma_f32_16x16x32_bf16 v[32:35], v[168:171], v[196:199], v[32:35]
	v_mfma_f32_16x16x32_bf16 v[28:31], v[160:163], v[204:207], v[28:31]
	v_mfma_f32_16x16x32_bf16 v[16:19], v[168:171], v[204:207], v[16:19]
	v_mfma_f32_16x16x32_bf16 v[12:15], v[160:163], v[212:215], v[12:15]
	v_mfma_f32_16x16x32_bf16 v[4:7], v[168:171], v[212:215], v[4:7]
	s_barrier
	s_add_i32 s57, s57, 2
	s_add_u32 s36, s36, 0x100
	s_addc_u32 s37, s37, 0
	s_add_u32 s25, s25, 0x100
	s_addc_u32 s56, s56, 0
	s_cmp_gt_u32 s57, 29
	s_cbranch_scc0 .LBB0_1037
	s_setprio 0
	s_and_b64 vcc, exec, s[16:17]
	s_mov_b32 s56, s62
	s_cbranch_vccz .LBB0_1040
	s_barrier

; #define PG8_STAGE(bufoff, gbase, voff) do { _Pragma("unroll") for (int _i = 0; _i < 2; ++_i) \
;         __builtin_amdgcn_global_load_lds((const unsigned*)((const char*)(gbase) + (voff)[_i]), (LAS unsigned*)(lds + (bufoff) + ldsw + _i * 8192), 16, 0, 0); } while (0)
; #define PG8_LDA(dst, b, h) do { _Pragma("unroll") for (int m = 0; m < 4; ++m) _Pragma("unroll") for (int k = 0; k < 2; ++k) dst[m][k] = *(const LAS bf16x8*)(lds + PG8_SA(b, h) + aoff + m * 2048 + k * 1024); } while (0)
; #define PG8_LDB(dst, b, h) do { _Pragma("unroll") for (int n = 0; n < 2; ++n) _Pragma("unroll") for (int k = 0; k < 2; ++k) dst[n][k] = *(const LAS bf16x8*)(lds + PG8_SB(b, h) + boff + n * 2048 + k * 1024); } while (0)
; #define PG8_MMA(ai, bj, At, Bt) do { __builtin_amdgcn_s_setprio(1); _Pragma("unroll") for (int m = 0; m < 4; ++m) _Pragma("unroll") for (int n = 0; n < 2; ++n) _Pragma("unroll") for (int k = 0; k < 2; ++k) \
;         acc[ai][bj][m][n] = __builtin_amdgcn_mfma_f32_16x16x32_bf16(Bt[n][k], At[m][k], acc[ai][bj][m][n], 0, 0, 0); __builtin_amdgcn_s_setprio(0); } while (0)
; #define PG8_WAIT_V(n) asm volatile("s_waitcnt vmcnt(" #n ")" ::: "memory")
; template <class Sched, class Epi, bool ALIGN_EPI, bool SP2>
; __device__ __forceinline__ void gemm_phase(LAS unsigned char* lds, const int K, const int lda, const int ldb, const Sched& S, const Epi& E) {
;     ...
;         for (int t = 0; t < nt; t += 2) {
;             const bool last = (t == nt - 2);
;             const char* a1 = cA + (size_t)(t + 1) * kstep;
;             const char* a2 = last ? nA : cA + (size_t)(t + 2) * kstep; const char* b2 = last ? nB : cB + (size_t)(t + 2) * kstep;
;             const char* a3 = a2 + kstep; const char* b3 = b2 + kstep;
;             if constexpr (SP2) {
;             PG8_LDB(B0, 0, 0); PG8_LDB(B1, 0, 1); PG8_SCHED; PG8_LDA(At, 0, 0); PG8_STAGE(PG8_SA(1, 1), a1 + hstepA, voffA);
;             PG8_WAIT_V(8); PG8_WAIT_L(0); PG8_BAR; PG8_MMA(0, 0, At, B0); PG8_MMA(0, 1, At, B1); PG8_BAR; PG8_SCHED;
;     ...
;         if (!keep) {
; #pragma unroll
;         for (int a = 0; a < 2; ++a)
; #pragma unroll
;             for (int b = 0; b < 2; ++b)
; #pragma unroll
;                 for (int m = 0; m < 4; ++m)
; #pragma unroll
;                     for (int n = 0; n < 2; ++n) acc[a][b][m][n] = (f32x4){0.f, 0.f, 0.f, 0.f};
;         }
;         cur = nxt; cA = nA; cB = nB; ++ui;
.LBB0_1119:
	s_add_u32 s49, s4, 0x100
	v_mov_b32_e32 v0, 0
	s_addc_u32 s50, s5, 0
	s_mov_b32 s51, -2
	v_mov_b32_e32 v1, v0
	v_mov_b32_e32 v2, v0
	v_mov_b32_e32 v3, v0
	v_mov_b32_e32 v4, v0
	v_mov_b32_e32 v5, v0
	v_mov_b32_e32 v6, v0
	v_mov_b32_e32 v7, v0
	v_mov_b32_e32 v12, v0
	v_mov_b32_e32 v13, v0
	v_mov_b32_e32 v14, v0
	v_mov_b32_e32 v15, v0
	v_mov_b32_e32 v20, v0
	v_mov_b32_e32 v21, v0
	v_mov_b32_e32 v22, v0
	v_mov_b32_e32 v23, v0
	v_mov_b32_e32 v32, v0
	v_mov_b32_e32 v33, v0
	v_mov_b32_e32 v34, v0
	v_mov_b32_e32 v35, v0
	v_mov_b32_e32 v36, v0
	v_mov_b32_e32 v37, v0
	v_mov_b32_e32 v38, v0
	v_mov_b32_e32 v39, v0
	v_mov_b32_e32 v44, v0
	v_mov_b32_e32 v45, v0
	v_mov_b32_e32 v46, v0
	v_mov_b32_e32 v47, v0
	v_mov_b32_e32 v52, v0
	v_mov_b32_e32 v53, v0
	v_mov_b32_e32 v54, v0
	v_mov_b32_e32 v55, v0
	v_mov_b32_e32 v8, v0
	v_mov_b32_e32 v9, v0
	v_mov_b32_e32 v10, v0
	v_mov_b32_e32 v11, v0
	v_mov_b32_e32 v16, v0
	v_mov_b32_e32 v17, v0
	v_mov_b32_e32 v18, v0
	v_mov_b32_e32 v19, v0
	v_mov_b32_e32 v24, v0
	v_mov_b32_e32 v25, v0
	v_mov_b32_e32 v26, v0
	v_mov_b32_e32 v27, v0
	v_mov_b32_e32 v28, v0
	v_mov_b32_e32 v29, v0
	v_mov_b32_e32 v30, v0
	v_mov_b32_e32 v31, v0
	v_mov_b32_e32 v40, v0
	v_mov_b32_e32 v41, v0
	v_mov_b32_e32 v42, v0
	v_mov_b32_e32 v43, v0
	v_mov_b32_e32 v48, v0
	v_mov_b32_e32 v49, v0
	v_mov_b32_e32 v50, v0
	v_mov_b32_e32 v51, v0
	v_mov_b32_e32 v56, v0
	v_mov_b32_e32 v57, v0
	v_mov_b32_e32 v58, v0
	v_mov_b32_e32 v59, v0
	v_mov_b32_e32 v60, v0
	v_mov_b32_e32 v61, v0
	v_mov_b32_e32 v62, v0
	v_mov_b32_e32 v63, v0
	v_mov_b32_e32 v64, v0
	v_mov_b32_e32 v65, v0
	v_mov_b32_e32 v66, v0
	v_mov_b32_e32 v67, v0
	v_mov_b32_e32 v68, v0
	v_mov_b32_e32 v69, v0
	v_mov_b32_e32 v70, v0
	v_mov_b32_e32 v71, v0
	v_mov_b32_e32 v76, v0
	v_mov_b32_e32 v77, v0
	v_mov_b32_e32 v78, v0
	v_mov_b32_e32 v79, v0
	v_mov_b32_e32 v84, v0
	v_mov_b32_e32 v85, v0
	v_mov_b32_e32 v86, v0
	v_mov_b32_e32 v87, v0
	v_mov_b32_e32 v128, v0
	v_mov_b32_e32 v129, v0
	v_mov_b32_e32 v130, v0
	v_mov_b32_e32 v131, v0
	v_mov_b32_e32 v132, v0
	v_mov_b32_e32 v133, v0
	v_mov_b32_e32 v134, v0
	v_mov_b32_e32 v135, v0
	v_mov_b32_e32 v140, v0
	v_mov_b32_e32 v141, v0
	v_mov_b32_e32 v142, v0
	v_mov_b32_e32 v143, v0
	v_mov_b32_e32 v148, v0
	v_mov_b32_e32 v149, v0
	v_mov_b32_e32 v150, v0
	v_mov_b32_e32 v151, v0
	v_mov_b32_e32 v72, v0
	v_mov_b32_e32 v73, v0
	v_mov_b32_e32 v74, v0
	v_mov_b32_e32 v75, v0
	v_mov_b32_e32 v80, v0
	v_mov_b32_e32 v81, v0
	v_mov_b32_e32 v82, v0
	v_mov_b32_e32 v83, v0
	v_mov_b32_e32 v88, v0
	v_mov_b32_e32 v89, v0
	v_mov_b32_e32 v90, v0
	v_mov_b32_e32 v91, v0
	v_mov_b32_e32 v92, v0
	v_mov_b32_e32 v93, v0
	v_mov_b32_e32 v94, v0
	v_mov_b32_e32 v95, v0
	v_mov_b32_e32 v136, v0
	v_mov_b32_e32 v137, v0
	v_mov_b32_e32 v138, v0
	v_mov_b32_e32 v139, v0
	v_mov_b32_e32 v144, v0
	v_mov_b32_e32 v145, v0
	v_mov_b32_e32 v146, v0
	v_mov_b32_e32 v147, v0
	v_mov_b32_e32 v152, v0
	v_mov_b32_e32 v153, v0
	v_mov_b32_e32 v154, v0
	v_mov_b32_e32 v155, v0
	v_mov_b32_e32 v156, v0
	v_mov_b32_e32 v157, v0
	v_mov_b32_e32 v158, v0
	v_mov_b32_e32 v159, v0
	v_readlane_b32 s98, v255, 13
	s_nop 4
	s_cmp_lt_u32 s98, 4
	s_cbranch_scc1 .Lprio_skip_1120
	s_setprio 1
.Lprio_skip_1120:
.LBB0_1120:
	ds_read_b128 v[96:99], v178
	ds_read_b128 v[100:103], v178 offset:1024
	ds_read_b128 v[104:107], v178 offset:2048
	ds_read_b128 v[108:111], v178 offset:3072
	ds_read_b128 v[112:115], v180
	ds_read_b128 v[116:119], v180 offset:1024
	ds_read_b128 v[120:123], v180 offset:2048
	ds_read_b128 v[124:127], v180 offset:3072
	s_add_u32 s4, s0, 0x100
	s_addc_u32 s5, s1, 0
	s_cmpk_eq_i32 s51, 0x54
	s_cselect_b32 s27, s21, s5
	s_cselect_b32 s26, s20, s4
	s_cselect_b32 s25, s23, s50
	s_cselect_b32 s24, s22, s49
	v_lshl_add_u64 v[172:173], s[0:1], 0, v[164:165]
	s_add_i32 m0, s17, 0xc000
	ds_read_b128 v[168:171], v181
	ds_read_b128 v[184:187], v181 offset:1024
	ds_read_b128 v[188:191], v181 offset:2048
	ds_read_b128 v[192:195], v181 offset:3072
	ds_read_b128 v[196:199], v181 offset:4096
	ds_read_b128 v[200:203], v181 offset:5120
	ds_read_b128 v[204:207], v181 offset:6144
	ds_read_b128 v[208:211], v181 offset:7168
	global_load_lds_dwordx4 v[172:173], off
	v_lshl_add_u64 v[172:173], s[0:1], 0, v[166:167]
	s_add_i32 m0, s17, 0xe000
	s_nop 0
	global_load_lds_dwordx4 v[172:173], off
	s_waitcnt vmcnt(8)
	s_waitcnt lgkmcnt(0)
	s_barrier
	s_waitcnt lgkmcnt(0)
	v_mfma_f32_16x16x32_bf16 v[156:159], v[96:99], v[168:171], v[156:159]
	v_mfma_f32_16x16x32_bf16 v[152:155], v[104:107], v[168:171], v[152:155]
	v_mfma_f32_16x16x32_bf16 v[144:147], v[96:99], v[188:191], v[144:147]
	v_mfma_f32_16x16x32_bf16 v[136:139], v[104:107], v[188:191], v[136:139]
	v_mfma_f32_16x16x32_bf16 v[92:95], v[96:99], v[196:199], v[92:95]
	v_mfma_f32_16x16x32_bf16 v[88:91], v[104:107], v[196:199], v[88:91]
	v_mfma_f32_16x16x32_bf16 v[80:83], v[96:99], v[204:207], v[80:83]
	v_mfma_f32_16x16x32_bf16 v[72:75], v[104:107], v[204:207], v[72:75]
	v_mfma_f32_16x16x32_bf16 v[156:159], v[100:103], v[184:187], v[156:159]
	v_mfma_f32_16x16x32_bf16 v[152:155], v[108:111], v[184:187], v[152:155]
	v_mfma_f32_16x16x32_bf16 v[144:147], v[100:103], v[192:195], v[144:147]
	v_mfma_f32_16x16x32_bf16 v[136:139], v[108:111], v[192:195], v[136:139]
	v_mfma_f32_16x16x32_bf16 v[92:95], v[100:103], v[200:203], v[92:95]
	v_mfma_f32_16x16x32_bf16 v[88:91], v[108:111], v[200:203], v[88:91]
	v_mfma_f32_16x16x32_bf16 v[80:83], v[100:103], v[208:211], v[80:83]
	v_mfma_f32_16x16x32_bf16 v[72:75], v[108:111], v[208:211], v[72:75]
	v_mfma_f32_16x16x32_bf16 v[148:151], v[112:115], v[168:171], v[148:151]
	v_mfma_f32_16x16x32_bf16 v[140:143], v[120:123], v[168:171], v[140:143]
	v_mfma_f32_16x16x32_bf16 v[132:135], v[112:115], v[188:191], v[132:135]
	v_mfma_f32_16x16x32_bf16 v[128:131], v[120:123], v[188:191], v[128:131]
	v_mfma_f32_16x16x32_bf16 v[84:87], v[112:115], v[196:199], v[84:87]
	v_mfma_f32_16x16x32_bf16 v[76:79], v[120:123], v[196:199], v[76:79]
	v_mfma_f32_16x16x32_bf16 v[68:71], v[112:115], v[204:207], v[68:71]
	v_mfma_f32_16x16x32_bf16 v[64:67], v[120:123], v[204:207], v[64:67]
	v_mfma_f32_16x16x32_bf16 v[148:151], v[116:119], v[184:187], v[148:151]
	v_mfma_f32_16x16x32_bf16 v[140:143], v[124:127], v[184:187], v[140:143]
	v_mfma_f32_16x16x32_bf16 v[132:135], v[116:119], v[192:195], v[132:135]
	v_mfma_f32_16x16x32_bf16 v[128:131], v[124:127], v[192:195], v[128:131]
	v_mfma_f32_16x16x32_bf16 v[84:87], v[116:119], v[200:203], v[84:87]
	v_mfma_f32_16x16x32_bf16 v[76:79], v[124:127], v[200:203], v[76:79]
	v_mfma_f32_16x16x32_bf16 v[68:71], v[116:119], v[208:211], v[68:71]
	v_mfma_f32_16x16x32_bf16 v[64:67], v[124:127], v[208:211], v[64:67]
	s_barrier
; #define PG8_STAGE(bufoff, gbase, voff) do { _Pragma("unroll") for (int _i = 0; _i < 2; ++_i) \
;         __builtin_amdgcn_global_load_lds((const unsigned*)((const char*)(gbase) + (voff)[_i]), (LAS unsigned*)(lds + (bufoff) + ldsw + _i * 8192), 16, 0, 0); } while (0)
; #define PG8_LDA(dst, b, h) do { _Pragma("unroll") for (int m = 0; m < 4; ++m) _Pragma("unroll") for (int k = 0; k < 2; ++k) dst[m][k] = *(const LAS bf16x8*)(lds + PG8_SA(b, h) + aoff + m * 2048 + k * 1024); } while (0)
; #define PG8_LDB(dst, b, h) do { _Pragma("unroll") for (int n = 0; n < 2; ++n) _Pragma("unroll") for (int k = 0; k < 2; ++k) dst[n][k] = *(const LAS bf16x8*)(lds + PG8_SB(b, h) + boff + n * 2048 + k * 1024); } while (0)
; #define PG8_MMA(ai, bj, At, Bt) do { __builtin_amdgcn_s_setprio(1); _Pragma("unroll") for (int m = 0; m < 4; ++m) _Pragma("unroll") for (int n = 0; n < 2; ++n) _Pragma("unroll") for (int k = 0; k < 2; ++k) \
;         acc[ai][bj][m][n] = __builtin_amdgcn_mfma_f32_16x16x32_bf16(Bt[n][k], At[m][k], acc[ai][bj][m][n], 0, 0, 0); __builtin_amdgcn_s_setprio(0); } while (0)
; #define PG8_WAIT_V(n) asm volatile("s_waitcnt vmcnt(" #n ")" ::: "memory")
; #define PG8_WAIT_L(n) asm volatile("s_waitcnt lgkmcnt(" #n ")" ::: "memory")
; #define PG8_BAR __builtin_amdgcn_s_barrier()
; #define PG8_SCHED __builtin_amdgcn_sched_barrier(0)
; template <class Sched, class Epi, bool ALIGN_EPI, bool SP2>
; __device__ __forceinline__ void gemm_phase(LAS unsigned char* lds, const int K, const int lda, const int ldb, const Sched& S, const Epi& E) {
;     ...
;             PG8_WAIT_V(8); PG8_WAIT_L(0); PG8_BAR; PG8_MMA(0, 0, At, B0); PG8_MMA(0, 1, At, B1); PG8_BAR; PG8_SCHED;
;             PG8_LDA(At, 0, 1); PG8_STAGE(PG8_SB(0, 0), b2, voffB); PG8_STAGE(PG8_SB(0, 1), b2 + hstepB, voffB); PG8_STAGE(PG8_SA(0, 0), a2, voffA);
;             PG8_WAIT_V(8); PG8_WAIT_L(0); PG8_BAR; PG8_MMA(1, 0, At, B0); PG8_MMA(1, 1, At, B1); PG8_BAR; PG8_SCHED;
;             PG8_LDB(B0, 1, 0); PG8_LDB(B1, 1, 1); PG8_SCHED; PG8_LDA(At, 1, 0); PG8_STAGE(PG8_SA(0, 1), a2 + hstepA, voffA);
;             PG8_WAIT_V(8); PG8_WAIT_L(0); PG8_BAR; PG8_MMA(0, 0, At, B0); PG8_MMA(0, 1, At, B1); PG8_BAR; PG8_SCHED;
	s_add_i32 s0, s42, s15
	v_lshl_add_u64 v[172:173], s[24:25], 0, v[160:161]
	s_mov_b32 m0, s0
	ds_read_b128 v[168:171], v181 offset:16384
	ds_read_b128 v[184:187], v181 offset:17408
	ds_read_b128 v[188:191], v181 offset:18432
	ds_read_b128 v[192:195], v181 offset:19456
	ds_read_b128 v[196:199], v181 offset:20480
	ds_read_b128 v[200:203], v181 offset:21504
	ds_read_b128 v[204:207], v181 offset:22528
	ds_read_b128 v[208:211], v181 offset:23552
	global_load_lds_dwordx4 v[172:173], off
	s_add_i32 m0, s0, 0x2000
	s_add_u32 s0, s24, 0x160000
	v_lshl_add_u64 v[212:213], s[24:25], 0, v[162:163]
	s_addc_u32 s1, s25, 0
	s_add_i32 s52, s43, s15
	global_load_lds_dwordx4 v[212:213], off
	v_lshl_add_u64 v[214:215], s[0:1], 0, v[160:161]
	s_mov_b32 m0, s52
	v_lshl_add_u64 v[216:217], s[26:27], 0, v[162:163]
	global_load_lds_dwordx4 v[214:215], off
	v_lshl_add_u64 v[214:215], s[0:1], 0, v[162:163]
	s_add_i32 m0, s52, 0x2000
	s_nop 0
	global_load_lds_dwordx4 v[214:215], off
	v_lshl_add_u64 v[214:215], s[26:27], 0, v[160:161]
	s_mov_b32 m0, s17
	s_nop 0
	global_load_lds_dwordx4 v[214:215], off
	s_mov_b32 m0, s28
	s_nop 0
	global_load_lds_dwordx4 v[216:217], off
	s_waitcnt vmcnt(8)
	s_waitcnt lgkmcnt(0)
	s_barrier
	s_waitcnt lgkmcnt(0)
	v_mfma_f32_16x16x32_bf16 v[60:63], v[96:99], v[168:171], v[60:63]
	v_mfma_f32_16x16x32_bf16 v[56:59], v[104:107], v[168:171], v[56:59]
	v_mfma_f32_16x16x32_bf16 v[48:51], v[96:99], v[188:191], v[48:51]
	v_mfma_f32_16x16x32_bf16 v[40:43], v[104:107], v[188:191], v[40:43]
	v_mfma_f32_16x16x32_bf16 v[28:31], v[96:99], v[196:199], v[28:31]
	v_mfma_f32_16x16x32_bf16 v[24:27], v[104:107], v[196:199], v[24:27]
	v_mfma_f32_16x16x32_bf16 v[16:19], v[96:99], v[204:207], v[16:19]
	v_mfma_f32_16x16x32_bf16 v[8:11], v[104:107], v[204:207], v[8:11]
	v_mfma_f32_16x16x32_bf16 v[60:63], v[100:103], v[184:187], v[60:63]
	v_mfma_f32_16x16x32_bf16 v[56:59], v[108:111], v[184:187], v[56:59]
	v_mfma_f32_16x16x32_bf16 v[48:51], v[100:103], v[192:195], v[48:51]
	v_mfma_f32_16x16x32_bf16 v[40:43], v[108:111], v[192:195], v[40:43]
	v_mfma_f32_16x16x32_bf16 v[28:31], v[100:103], v[200:203], v[28:31]
	v_mfma_f32_16x16x32_bf16 v[24:27], v[108:111], v[200:203], v[24:27]
	v_mfma_f32_16x16x32_bf16 v[16:19], v[100:103], v[208:211], v[16:19]
	v_mfma_f32_16x16x32_bf16 v[8:11], v[108:111], v[208:211], v[8:11]
	v_mfma_f32_16x16x32_bf16 v[52:55], v[112:115], v[168:171], v[52:55]
	v_mfma_f32_16x16x32_bf16 v[44:47], v[120:123], v[168:171], v[44:47]
	v_mfma_f32_16x16x32_bf16 v[36:39], v[112:115], v[188:191], v[36:39]
	v_mfma_f32_16x16x32_bf16 v[32:35], v[120:123], v[188:191], v[32:35]
	v_mfma_f32_16x16x32_bf16 v[20:23], v[112:115], v[196:199], v[20:23]
	v_mfma_f32_16x16x32_bf16 v[12:15], v[120:123], v[196:199], v[12:15]
	v_mfma_f32_16x16x32_bf16 v[4:7], v[112:115], v[204:207], v[4:7]
	v_mfma_f32_16x16x32_bf16 v[0:3], v[120:123], v[204:207], v[0:3]
	v_mfma_f32_16x16x32_bf16 v[52:55], v[116:119], v[184:187], v[52:55]
	v_mfma_f32_16x16x32_bf16 v[44:47], v[124:127], v[184:187], v[44:47]
	v_mfma_f32_16x16x32_bf16 v[36:39], v[116:119], v[192:195], v[36:39]
	v_mfma_f32_16x16x32_bf16 v[32:35], v[124:127], v[192:195], v[32:35]
	v_mfma_f32_16x16x32_bf16 v[20:23], v[116:119], v[200:203], v[20:23]
	v_mfma_f32_16x16x32_bf16 v[12:15], v[124:127], v[200:203], v[12:15]
	v_mfma_f32_16x16x32_bf16 v[4:7], v[116:119], v[208:211], v[4:7]
	v_mfma_f32_16x16x32_bf16 v[0:3], v[124:127], v[208:211], v[0:3]
	s_barrier
	s_add_i32 s52, 0, 0x18000
	s_add_i32 s53, 0, 0x1c000
	v_add_u32_e32 v108, s52, v175
	v_add_u32_e32 v124, s53, v175
	ds_read_b128 v[96:99], v108
	ds_read_b128 v[100:103], v108 offset:1024
	ds_read_b128 v[104:107], v108 offset:2048
	ds_read_b128 v[108:111], v108 offset:3072
	ds_read_b128 v[112:115], v124
	ds_read_b128 v[116:119], v124 offset:1024
	ds_read_b128 v[120:123], v124 offset:2048
	ds_read_b128 v[124:127], v124 offset:3072
	s_add_u32 s0, s26, 0x160000
	s_addc_u32 s1, s27, 0
	s_mov_b32 m0, s29
	v_lshl_add_u64 v[218:219], s[0:1], 0, v[160:161]
	ds_read_b128 v[168:171], v181 offset:32768
	ds_read_b128 v[184:187], v181 offset:33792
	ds_read_b128 v[188:191], v181 offset:34816
	ds_read_b128 v[192:195], v181 offset:35840
	ds_read_b128 v[196:199], v181 offset:36864
	ds_read_b128 v[200:203], v181 offset:37888
	ds_read_b128 v[204:207], v181 offset:38912
	ds_read_b128 v[208:211], v181 offset:39936
	global_load_lds_dwordx4 v[218:219], off
	v_lshl_add_u64 v[218:219], s[0:1], 0, v[162:163]
	s_mov_b32 m0, s33
	s_nop 0
	global_load_lds_dwordx4 v[218:219], off
	s_waitcnt vmcnt(8)
	s_waitcnt lgkmcnt(0)
	s_barrier
; #define PG8_STAGE(bufoff, gbase, voff) do { _Pragma("unroll") for (int _i = 0; _i < 2; ++_i) \
;         __builtin_amdgcn_global_load_lds((const unsigned*)((const char*)(gbase) + (voff)[_i]), (LAS unsigned*)(lds + (bufoff) + ldsw + _i * 8192), 16, 0, 0); } while (0)
; #define PG8_LDA(dst, b, h) do { _Pragma("unroll") for (int m = 0; m < 4; ++m) _Pragma("unroll") for (int k = 0; k < 2; ++k) dst[m][k] = *(const LAS bf16x8*)(lds + PG8_SA(b, h) + aoff + m * 2048 + k * 1024); } while (0)
; #define PG8_MMA(ai, bj, At, Bt) do { __builtin_amdgcn_s_setprio(1); _Pragma("unroll") for (int m = 0; m < 4; ++m) _Pragma("unroll") for (int n = 0; n < 2; ++n) _Pragma("unroll") for (int k = 0; k < 2; ++k) \
;         acc[ai][bj][m][n] = __builtin_amdgcn_mfma_f32_16x16x32_bf16(Bt[n][k], At[m][k], acc[ai][bj][m][n], 0, 0, 0); __builtin_amdgcn_s_setprio(0); } while (0)
; #define PG8_WAIT_V(n) asm volatile("s_waitcnt vmcnt(" #n ")" ::: "memory")
; #define PG8_WAIT_L(n) asm volatile("s_waitcnt lgkmcnt(" #n ")" ::: "memory")
; #define PG8_BAR __builtin_amdgcn_s_barrier()
; #define PG8_SCHED __builtin_amdgcn_sched_barrier(0)
; template <class Sched, class Epi, bool ALIGN_EPI, bool SP2>
; __device__ __forceinline__ void gemm_phase(LAS unsigned char* lds, const int K, const int lda, const int ldb, const Sched& S, const Epi& E) {
;     ...
;             PG8_WAIT_V(8); PG8_WAIT_L(0); PG8_BAR; PG8_MMA(0, 0, At, B0); PG8_MMA(0, 1, At, B1); PG8_BAR; PG8_SCHED;
;             PG8_LDA(At, 1, 1); PG8_STAGE(PG8_SB(1, 0), b3, voffB); PG8_STAGE(PG8_SB(1, 1), b3 + hstepB, voffB); PG8_STAGE(PG8_SA(1, 0), a3, voffA);
;             PG8_WAIT_V(8); PG8_WAIT_L(0); PG8_BAR; PG8_MMA(1, 0, At, B0); PG8_MMA(1, 1, At, B1); PG8_BAR; PG8_SCHED;
	s_waitcnt lgkmcnt(0)
	v_mfma_f32_16x16x32_bf16 v[156:159], v[96:99], v[168:171], v[156:159]
	v_mfma_f32_16x16x32_bf16 v[152:155], v[104:107], v[168:171], v[152:155]
	v_mfma_f32_16x16x32_bf16 v[144:147], v[96:99], v[188:191], v[144:147]
	v_mfma_f32_16x16x32_bf16 v[136:139], v[104:107], v[188:191], v[136:139]
	v_mfma_f32_16x16x32_bf16 v[92:95], v[96:99], v[196:199], v[92:95]
	v_mfma_f32_16x16x32_bf16 v[88:91], v[104:107], v[196:199], v[88:91]
	v_mfma_f32_16x16x32_bf16 v[80:83], v[96:99], v[204:207], v[80:83]
	v_mfma_f32_16x16x32_bf16 v[72:75], v[104:107], v[204:207], v[72:75]
	v_mfma_f32_16x16x32_bf16 v[156:159], v[100:103], v[184:187], v[156:159]
	v_mfma_f32_16x16x32_bf16 v[152:155], v[108:111], v[184:187], v[152:155]
	v_mfma_f32_16x16x32_bf16 v[144:147], v[100:103], v[192:195], v[144:147]
	v_mfma_f32_16x16x32_bf16 v[136:139], v[108:111], v[192:195], v[136:139]
	v_mfma_f32_16x16x32_bf16 v[92:95], v[100:103], v[200:203], v[92:95]
	v_mfma_f32_16x16x32_bf16 v[88:91], v[108:111], v[200:203], v[88:91]
	v_mfma_f32_16x16x32_bf16 v[80:83], v[100:103], v[208:211], v[80:83]
	v_mfma_f32_16x16x32_bf16 v[72:75], v[108:111], v[208:211], v[72:75]
	v_mfma_f32_16x16x32_bf16 v[148:151], v[112:115], v[168:171], v[148:151]
	v_mfma_f32_16x16x32_bf16 v[140:143], v[120:123], v[168:171], v[140:143]
	v_mfma_f32_16x16x32_bf16 v[132:135], v[112:115], v[188:191], v[132:135]
	v_mfma_f32_16x16x32_bf16 v[128:131], v[120:123], v[188:191], v[128:131]
	v_mfma_f32_16x16x32_bf16 v[84:87], v[112:115], v[196:199], v[84:87]
	v_mfma_f32_16x16x32_bf16 v[76:79], v[120:123], v[196:199], v[76:79]
	v_mfma_f32_16x16x32_bf16 v[68:71], v[112:115], v[204:207], v[68:71]
	v_mfma_f32_16x16x32_bf16 v[64:67], v[120:123], v[204:207], v[64:67]
	v_mfma_f32_16x16x32_bf16 v[148:151], v[116:119], v[184:187], v[148:151]
	v_mfma_f32_16x16x32_bf16 v[140:143], v[124:127], v[184:187], v[140:143]
	v_mfma_f32_16x16x32_bf16 v[132:135], v[116:119], v[192:195], v[132:135]
	v_mfma_f32_16x16x32_bf16 v[128:131], v[124:127], v[192:195], v[128:131]
	v_mfma_f32_16x16x32_bf16 v[84:87], v[116:119], v[200:203], v[84:87]
	v_mfma_f32_16x16x32_bf16 v[76:79], v[124:127], v[200:203], v[76:79]
	v_mfma_f32_16x16x32_bf16 v[68:71], v[116:119], v[208:211], v[68:71]
	v_mfma_f32_16x16x32_bf16 v[64:67], v[124:127], v[208:211], v[64:67]
	s_barrier
	s_add_i32 s0, s52, s15
	v_lshl_add_u64 v[172:173], v[172:173], 0, s[10:11]
	s_mov_b32 m0, s0
	ds_read_b128 v[168:171], v181 offset:49152
	ds_read_b128 v[184:187], v181 offset:50176
	ds_read_b128 v[188:191], v181 offset:51200
	ds_read_b128 v[192:195], v181 offset:52224
	ds_read_b128 v[196:199], v181 offset:53248
	ds_read_b128 v[200:203], v181 offset:54272
	ds_read_b128 v[204:207], v181 offset:55296
	ds_read_b128 v[208:211], v181 offset:56320
	global_load_lds_dwordx4 v[172:173], off
	s_add_i32 m0, s0, 0x2000
	s_add_u32 s0, s24, 0x160080
	v_lshl_add_u64 v[172:173], v[212:213], 0, s[10:11]
	s_addc_u32 s1, s25, 0
	s_add_i32 s24, s53, s15
	global_load_lds_dwordx4 v[172:173], off
	v_lshl_add_u64 v[172:173], s[0:1], 0, v[160:161]
	s_mov_b32 m0, s24
	s_nop 0
	global_load_lds_dwordx4 v[172:173], off
	v_lshl_add_u64 v[172:173], s[0:1], 0, v[162:163]
	s_add_i32 m0, s24, 0x2000
	s_nop 0
	global_load_lds_dwordx4 v[172:173], off
	v_lshl_add_u64 v[172:173], v[214:215], 0, s[10:11]
	s_mov_b32 m0, s36
	s_nop 0
	global_load_lds_dwordx4 v[172:173], off
	v_lshl_add_u64 v[172:173], v[216:217], 0, s[10:11]
	s_mov_b32 m0, s37
	s_nop 0
	global_load_lds_dwordx4 v[172:173], off
	s_waitcnt vmcnt(8)
	s_waitcnt lgkmcnt(0)
	s_barrier
	s_waitcnt lgkmcnt(0)
	v_mfma_f32_16x16x32_bf16 v[60:63], v[96:99], v[168:171], v[60:63]
	v_mfma_f32_16x16x32_bf16 v[56:59], v[104:107], v[168:171], v[56:59]
	v_mfma_f32_16x16x32_bf16 v[48:51], v[96:99], v[188:191], v[48:51]
	v_mfma_f32_16x16x32_bf16 v[40:43], v[104:107], v[188:191], v[40:43]
	v_mfma_f32_16x16x32_bf16 v[28:31], v[96:99], v[196:199], v[28:31]
	v_mfma_f32_16x16x32_bf16 v[24:27], v[104:107], v[196:199], v[24:27]
	v_mfma_f32_16x16x32_bf16 v[16:19], v[96:99], v[204:207], v[16:19]
	v_mfma_f32_16x16x32_bf16 v[8:11], v[104:107], v[204:207], v[8:11]
	v_mfma_f32_16x16x32_bf16 v[60:63], v[100:103], v[184:187], v[60:63]
	v_mfma_f32_16x16x32_bf16 v[56:59], v[108:111], v[184:187], v[56:59]
	v_mfma_f32_16x16x32_bf16 v[48:51], v[100:103], v[192:195], v[48:51]
	v_mfma_f32_16x16x32_bf16 v[40:43], v[108:111], v[192:195], v[40:43]
	v_mfma_f32_16x16x32_bf16 v[28:31], v[100:103], v[200:203], v[28:31]
	v_mfma_f32_16x16x32_bf16 v[24:27], v[108:111], v[200:203], v[24:27]
	v_mfma_f32_16x16x32_bf16 v[16:19], v[100:103], v[208:211], v[16:19]
	v_mfma_f32_16x16x32_bf16 v[8:11], v[108:111], v[208:211], v[8:11]
	v_mfma_f32_16x16x32_bf16 v[52:55], v[112:115], v[168:171], v[52:55]
	v_mfma_f32_16x16x32_bf16 v[44:47], v[120:123], v[168:171], v[44:47]
	v_mfma_f32_16x16x32_bf16 v[36:39], v[112:115], v[188:191], v[36:39]
	v_mfma_f32_16x16x32_bf16 v[32:35], v[120:123], v[188:191], v[32:35]
	v_mfma_f32_16x16x32_bf16 v[20:23], v[112:115], v[196:199], v[20:23]
	v_mfma_f32_16x16x32_bf16 v[12:15], v[120:123], v[196:199], v[12:15]
	v_mfma_f32_16x16x32_bf16 v[4:7], v[112:115], v[204:207], v[4:7]
	v_mfma_f32_16x16x32_bf16 v[0:3], v[120:123], v[204:207], v[0:3]
	v_mfma_f32_16x16x32_bf16 v[52:55], v[116:119], v[184:187], v[52:55]
	v_mfma_f32_16x16x32_bf16 v[44:47], v[124:127], v[184:187], v[44:47]
	v_mfma_f32_16x16x32_bf16 v[36:39], v[116:119], v[192:195], v[36:39]
	v_mfma_f32_16x16x32_bf16 v[32:35], v[124:127], v[192:195], v[32:35]
	v_mfma_f32_16x16x32_bf16 v[20:23], v[116:119], v[200:203], v[20:23]
	v_mfma_f32_16x16x32_bf16 v[12:15], v[124:127], v[200:203], v[12:15]
	v_mfma_f32_16x16x32_bf16 v[4:7], v[116:119], v[208:211], v[4:7]
	v_mfma_f32_16x16x32_bf16 v[0:3], v[124:127], v[208:211], v[0:3]
	s_barrier
	s_add_i32 s51, s51, 2
	s_add_u32 s49, s49, 0x100
	s_addc_u32 s50, s50, 0
	s_cmpk_gt_u32 s51, 0x55
	s_mov_b64 s[0:1], s[4:5]
	s_cbranch_scc0 .LBB0_1120
	s_setprio 0
	s_and_b64 vcc, exec, s[12:13]
	s_cbranch_vccz .LBB0_1123
	s_barrier
